# attention: all 13 PV bodies read V with ds_read_b64 into operand regs; redundant canonicalizing v_max removed/fused (attention max trees, relu epilogue)
# speedup vs baseline: 1.0160x; 1.0039x over previous
; DEVI float opq(float x) { asm("" : "+v"(x)); return x; }
; template <int DK, int MODE, int RBM, class SF, class FF, class POST>
; DEVI void attn_tile_body(const bf16x8 (&qf)[2][DK / 32], const char* Ks, const char* Vs, SF& sf, FF& ff, POST& post,
;                          int cur, int c0, int c1, float (&m)[2], float (&l)[2], f32x4 (&o)[5][2], int fr, int fq) {
;     ...
; #pragma unroll
;   for (int ks = 0; ks < NKC; ++ks)
; #pragma unroll
;     for (int kb = 0; kb < 4; ++kb) {
;       const int koff = DK == 64 ? (kb * 16 + fr) * 128 + (((ks * 4 + fq) ^ (fr & 7)) * 16)
;                                 : (kb * 16 + fr) * 192 + ((ks * 4 + (fq ^ ((fr >> 2) & 3))) * 16);
;       bf16x8 kf = *(const bf16x8*)(Ks + koff);
;       if (RBM & 1) s[kb][0] = __builtin_amdgcn_mfma_f32_16x16x32_bf16(kf, qf[0][ks], s[kb][0], 0, 0, 0);
;       if (RBM & 2) s[kb][1] = __builtin_amdgcn_mfma_f32_16x16x32_bf16(kf, qf[1][ks], s[kb][1], 0, 0, 0);
;     }
; #pragma unroll
;   for (int rb = 0; rb < 2; ++rb) {
;     if (!(RBM & (1 << rb))) continue;
;     const int cm = rb == 0 ? c0 : c1;
;     if (cm == 2) {
;       const float cl = ff.cl(rb, cur);
;       const float fsc = ff.sc;
;       if (FF::HASVEC) {
; #pragma unroll
;         for (int kb = 0; kb < 4; ++kb) {
;           const f32x4 av = ff.vec(kb);
; #pragma unroll
;           for (int j = 0; j < 4; ++j) s[kb][rb][j] = opq(fmaf(s[kb][rb][j], fsc, av[j]));
;         }
;       }
;       if (MODE == 2) {
;         const float c = cl - m[rb];
; #pragma unroll
;         for (int kb = 0; kb < 4; ++kb)
; #pragma unroll
;           for (int j = 0; j < 4; ++j) {
;             const float e = FF::HASVEC ? opq(s[kb][rb][j] + c) : opq(fmaf(s[kb][rb][j], fsc, c));
;             s[kb][rb][j] = opq(fexp2(e) * l[rb]);
;           }
;       } else if (MODE == 0) {
;         float mx = max16(s[0][rb], s[1][rb], s[2][rb], s[3][rb]);
;         mx = xmax16(mx); mx = xmax32(mx);
;         const float cand = FF::HASVEC ? (mx + cl) : fmaf(mx, fsc, cl);
;         if (__builtin_amdgcn_ballot_w64(cand > m[rb] + DEFER_THR) != 0) {
;           const float mn = fmaxf(m[rb], cand);
;           const float alpha = fexp2(m[rb] - mn);
;           m[rb] = mn;
; #pragma unroll
;           for (int db = 0; db < 5; ++db)
; #pragma unroll
;             for (int j = 0; j < 4; ++j) o[db][rb][j] = opq(o[db][rb][j] * alpha);
;         }
.LBB0_539:
	s_or_b64 exec, exec, s[54:55]
	v_lshrrev_b64 v[2:3], v60, v[118:119]
	s_and_b64 s[6:7], exec, vcc
	v_and_b32_e32 v2, 1, v2
	s_or_b64 s[52:53], s[6:7], s[52:53]
	v_cmp_eq_u32_e32 vcc, 1, v2
	s_and_saveexec_b64 s[38:39], vcc
	s_cbranch_execz .LBB0_557
	v_lshlrev_b32_e32 v197, 6, v60
	s_mul_i32 s6, s42, 0x4100
	v_or_b32_e32 v2, 63, v197
	v_cmp_le_i32_e32 vcc, v2, v113
	v_add_u32_e32 v2, s6, v115
	v_add_u32_e32 v3, v2, v123
	ds_read_b128 v[72:75], v3 offset:4096
	ds_read_b128 v[60:63], v3
	v_add_u32_e32 v2, v2, v134
	ds_read_b128 v[68:71], v3 offset:2048
	s_waitcnt lgkmcnt(0)
	v_mfma_f32_16x16x32_bf16 v[80:83], v[72:75], v[8:11], 0
	v_mfma_f32_16x16x32_bf16 v[144:147], v[72:75], v[16:19], 0
	ds_read_b128 v[72:75], v3 offset:6144
	s_waitcnt lgkmcnt(0)
	v_mfma_f32_16x16x32_bf16 v[148:151], v[72:75], v[8:11], 0
	v_mfma_f32_16x16x32_bf16 v[192:195], v[72:75], v[16:19], 0
	ds_read_b128 v[72:75], v2
	v_mfma_f32_16x16x32_bf16 v[64:67], v[60:63], v[8:11], 0
	v_mfma_f32_16x16x32_bf16 v[60:63], v[60:63], v[16:19], 0
	s_waitcnt lgkmcnt(0)
	v_mfma_f32_16x16x32_bf16 v[92:95], v[72:75], v[4:7], v[64:67]
	v_mfma_f32_16x16x32_bf16 v[72:75], v[72:75], v[12:15], v[60:63]
	s_nop 4
	ds_read_b128 v[60:63], v2 offset:2048
	v_mfma_f32_16x16x32_bf16 v[76:79], v[68:71], v[8:11], 0
	v_mfma_f32_16x16x32_bf16 v[68:71], v[68:71], v[16:19], 0
	s_waitcnt lgkmcnt(0)
	v_mfma_f32_16x16x32_bf16 v[88:91], v[60:63], v[4:7], v[76:79]
	v_mfma_f32_16x16x32_bf16 v[68:71], v[60:63], v[12:15], v[68:71]
	ds_read_b128 v[60:63], v2 offset:4096
	s_waitcnt lgkmcnt(0)
	v_mfma_f32_16x16x32_bf16 v[84:87], v[60:63], v[4:7], v[80:83]
	v_mfma_f32_16x16x32_bf16 v[64:67], v[60:63], v[12:15], v[144:147]
	ds_read_b128 v[60:63], v2 offset:6144
	s_waitcnt lgkmcnt(0)
	v_mfma_f32_16x16x32_bf16 v[80:83], v[60:63], v[4:7], v[148:151]
	v_add_u32_e32 v144, s6, v106
	v_mfma_f32_16x16x32_bf16 v[60:63], v[60:63], v[12:15], v[192:195]
	s_and_saveexec_b64 s[54:55], vcc
	s_xor_b64 s[54:55], exec, s[54:55]
	s_cbranch_execz .LBB0_544
	ds_read_b128 v[76:79], v144 offset:16384
	ds_read_b128 v[148:151], v144 offset:16576
	s_waitcnt lgkmcnt(0)
	v_sub_f32_e32 v146, 0, v76
	v_sub_f32_e32 v145, 0, v77
	v_fmac_f32_e32 v146, 0x3e38aa3b, v92
	v_fmac_f32_e32 v145, 0x3e38aa3b, v93
	v_sub_f32_e32 v93, 0, v78
	v_sub_f32_e32 v92, 0, v79
	ds_read_b128 v[76:79], v144 offset:16448
	v_fmac_f32_e32 v93, 0x3e38aa3b, v94
	v_fmac_f32_e32 v92, 0x3e38aa3b, v95
	s_waitcnt lgkmcnt(0)
	v_sub_f32_e32 v94, 0, v76
	v_fmac_f32_e32 v94, 0x3e38aa3b, v88
	v_sub_f32_e32 v88, 0, v77
	v_fmac_f32_e32 v88, 0x3e38aa3b, v89
	v_sub_f32_e32 v89, 0, v78
	v_fmac_f32_e32 v89, 0x3e38aa3b, v90
	v_sub_f32_e32 v90, 0, v79
	s_waitcnt vmcnt(0)
	ds_read_b128 v[76:79], v144 offset:16512
	v_fmac_f32_e32 v90, 0x3e38aa3b, v91
	v_max_f32_e32 v2, v145, v145
	v_max_f32_e32 v3, v146, v146
	s_waitcnt lgkmcnt(0)
	v_sub_f32_e32 v91, 0, v77
	v_fmac_f32_e32 v91, 0x3e38aa3b, v85
	v_sub_f32_e32 v85, 0, v78
	v_fmac_f32_e32 v85, 0x3e38aa3b, v86
	v_sub_f32_e32 v86, 0, v148
	v_sub_f32_e32 v95, 0, v76
	v_fmac_f32_e32 v86, 0x3e38aa3b, v80
	v_sub_f32_e32 v80, 0, v149
	v_fmac_f32_e32 v95, 0x3e38aa3b, v84
	v_sub_f32_e32 v84, 0, v79
	v_fmac_f32_e32 v80, 0x3e38aa3b, v81
	v_sub_f32_e32 v81, 0, v150
	v_fmac_f32_e32 v84, 0x3e38aa3b, v87
	v_fmac_f32_e32 v81, 0x3e38aa3b, v82
	v_sub_f32_e32 v82, 0, v151
	v_fmac_f32_e32 v82, 0x3e38aa3b, v83
	v_max_f32_e32 v2, v3, v2
	v_max3_f32 v3, v92, v94, v88
	v_max3_f32 v83, v91, v85, v84
	v_max3_f32 v87, v86, v80, v81
	s_nop 0
	v_max3_f32 v76, v89, v90, v95
	v_max3_f32 v2, v2, v93, v3
	v_max3_f32 v3, v83, v87, v82
	v_max3_f32 v2, v2, v76, v3
	v_mov_b32_e32 v3, v2
	s_nop 1
	v_permlane16_swap_b32_e32 v2, v3
	v_max_f32_e32 v2, v2, v3
	v_mov_b32_e32 v3, v2
	s_nop 1
	v_permlane32_swap_b32_e32 v2, v3
	v_max_f32_e32 v124, v2, v3
	v_pk_add_f32 v[2:3], v[108:109], v[124:125]
	s_nop 0
	v_cmp_gt_f32_e32 vcc, v2, v3
	s_cbranch_vccz .LBB0_543
	v_max_f32_e32 v3, v109, v109
	v_max_f32_e32 v2, v3, v2
	v_sub_f32_e32 v3, v109, v2
	v_exp_f32_e32 v3, v3
	v_mov_b32_e32 v109, v2
	v_mul_f32_e32 v56, v56, v3
	v_mul_f32_e32 v57, v57, v3
	v_mul_f32_e32 v58, v58, v3
	v_mul_f32_e32 v59, v59, v3
	v_mul_f32_e32 v52, v52, v3
	v_mul_f32_e32 v53, v53, v3
	v_mul_f32_e32 v54, v54, v3
	v_mul_f32_e32 v55, v55, v3
	v_mul_f32_e32 v48, v48, v3
	v_mul_f32_e32 v49, v49, v3
	v_mul_f32_e32 v50, v50, v3
	v_mul_f32_e32 v51, v51, v3
	v_mul_f32_e32 v44, v44, v3
	v_mul_f32_e32 v45, v45, v3
	v_mul_f32_e32 v46, v46, v3
	v_mul_f32_e32 v47, v47, v3
	v_mul_f32_e32 v24, v24, v3
	v_mul_f32_e32 v25, v25, v3
	v_mul_f32_e32 v26, v26, v3
	v_mul_f32_e32 v27, v27, v3

; DEVI float opq(float x) { asm("" : "+v"(x)); return x; }
; DEVI float fexp2(float x) { return __builtin_amdgcn_exp2f(x); }
; template <int DK, int MODE, int RBM, class SF, class FF, class POST>
; DEVI void attn_tile_body(const bf16x8 (&qf)[2][DK / 32], const char* Ks, const char* Vs, SF& sf, FF& ff, POST& post,
;                          int cur, int c0, int c1, float (&m)[2], float (&l)[2], f32x4 (&o)[5][2], int fr, int fq) {
;     ...
; #pragma unroll
;     for (int kb = 0; kb < 4; ++kb)
; #pragma unroll
;       for (int j = 0; j < 4; ++j) s[kb][rb][j] = sf(rb, kb, j, cur, s[kb][rb][j]);
;     if (MODE == 2) {
; #pragma unroll
;       for (int kb = 0; kb < 4; ++kb)
; #pragma unroll
;         for (int j = 0; j < 4; ++j) s[kb][rb][j] = fexp2(s[kb][rb][j] - m[rb]) * l[rb];
;     } else if (MODE == 0) {
;       float mx = max16(s[0][rb], s[1][rb], s[2][rb], s[3][rb]);
;       mx = xmax16(mx); mx = xmax32(mx);
;       if (__builtin_amdgcn_ballot_w64(mx > m[rb] + DEFER_THR) != 0) {
;         const float mn = fmaxf(m[rb], mx);
;         const float alpha = fexp2(m[rb] - mn);
;         m[rb] = mn;
; #pragma unroll
;         for (int db = 0; db < 5; ++db)
; #pragma unroll
;           for (int j = 0; j < 4; ++j) o[db][rb][j] = opq(o[db][rb][j] * alpha);
;       }
;       const float mm = m[rb];
; #pragma unroll
;       for (int kb = 0; kb < 4; ++kb)
; #pragma unroll
;         for (int j = 0; j < 4; ++j) s[kb][rb][j] = fexp2(s[kb][rb][j] - mm);
.LBB0_544:
	s_or_saveexec_b64 s[54:55], s[54:55]
	v_or_b32_e32 v205, v197, v114
	v_or_b32_e32 v204, 2, v205
	v_or_b32_e32 v203, 3, v205
	v_or_b32_e32 v202, 16, v205
	v_or_b32_e32 v201, 17, v205
	v_or_b32_e32 v200, 18, v205
	v_or_b32_e32 v199, 19, v205
	v_or_b32_e32 v124, 32, v205
	v_or_b32_e32 v3, 33, v205
	v_or_b32_e32 v2, 34, v205
	v_or_b32_e32 v198, 35, v205
	s_xor_b64 exec, exec, s[54:55]
	s_cbranch_execz .LBB0_548
	ds_read_b128 v[76:79], v144 offset:16384
	v_cmp_le_i32_e32 vcc, v205, v102
	ds_read_b128 v[146:149], v144 offset:16576
	s_waitcnt lgkmcnt(0)
	v_sub_f32_e32 v76, v108, v76
	v_fmac_f32_e32 v76, 0x3e38aa3b, v92
	v_cndmask_b32_e32 v92, v181, v76, vcc
	v_sub_f32_e32 v76, v108, v77
	v_fmac_f32_e32 v76, 0x3e38aa3b, v93
	v_cmp_lt_i32_e32 vcc, v205, v102
	v_sub_f32_e32 v145, v108, v146
	v_fmac_f32_e32 v145, 0x3e38aa3b, v80
	v_cndmask_b32_e32 v93, v181, v76, vcc
	v_sub_f32_e32 v76, v108, v78
	v_fmac_f32_e32 v76, 0x3e38aa3b, v94
	v_cmp_le_i32_e32 vcc, v204, v102
	s_nop 1
	v_cndmask_b32_e32 v94, v181, v76, vcc
	v_sub_f32_e32 v76, v108, v79
	v_fmac_f32_e32 v76, 0x3e38aa3b, v95
	v_cmp_le_i32_e32 vcc, v203, v102
	s_nop 1
	v_cndmask_b32_e32 v95, v181, v76, vcc
	ds_read_b128 v[76:79], v144 offset:16448
	v_cmp_le_i32_e32 vcc, v202, v102
	s_waitcnt lgkmcnt(0)
	v_sub_f32_e32 v76, v108, v76
	v_fmac_f32_e32 v76, 0x3e38aa3b, v88
	v_cndmask_b32_e32 v88, v181, v76, vcc
	v_sub_f32_e32 v76, v108, v77
	v_fmac_f32_e32 v76, 0x3e38aa3b, v89
	v_cmp_le_i32_e32 vcc, v201, v102
	s_nop 1
	v_cndmask_b32_e32 v89, v181, v76, vcc
	v_sub_f32_e32 v76, v108, v78
	v_fmac_f32_e32 v76, 0x3e38aa3b, v90
	v_cmp_le_i32_e32 vcc, v200, v102
	s_nop 1
	v_cndmask_b32_e32 v90, v181, v76, vcc
	v_sub_f32_e32 v76, v108, v79
	v_fmac_f32_e32 v76, 0x3e38aa3b, v91
	v_cmp_le_i32_e32 vcc, v199, v102
	s_nop 1
	v_cndmask_b32_e32 v91, v181, v76, vcc
	ds_read_b128 v[76:79], v144 offset:16512
	v_cmp_le_i32_e32 vcc, v124, v102
	s_waitcnt lgkmcnt(0)
	v_sub_f32_e32 v76, v108, v76
	v_fmac_f32_e32 v76, 0x3e38aa3b, v84
	v_cndmask_b32_e32 v84, v181, v76, vcc
	v_sub_f32_e32 v76, v108, v77
	v_fmac_f32_e32 v76, 0x3e38aa3b, v85
	v_cmp_le_i32_e32 vcc, v3, v102
	v_max3_f32 v146, v90, v91, v84
	s_nop 0
	v_cndmask_b32_e32 v85, v181, v76, vcc
	v_sub_f32_e32 v76, v108, v78
	v_fmac_f32_e32 v76, 0x3e38aa3b, v86
	v_cmp_le_i32_e32 vcc, v2, v102
	s_nop 1
	v_cndmask_b32_e32 v86, v181, v76, vcc
	v_sub_f32_e32 v76, v108, v79
	v_fmac_f32_e32 v76, 0x3e38aa3b, v87
	v_cmp_le_i32_e32 vcc, v198, v102
	s_nop 1
	v_cndmask_b32_e32 v87, v181, v76, vcc
	v_or_b32_e32 v76, 48, v205
	v_cmp_le_i32_e32 vcc, v76, v102
	v_or_b32_e32 v76, 49, v205
	s_nop 0
	v_cndmask_b32_e32 v80, v181, v145, vcc
	v_sub_f32_e32 v145, v108, v147
	v_fmac_f32_e32 v145, 0x3e38aa3b, v81
	v_cmp_le_i32_e32 vcc, v76, v102
	v_or_b32_e32 v76, 50, v205
	v_max3_f32 v147, v85, v86, v87
	v_cndmask_b32_e32 v81, v181, v145, vcc
	v_sub_f32_e32 v145, v108, v148
	v_fmac_f32_e32 v145, 0x3e38aa3b, v82
	v_cmp_le_i32_e32 vcc, v76, v102
	v_or_b32_e32 v76, 51, v205
	s_nop 0
	v_cndmask_b32_e32 v82, v181, v145, vcc
	v_sub_f32_e32 v145, v108, v149
	v_fmac_f32_e32 v145, 0x3e38aa3b, v83
	v_cmp_le_i32_e32 vcc, v76, v102
	v_max_f32_e32 v76, v92, v93
	v_max3_f32 v148, v80, v81, v82
	v_cndmask_b32_e32 v83, v181, v145, vcc
	v_max3_f32 v145, v95, v88, v89
	v_max3_f32 v76, v76, v94, v145
	v_max3_f32 v145, v147, v148, v83
	v_max3_f32 v76, v76, v146, v145
	v_mov_b32_e32 v145, v76
	s_nop 1
	v_permlane16_swap_b32_e32 v76, v145
	v_max_f32_e32 v76, v76, v145
	v_mov_b32_e32 v145, v76
	s_nop 1
	v_permlane32_swap_b32_e32 v76, v145
	v_max_f32_e32 v76, v76, v145
	v_add_f32_e32 v145, 0x41000000, v109
	v_cmp_gt_f32_e32 vcc, v76, v145
	s_cbranch_vccz .LBB0_547
	v_max_f32_e32 v145, v109, v109
	v_max_f32_e32 v76, v145, v76
	v_sub_f32_e32 v109, v109, v76
	v_exp_f32_e32 v109, v109
	s_nop 0
	v_mul_f32_e32 v56, v56, v109
	v_mul_f32_e32 v57, v57, v109
	v_mul_f32_e32 v58, v58, v109
	v_mul_f32_e32 v59, v59, v109
	v_mul_f32_e32 v52, v52, v109
	v_mul_f32_e32 v53, v53, v109
	v_mul_f32_e32 v54, v54, v109
	v_mul_f32_e32 v55, v55, v109
	v_mul_f32_e32 v48, v48, v109
	v_mul_f32_e32 v49, v49, v109
	v_mul_f32_e32 v50, v50, v109
	v_mul_f32_e32 v51, v51, v109
	v_mul_f32_e32 v44, v44, v109
	v_mul_f32_e32 v45, v45, v109
	v_mul_f32_e32 v46, v46, v109
	v_mul_f32_e32 v47, v47, v109
	v_mul_f32_e32 v24, v24, v109
	v_mul_f32_e32 v25, v25, v109
	v_mul_f32_e32 v26, v26, v109
	v_mul_f32_e32 v27, v27, v109
	v_mov_b32_e32 v109, v76

; DEVI float opq(float x) { asm("" : "+v"(x)); return x; }
; DEVI float fexp2(float x) { return __builtin_amdgcn_exp2f(x); }
; template <int DK, int MODE, int RBM, class SF, class FF, class POST>
; DEVI void attn_tile_body(const bf16x8 (&qf)[2][DK / 32], const char* Ks, const char* Vs, SF& sf, FF& ff, POST& post,
;                          int cur, int c0, int c1, float (&m)[2], float (&l)[2], f32x4 (&o)[5][2], int fr, int fq) {
;     ...
;     if (cm == 2) {
;       const float cl = ff.cl(rb, cur);
;       const float fsc = ff.sc;
;       if (FF::HASVEC) {
; #pragma unroll
;         for (int kb = 0; kb < 4; ++kb) {
;           const f32x4 av = ff.vec(kb);
; #pragma unroll
;           for (int j = 0; j < 4; ++j) s[kb][rb][j] = opq(fmaf(s[kb][rb][j], fsc, av[j]));
;         }
;       }
;       if (MODE == 2) {
;         const float c = cl - m[rb];
; #pragma unroll
;         for (int kb = 0; kb < 4; ++kb)
; #pragma unroll
;           for (int j = 0; j < 4; ++j) {
;             const float e = FF::HASVEC ? opq(s[kb][rb][j] + c) : opq(fmaf(s[kb][rb][j], fsc, c));
;             s[kb][rb][j] = opq(fexp2(e) * l[rb]);
;           }
;       } else if (MODE == 0) {
;         float mx = max16(s[0][rb], s[1][rb], s[2][rb], s[3][rb]);
;         mx = xmax16(mx); mx = xmax32(mx);
;         const float cand = FF::HASVEC ? (mx + cl) : fmaf(mx, fsc, cl);
;         if (__builtin_amdgcn_ballot_w64(cand > m[rb] + DEFER_THR) != 0) {
;           const float mn = fmaxf(m[rb], cand);
;           const float alpha = fexp2(m[rb] - mn);
;           m[rb] = mn;
; #pragma unroll
;           for (int db = 0; db < 5; ++db)
; #pragma unroll
;             for (int j = 0; j < 4; ++j) o[db][rb][j] = opq(o[db][rb][j] * alpha);
;         }
.LBB0_548:
	s_or_b64 exec, exec, s[54:55]
	v_or_b32_e32 v80, 47, v197
	v_cmp_le_i32_e32 vcc, v80, v113
	s_and_saveexec_b64 s[54:55], vcc
	s_xor_b64 s[54:55], exec, s[54:55]
	s_cbranch_execz .LBB0_552
	ds_read_b128 v[78:81], v144 offset:16384
	s_waitcnt lgkmcnt(0)
	v_sub_f32_e32 v78, 0, v78
	v_sub_f32_e32 v77, 0, v79
	v_fmac_f32_e32 v78, 0x3e38aa3b, v72
	v_fmac_f32_e32 v77, 0x3e38aa3b, v73
	v_sub_f32_e32 v73, 0, v80
	v_sub_f32_e32 v72, 0, v81
	ds_read_b128 v[80:83], v144 offset:16448
	v_fmac_f32_e32 v73, 0x3e38aa3b, v74
	v_fmac_f32_e32 v72, 0x3e38aa3b, v75
	s_waitcnt lgkmcnt(0)
	v_sub_f32_e32 v74, 0, v80
	v_fmac_f32_e32 v74, 0x3e38aa3b, v68
	v_sub_f32_e32 v68, 0, v81
	v_fmac_f32_e32 v68, 0x3e38aa3b, v69
	v_sub_f32_e32 v69, 0, v82
	v_fmac_f32_e32 v69, 0x3e38aa3b, v70
	v_sub_f32_e32 v70, 0, v83
	ds_read_b128 v[80:83], v144 offset:16512
	v_fmac_f32_e32 v70, 0x3e38aa3b, v71
	v_max_f32_e32 v2, v77, v77
	v_max_f32_e32 v3, v78, v78
	s_waitcnt lgkmcnt(0)
	v_sub_f32_e32 v75, 0, v80
	v_sub_f32_e32 v71, 0, v81
	v_fmac_f32_e32 v75, 0x3e38aa3b, v64
	v_fmac_f32_e32 v71, 0x3e38aa3b, v65
	v_sub_f32_e32 v65, 0, v82
	v_sub_f32_e32 v64, 0, v83
	ds_read_b128 v[80:83], v144 offset:16576
	v_fmac_f32_e32 v65, 0x3e38aa3b, v66
	v_fmac_f32_e32 v64, 0x3e38aa3b, v67
	s_waitcnt lgkmcnt(0)
	v_sub_f32_e32 v66, 0, v80
	v_fmac_f32_e32 v66, 0x3e38aa3b, v60
	v_sub_f32_e32 v60, 0, v81
	v_fmac_f32_e32 v60, 0x3e38aa3b, v61
	v_sub_f32_e32 v61, 0, v82
	v_fmac_f32_e32 v61, 0x3e38aa3b, v62
	v_sub_f32_e32 v62, 0, v83
	v_fmac_f32_e32 v62, 0x3e38aa3b, v63
	v_max_f32_e32 v2, v3, v2
	v_max3_f32 v3, v72, v74, v68
	v_max3_f32 v67, v71, v65, v64
	v_max3_f32 v79, v66, v60, v61
	s_nop 0
	v_max3_f32 v63, v69, v70, v75
	v_max3_f32 v2, v2, v73, v3
	v_max3_f32 v3, v67, v79, v62
	v_max3_f32 v2, v2, v63, v3
	v_mov_b32_e32 v3, v2
	s_nop 1
	v_permlane16_swap_b32_e32 v2, v3
	v_max_f32_e32 v2, v2, v3
	v_mov_b32_e32 v3, v2
	s_nop 1
	v_permlane32_swap_b32_e32 v2, v3
	v_max_f32_e32 v124, v2, v3
	v_pk_add_f32 v[2:3], v[110:111], v[124:125]
	s_nop 0
	v_cmp_gt_f32_e32 vcc, v2, v3
	s_cbranch_vccz .LBB0_551
	v_max_f32_e32 v3, v111, v111
	v_max_f32_e32 v2, v3, v2
	v_sub_f32_e32 v3, v111, v2
	v_exp_f32_e32 v3, v3
	v_mov_b32_e32 v111, v2
	v_mul_f32_e32 v40, v40, v3
	v_mul_f32_e32 v41, v41, v3
	v_mul_f32_e32 v42, v42, v3
	v_mul_f32_e32 v43, v43, v3
	v_mul_f32_e32 v36, v36, v3
	v_mul_f32_e32 v37, v37, v3
	v_mul_f32_e32 v38, v38, v3
	v_mul_f32_e32 v39, v39, v3
	v_mul_f32_e32 v32, v32, v3
	v_mul_f32_e32 v33, v33, v3
	v_mul_f32_e32 v34, v34, v3
	v_mul_f32_e32 v35, v35, v3
	v_mul_f32_e32 v28, v28, v3
	v_mul_f32_e32 v29, v29, v3
	v_mul_f32_e32 v30, v30, v3
	v_mul_f32_e32 v31, v31, v3
	v_mul_f32_e32 v20, v20, v3
	v_mul_f32_e32 v21, v21, v3
	v_mul_f32_e32 v22, v22, v3
	v_mul_f32_e32 v23, v23, v3

; DEVI float opq(float x) { asm("" : "+v"(x)); return x; }
; DEVI float fexp2(float x) { return __builtin_amdgcn_exp2f(x); }
; template <int DK, int MODE, int RBM, class SF, class FF, class POST>
; DEVI void attn_tile_body(const bf16x8 (&qf)[2][DK / 32], const char* Ks, const char* Vs, SF& sf, FF& ff, POST& post,
;                          int cur, int c0, int c1, float (&m)[2], float (&l)[2], f32x4 (&o)[5][2], int fr, int fq) {
;     ...
; #pragma unroll
;     for (int kb = 0; kb < 4; ++kb)
; #pragma unroll
;       for (int j = 0; j < 4; ++j) s[kb][rb][j] = sf(rb, kb, j, cur, s[kb][rb][j]);
;     if (MODE == 2) {
; #pragma unroll
;       for (int kb = 0; kb < 4; ++kb)
; #pragma unroll
;         for (int j = 0; j < 4; ++j) s[kb][rb][j] = fexp2(s[kb][rb][j] - m[rb]) * l[rb];
;     } else if (MODE == 0) {
;       float mx = max16(s[0][rb], s[1][rb], s[2][rb], s[3][rb]);
;       mx = xmax16(mx); mx = xmax32(mx);
;       if (__builtin_amdgcn_ballot_w64(mx > m[rb] + DEFER_THR) != 0) {
;         const float mn = fmaxf(m[rb], mx);
;         const float alpha = fexp2(m[rb] - mn);
;         m[rb] = mn;
; #pragma unroll
;         for (int db = 0; db < 5; ++db)
; #pragma unroll
;           for (int j = 0; j < 4; ++j) o[db][rb][j] = opq(o[db][rb][j] * alpha);
;       }
;       const float mm = m[rb];
; #pragma unroll
;       for (int kb = 0; kb < 4; ++kb)
; #pragma unroll
;         for (int j = 0; j < 4; ++j) s[kb][rb][j] = fexp2(s[kb][rb][j] - mm);
.LBB0_552:
	s_andn2_saveexec_b64 s[54:55], s[54:55]
	s_cbranch_execz .LBB0_556
	ds_read_b128 v[80:83], v144 offset:16384
	v_cmp_le_i32_e32 vcc, v205, v104
	v_sub_f32_e32 v77, v110, v77
	v_fmac_f32_e32 v77, 0x3e38aa3b, v65
	s_waitcnt lgkmcnt(0)
	v_sub_f32_e32 v80, v110, v80
	v_fmac_f32_e32 v80, 0x3e38aa3b, v72
	v_cndmask_b32_e32 v72, v181, v80, vcc
	v_sub_f32_e32 v80, v110, v81
	v_fmac_f32_e32 v80, 0x3e38aa3b, v73
	v_cmp_lt_i32_e32 vcc, v205, v104
	s_nop 1
	v_cndmask_b32_e32 v73, v181, v80, vcc
	v_sub_f32_e32 v80, v110, v82
	v_fmac_f32_e32 v80, 0x3e38aa3b, v74
	v_cmp_le_i32_e32 vcc, v205, v140
	s_nop 1
	v_cndmask_b32_e32 v74, v181, v80, vcc
	v_sub_f32_e32 v80, v110, v83
	v_fmac_f32_e32 v80, 0x3e38aa3b, v75
	v_cmp_le_i32_e32 vcc, v205, v141
	s_nop 1
	v_cndmask_b32_e32 v75, v181, v80, vcc
	ds_read_b128 v[80:83], v144 offset:16448
	v_cmp_le_i32_e32 vcc, v205, v102
	s_waitcnt lgkmcnt(0)
	v_sub_f32_e32 v80, v110, v80
	v_fmac_f32_e32 v80, 0x3e38aa3b, v68
	v_cndmask_b32_e32 v68, v181, v80, vcc
	v_sub_f32_e32 v80, v110, v81
	v_fmac_f32_e32 v80, 0x3e38aa3b, v69
	v_cmp_lt_i32_e32 vcc, v205, v102
	s_nop 1
	v_cndmask_b32_e32 v69, v181, v80, vcc
	v_sub_f32_e32 v80, v110, v82
	v_fmac_f32_e32 v80, 0x3e38aa3b, v70
	v_cmp_le_i32_e32 vcc, v204, v102
	s_nop 1
	v_cndmask_b32_e32 v70, v181, v80, vcc
	v_sub_f32_e32 v80, v110, v83
	v_fmac_f32_e32 v80, 0x3e38aa3b, v71
	v_cmp_le_i32_e32 vcc, v203, v102
	s_nop 1
	v_cndmask_b32_e32 v71, v181, v80, vcc
	ds_read_b32 v80, v144 offset:16512
	v_cmp_le_i32_e32 vcc, v202, v102
	s_waitcnt lgkmcnt(0)
	v_sub_f32_e32 v80, v110, v80
	v_fmac_f32_e32 v80, 0x3e38aa3b, v64
	v_cndmask_b32_e32 v64, v181, v80, vcc
	v_cmp_le_i32_e32 vcc, v201, v102
	s_nop 1
	v_cndmask_b32_e32 v65, v181, v77, vcc
	v_sub_f32_e32 v77, v110, v78
	v_fmac_f32_e32 v77, 0x3e38aa3b, v66
	v_cmp_le_i32_e32 vcc, v200, v102
	s_nop 1
	v_cndmask_b32_e32 v66, v181, v77, vcc
	v_sub_f32_e32 v77, v110, v79
	ds_read_b128 v[78:81], v144 offset:16576
	v_fmac_f32_e32 v77, 0x3e38aa3b, v67
	v_cmp_le_i32_e32 vcc, v199, v102
	s_nop 1
	v_cndmask_b32_e32 v67, v181, v77, vcc
	s_waitcnt lgkmcnt(0)
	v_sub_f32_e32 v77, v110, v78
	v_fmac_f32_e32 v77, 0x3e38aa3b, v60
	v_cmp_le_i32_e32 vcc, v124, v102
	v_max3_f32 v78, v65, v66, v67
	s_nop 0
	v_cndmask_b32_e32 v60, v181, v77, vcc
	v_sub_f32_e32 v77, v110, v79
	v_fmac_f32_e32 v77, 0x3e38aa3b, v61
	v_cmp_le_i32_e32 vcc, v3, v102
	v_sub_f32_e32 v61, v110, v80
	v_fmac_f32_e32 v61, 0x3e38aa3b, v62
	v_cndmask_b32_e32 v3, v181, v77, vcc
	v_cmp_le_i32_e32 vcc, v2, v102
	v_max_f32_e32 v62, v72, v73
	v_max3_f32 v77, v70, v71, v64
	v_cndmask_b32_e32 v2, v181, v61, vcc
	v_sub_f32_e32 v61, v110, v81
	v_fmac_f32_e32 v61, 0x3e38aa3b, v63
	v_cmp_le_i32_e32 vcc, v198, v102
	v_max3_f32 v63, v75, v68, v69
	v_max3_f32 v79, v60, v3, v2
	v_cndmask_b32_e32 v61, v181, v61, vcc
	v_max3_f32 v62, v62, v74, v63
	v_max3_f32 v63, v78, v79, v61
	v_max3_f32 v62, v62, v77, v63
	v_mov_b32_e32 v63, v62
	s_nop 1
	v_permlane16_swap_b32_e32 v62, v63
	v_max_f32_e32 v62, v62, v63
	v_mov_b32_e32 v63, v62
	s_nop 1
	v_permlane32_swap_b32_e32 v62, v63
	v_max_f32_e32 v62, v62, v63
	v_add_f32_e32 v63, 0x41000000, v111
	v_cmp_gt_f32_e32 vcc, v62, v63
	s_cbranch_vccz .LBB0_555
	v_max_f32_e32 v63, v111, v111
	v_max_f32_e32 v62, v63, v62
	v_sub_f32_e32 v63, v111, v62
	v_exp_f32_e32 v63, v63
	v_mov_b32_e32 v111, v62
	v_mul_f32_e32 v40, v40, v63
	v_mul_f32_e32 v41, v41, v63
	v_mul_f32_e32 v42, v42, v63
	v_mul_f32_e32 v43, v43, v63
	v_mul_f32_e32 v36, v36, v63
	v_mul_f32_e32 v37, v37, v63
	v_mul_f32_e32 v38, v38, v63
	v_mul_f32_e32 v39, v39, v63
	v_mul_f32_e32 v32, v32, v63
	v_mul_f32_e32 v33, v33, v63
	v_mul_f32_e32 v34, v34, v63
	v_mul_f32_e32 v35, v35, v63
	v_mul_f32_e32 v28, v28, v63
	v_mul_f32_e32 v29, v29, v63
	v_mul_f32_e32 v30, v30, v63
	v_mul_f32_e32 v31, v31, v63
	v_mul_f32_e32 v20, v20, v63
	v_mul_f32_e32 v21, v21, v63
	v_mul_f32_e32 v22, v22, v63
	v_mul_f32_e32 v23, v23, v63

; DEVI float opq(float x) { asm("" : "+v"(x)); return x; }
; template <int DK, int MODE, int RBM, class SF, class FF, class POST>
; DEVI void attn_tile_body(const bf16x8 (&qf)[2][DK / 32], const char* Ks, const char* Vs, SF& sf, FF& ff, POST& post,
;                          int cur, int c0, int c1, float (&m)[2], float (&l)[2], f32x4 (&o)[5][2], int fr, int fq) {
;     ...
; #pragma unroll
;   for (int ks = 0; ks < NKC; ++ks)
; #pragma unroll
;     for (int kb = 0; kb < 4; ++kb) {
;       const int koff = DK == 64 ? (kb * 16 + fr) * 128 + (((ks * 4 + fq) ^ (fr & 7)) * 16)
;                                 : (kb * 16 + fr) * 192 + ((ks * 4 + (fq ^ ((fr >> 2) & 3))) * 16);
;       bf16x8 kf = *(const bf16x8*)(Ks + koff);
;       if (RBM & 1) s[kb][0] = __builtin_amdgcn_mfma_f32_16x16x32_bf16(kf, qf[0][ks], s[kb][0], 0, 0, 0);
;       if (RBM & 2) s[kb][1] = __builtin_amdgcn_mfma_f32_16x16x32_bf16(kf, qf[1][ks], s[kb][1], 0, 0, 0);
;     }
; #pragma unroll
;   for (int rb = 0; rb < 2; ++rb) {
;     if (!(RBM & (1 << rb))) continue;
;     const int cm = rb == 0 ? c0 : c1;
;     if (cm == 2) {
;       const float cl = ff.cl(rb, cur);
;       const float fsc = ff.sc;
;       if (FF::HASVEC) {
; #pragma unroll
;         for (int kb = 0; kb < 4; ++kb) {
;           const f32x4 av = ff.vec(kb);
; #pragma unroll
;           for (int j = 0; j < 4; ++j) s[kb][rb][j] = opq(fmaf(s[kb][rb][j], fsc, av[j]));
;         }
;       }
;       if (MODE == 2) {
;         const float c = cl - m[rb];
; #pragma unroll
;         for (int kb = 0; kb < 4; ++kb)
; #pragma unroll
;           for (int j = 0; j < 4; ++j) {
;             const float e = FF::HASVEC ? opq(s[kb][rb][j] + c) : opq(fmaf(s[kb][rb][j], fsc, c));
;             s[kb][rb][j] = opq(fexp2(e) * l[rb]);
;           }
;       } else if (MODE == 0) {
;         float mx = max16(s[0][rb], s[1][rb], s[2][rb], s[3][rb]);
;         mx = xmax16(mx); mx = xmax32(mx);
;         const float cand = FF::HASVEC ? (mx + cl) : fmaf(mx, fsc, cl);
;         if (__builtin_amdgcn_ballot_w64(cand > m[rb] + DEFER_THR) != 0) {
;           const float mn = fmaxf(m[rb], cand);
;           const float alpha = fexp2(m[rb] - mn);
;           m[rb] = mn;
; #pragma unroll
;           for (int db = 0; db < 5; ++db)
; #pragma unroll
;             for (int j = 0; j < 4; ++j) o[db][rb][j] = opq(o[db][rb][j] * alpha);
;         }
.LBB0_557:
	s_or_b64 exec, exec, s[38:39]
	v_cmp_lt_i32_e32 vcc, -1, v143
	s_and_saveexec_b64 s[38:39], vcc
	s_cbranch_execz .LBB0_530
	v_lshrrev_b64 v[2:3], v143, v[118:119]
	v_and_b32_e32 v2, 1, v2
	v_cmp_eq_u32_e32 vcc, 1, v2
	s_and_saveexec_b64 s[54:55], vcc
	s_cbranch_execz .LBB0_529
	v_lshlrev_b32_e32 v196, 6, v143
	s_mul_i32 s6, s42, 0x4100
	v_or_b32_e32 v2, 63, v196
	v_cmp_le_i32_e32 vcc, v2, v113
	v_add_u32_e32 v2, s6, v115
	v_add_u32_e32 v3, v2, v123
	ds_read_b128 v[72:75], v3 offset:20736
	ds_read_b128 v[60:63], v3 offset:16640
	v_add_u32_e32 v2, v2, v134
	ds_read_b128 v[68:71], v3 offset:18688
	v_add_u32_e32 v143, s6, v106
	s_waitcnt lgkmcnt(0)
	v_mfma_f32_16x16x32_bf16 v[80:83], v[72:75], v[8:11], 0
	v_mfma_f32_16x16x32_bf16 v[144:147], v[72:75], v[16:19], 0
	ds_read_b128 v[72:75], v3 offset:22784
	s_waitcnt lgkmcnt(0)
	v_mfma_f32_16x16x32_bf16 v[148:151], v[72:75], v[8:11], 0
	v_mfma_f32_16x16x32_bf16 v[192:195], v[72:75], v[16:19], 0
	ds_read_b128 v[72:75], v2 offset:16640
	v_mfma_f32_16x16x32_bf16 v[64:67], v[60:63], v[8:11], 0
	v_mfma_f32_16x16x32_bf16 v[60:63], v[60:63], v[16:19], 0
	s_waitcnt lgkmcnt(0)
	v_mfma_f32_16x16x32_bf16 v[92:95], v[72:75], v[4:7], v[64:67]
	v_mfma_f32_16x16x32_bf16 v[72:75], v[72:75], v[12:15], v[60:63]
	s_nop 4
	ds_read_b128 v[60:63], v2 offset:18688
	v_mfma_f32_16x16x32_bf16 v[76:79], v[68:71], v[8:11], 0
	v_mfma_f32_16x16x32_bf16 v[68:71], v[68:71], v[16:19], 0
	s_waitcnt lgkmcnt(0)
	v_mfma_f32_16x16x32_bf16 v[88:91], v[60:63], v[4:7], v[76:79]
	v_mfma_f32_16x16x32_bf16 v[68:71], v[60:63], v[12:15], v[68:71]
	ds_read_b128 v[60:63], v2 offset:20736
	s_waitcnt lgkmcnt(0)
	v_mfma_f32_16x16x32_bf16 v[84:87], v[60:63], v[4:7], v[80:83]
	v_mfma_f32_16x16x32_bf16 v[64:67], v[60:63], v[12:15], v[144:147]
	ds_read_b128 v[60:63], v2 offset:22784
	s_waitcnt lgkmcnt(0)
	v_mfma_f32_16x16x32_bf16 v[80:83], v[60:63], v[4:7], v[148:151]
	v_mfma_f32_16x16x32_bf16 v[60:63], v[60:63], v[12:15], v[192:195]
	s_and_saveexec_b64 s[82:83], vcc
	s_xor_b64 s[94:95], exec, s[82:83]
	s_cbranch_execz .LBB0_563
	ds_read_b128 v[76:79], v143 offset:33024
	ds_read_b128 v[146:149], v143 offset:33216
	s_waitcnt lgkmcnt(0)
	v_sub_f32_e32 v145, 0, v76
	v_sub_f32_e32 v144, 0, v77
	v_fmac_f32_e32 v145, 0x3e38aa3b, v92
	v_fmac_f32_e32 v144, 0x3e38aa3b, v93
	v_sub_f32_e32 v93, 0, v78
	v_sub_f32_e32 v92, 0, v79
	ds_read_b128 v[76:79], v143 offset:33088
	v_fmac_f32_e32 v93, 0x3e38aa3b, v94
	v_fmac_f32_e32 v92, 0x3e38aa3b, v95
	s_waitcnt lgkmcnt(0)
	v_sub_f32_e32 v94, 0, v76
	v_fmac_f32_e32 v94, 0x3e38aa3b, v88
	v_sub_f32_e32 v88, 0, v77
	v_fmac_f32_e32 v88, 0x3e38aa3b, v89
	v_sub_f32_e32 v89, 0, v78
	v_fmac_f32_e32 v89, 0x3e38aa3b, v90
	v_sub_f32_e32 v90, 0, v79
	s_waitcnt vmcnt(0)
	ds_read_b128 v[76:79], v143 offset:33152
	v_fmac_f32_e32 v90, 0x3e38aa3b, v91
	v_max_f32_e32 v2, v144, v144
	v_max_f32_e32 v3, v145, v145
	s_waitcnt lgkmcnt(0)
	v_sub_f32_e32 v91, 0, v77
	v_fmac_f32_e32 v91, 0x3e38aa3b, v85
	v_sub_f32_e32 v85, 0, v78
	v_fmac_f32_e32 v85, 0x3e38aa3b, v86
	v_sub_f32_e32 v86, 0, v146
	v_sub_f32_e32 v95, 0, v76
	v_fmac_f32_e32 v86, 0x3e38aa3b, v80
	v_sub_f32_e32 v80, 0, v147
	v_fmac_f32_e32 v95, 0x3e38aa3b, v84
	v_sub_f32_e32 v84, 0, v79
	v_fmac_f32_e32 v80, 0x3e38aa3b, v81
	v_sub_f32_e32 v81, 0, v148
	v_fmac_f32_e32 v84, 0x3e38aa3b, v87
	v_fmac_f32_e32 v81, 0x3e38aa3b, v82
	v_sub_f32_e32 v82, 0, v149
	v_fmac_f32_e32 v82, 0x3e38aa3b, v83
	v_max_f32_e32 v2, v3, v2
	v_max3_f32 v3, v92, v94, v88
	v_max3_f32 v83, v91, v85, v84
	v_max3_f32 v87, v86, v80, v81
	s_nop 0
	v_max3_f32 v76, v89, v90, v95
	v_max3_f32 v2, v2, v93, v3
	v_max3_f32 v3, v83, v87, v82
	v_max3_f32 v2, v2, v76, v3
	v_mov_b32_e32 v3, v2
	s_nop 1
	v_permlane16_swap_b32_e32 v2, v3
	v_max_f32_e32 v2, v2, v3
	v_mov_b32_e32 v3, v2
	s_nop 1
	v_permlane32_swap_b32_e32 v2, v3
	v_max_f32_e32 v124, v2, v3
	v_pk_add_f32 v[2:3], v[108:109], v[124:125]
	s_nop 0
	v_cmp_gt_f32_e32 vcc, v2, v3
	s_cbranch_vccz .LBB0_562
	v_max_f32_e32 v3, v109, v109
	v_max_f32_e32 v2, v3, v2
	v_sub_f32_e32 v3, v109, v2
	v_exp_f32_e32 v3, v3
	v_mov_b32_e32 v109, v2
	v_mul_f32_e32 v56, v56, v3
	v_mul_f32_e32 v57, v57, v3
	v_mul_f32_e32 v58, v58, v3
	v_mul_f32_e32 v59, v59, v3
	v_mul_f32_e32 v52, v52, v3
	v_mul_f32_e32 v53, v53, v3
	v_mul_f32_e32 v54, v54, v3
	v_mul_f32_e32 v55, v55, v3
	v_mul_f32_e32 v48, v48, v3
	v_mul_f32_e32 v49, v49, v3
	v_mul_f32_e32 v50, v50, v3
	v_mul_f32_e32 v51, v51, v3
	v_mul_f32_e32 v44, v44, v3
	v_mul_f32_e32 v45, v45, v3
	v_mul_f32_e32 v46, v46, v3
	v_mul_f32_e32 v47, v47, v3
	v_mul_f32_e32 v24, v24, v3
	v_mul_f32_e32 v25, v25, v3
	v_mul_f32_e32 v26, v26, v3
	v_mul_f32_e32 v27, v27, v3

; DEVI float opq(float x) { asm("" : "+v"(x)); return x; }
; DEVI float fexp2(float x) { return __builtin_amdgcn_exp2f(x); }
; template <int DK, int MODE, int RBM, class SF, class FF, class POST>
; DEVI void attn_tile_body(const bf16x8 (&qf)[2][DK / 32], const char* Ks, const char* Vs, SF& sf, FF& ff, POST& post,
;                          int cur, int c0, int c1, float (&m)[2], float (&l)[2], f32x4 (&o)[5][2], int fr, int fq) {
;     ...
; #pragma unroll
;     for (int kb = 0; kb < 4; ++kb)
; #pragma unroll
;       for (int j = 0; j < 4; ++j) s[kb][rb][j] = sf(rb, kb, j, cur, s[kb][rb][j]);
;     if (MODE == 2) {
; #pragma unroll
;       for (int kb = 0; kb < 4; ++kb)
; #pragma unroll
;         for (int j = 0; j < 4; ++j) s[kb][rb][j] = fexp2(s[kb][rb][j] - m[rb]) * l[rb];
;     } else if (MODE == 0) {
;       float mx = max16(s[0][rb], s[1][rb], s[2][rb], s[3][rb]);
;       mx = xmax16(mx); mx = xmax32(mx);
;       if (__builtin_amdgcn_ballot_w64(mx > m[rb] + DEFER_THR) != 0) {
;         const float mn = fmaxf(m[rb], mx);
;         const float alpha = fexp2(m[rb] - mn);
;         m[rb] = mn;
; #pragma unroll
;         for (int db = 0; db < 5; ++db)
; #pragma unroll
;           for (int j = 0; j < 4; ++j) o[db][rb][j] = opq(o[db][rb][j] * alpha);
;       }
;       const float mm = m[rb];
; #pragma unroll
;       for (int kb = 0; kb < 4; ++kb)
; #pragma unroll
;         for (int j = 0; j < 4; ++j) s[kb][rb][j] = fexp2(s[kb][rb][j] - mm);
.LBB0_563:
	s_or_saveexec_b64 s[94:95], s[94:95]
	v_or_b32_e32 v204, v196, v114
	v_or_b32_e32 v203, 2, v204
	v_or_b32_e32 v202, 3, v204
	v_or_b32_e32 v201, 16, v204
	v_or_b32_e32 v200, 17, v204
	v_or_b32_e32 v199, 18, v204
	v_or_b32_e32 v198, 19, v204
	v_or_b32_e32 v124, 32, v204
	v_or_b32_e32 v3, 33, v204
	v_or_b32_e32 v2, 34, v204
	v_or_b32_e32 v197, 35, v204
	s_xor_b64 exec, exec, s[94:95]
	s_cbranch_execz .LBB0_567
	ds_read_b128 v[76:79], v143 offset:33024
	v_cmp_le_i32_e32 vcc, v204, v102
	ds_read_b128 v[144:147], v143 offset:33216
	s_waitcnt lgkmcnt(0)
	v_sub_f32_e32 v76, v108, v76
	v_fmac_f32_e32 v76, 0x3e38aa3b, v92
	v_cndmask_b32_e32 v92, v181, v76, vcc
	v_sub_f32_e32 v76, v108, v77
	v_fmac_f32_e32 v76, 0x3e38aa3b, v93
	v_cmp_lt_i32_e32 vcc, v204, v102
	v_sub_f32_e32 v144, v108, v144
	v_fmac_f32_e32 v144, 0x3e38aa3b, v80
	v_cndmask_b32_e32 v93, v181, v76, vcc
	v_sub_f32_e32 v76, v108, v78
	v_fmac_f32_e32 v76, 0x3e38aa3b, v94
	v_cmp_le_i32_e32 vcc, v203, v102
	s_nop 1
	v_cndmask_b32_e32 v94, v181, v76, vcc
	v_sub_f32_e32 v76, v108, v79
	v_fmac_f32_e32 v76, 0x3e38aa3b, v95
	v_cmp_le_i32_e32 vcc, v202, v102
	s_nop 1
	v_cndmask_b32_e32 v95, v181, v76, vcc
	ds_read_b128 v[76:79], v143 offset:33088
	v_cmp_le_i32_e32 vcc, v201, v102
	s_waitcnt lgkmcnt(0)
	v_sub_f32_e32 v76, v108, v76
	v_fmac_f32_e32 v76, 0x3e38aa3b, v88
	v_cndmask_b32_e32 v88, v181, v76, vcc
	v_sub_f32_e32 v76, v108, v77
	v_fmac_f32_e32 v76, 0x3e38aa3b, v89
	v_cmp_le_i32_e32 vcc, v200, v102
	s_nop 1
	v_cndmask_b32_e32 v89, v181, v76, vcc
	v_sub_f32_e32 v76, v108, v78
	v_fmac_f32_e32 v76, 0x3e38aa3b, v90
	v_cmp_le_i32_e32 vcc, v199, v102
	s_nop 1
	v_cndmask_b32_e32 v90, v181, v76, vcc
	v_sub_f32_e32 v76, v108, v79
	v_fmac_f32_e32 v76, 0x3e38aa3b, v91
	v_cmp_le_i32_e32 vcc, v198, v102
	s_nop 1
	v_cndmask_b32_e32 v91, v181, v76, vcc
	ds_read_b128 v[76:79], v143 offset:33152
	v_cmp_le_i32_e32 vcc, v124, v102
	s_waitcnt lgkmcnt(0)
	v_sub_f32_e32 v76, v108, v76
	v_fmac_f32_e32 v76, 0x3e38aa3b, v84
	v_cndmask_b32_e32 v84, v181, v76, vcc
	v_sub_f32_e32 v76, v108, v77
	v_fmac_f32_e32 v76, 0x3e38aa3b, v85
	v_cmp_le_i32_e32 vcc, v3, v102
	s_nop 1
	v_cndmask_b32_e32 v85, v181, v76, vcc
	v_sub_f32_e32 v76, v108, v78
	v_fmac_f32_e32 v76, 0x3e38aa3b, v86
	v_cmp_le_i32_e32 vcc, v2, v102
	s_nop 1
	v_cndmask_b32_e32 v86, v181, v76, vcc
	v_sub_f32_e32 v76, v108, v79
	v_fmac_f32_e32 v76, 0x3e38aa3b, v87
	v_cmp_le_i32_e32 vcc, v197, v102
	s_nop 1
	v_cndmask_b32_e32 v87, v181, v76, vcc
	v_or_b32_e32 v76, 48, v204
	v_cmp_le_i32_e32 vcc, v76, v102
	v_or_b32_e32 v76, 49, v204
	s_nop 0
	v_cndmask_b32_e32 v80, v181, v144, vcc
	v_sub_f32_e32 v144, v108, v145
	v_fmac_f32_e32 v144, 0x3e38aa3b, v81
	v_cmp_le_i32_e32 vcc, v76, v102
	v_or_b32_e32 v76, 50, v204
	v_max3_f32 v145, v90, v91, v84
	v_cndmask_b32_e32 v81, v181, v144, vcc
	v_sub_f32_e32 v144, v108, v146
	v_fmac_f32_e32 v144, 0x3e38aa3b, v82
	v_cmp_le_i32_e32 vcc, v76, v102
	v_or_b32_e32 v76, 51, v204
	v_max3_f32 v146, v85, v86, v87
	v_cndmask_b32_e32 v82, v181, v144, vcc
	v_sub_f32_e32 v144, v108, v147
	v_fmac_f32_e32 v144, 0x3e38aa3b, v83
	v_cmp_le_i32_e32 vcc, v76, v102
	v_max_f32_e32 v76, v92, v93
	v_max3_f32 v147, v80, v81, v82
	v_cndmask_b32_e32 v83, v181, v144, vcc
	v_max3_f32 v144, v95, v88, v89
	v_max3_f32 v76, v76, v94, v144
	v_max3_f32 v144, v146, v147, v83
	v_max3_f32 v76, v76, v145, v144
	v_mov_b32_e32 v144, v76
	s_nop 1
	v_permlane16_swap_b32_e32 v76, v144
	v_max_f32_e32 v76, v76, v144
	v_mov_b32_e32 v144, v76
	s_nop 1
	v_permlane32_swap_b32_e32 v76, v144
	v_max_f32_e32 v76, v76, v144
	v_add_f32_e32 v144, 0x41000000, v109
	v_cmp_gt_f32_e32 vcc, v76, v144
	s_cbranch_vccz .LBB0_566
	v_max_f32_e32 v144, v109, v109
	v_max_f32_e32 v76, v144, v76
	v_sub_f32_e32 v109, v109, v76
	v_exp_f32_e32 v109, v109
	s_nop 0
	v_mul_f32_e32 v56, v56, v109
	v_mul_f32_e32 v57, v57, v109
	v_mul_f32_e32 v58, v58, v109
	v_mul_f32_e32 v59, v59, v109
	v_mul_f32_e32 v52, v52, v109
	v_mul_f32_e32 v53, v53, v109
	v_mul_f32_e32 v54, v54, v109
	v_mul_f32_e32 v55, v55, v109
	v_mul_f32_e32 v48, v48, v109
	v_mul_f32_e32 v49, v49, v109
	v_mul_f32_e32 v50, v50, v109
	v_mul_f32_e32 v51, v51, v109
	v_mul_f32_e32 v44, v44, v109
	v_mul_f32_e32 v45, v45, v109
	v_mul_f32_e32 v46, v46, v109
	v_mul_f32_e32 v47, v47, v109
	v_mul_f32_e32 v24, v24, v109
	v_mul_f32_e32 v25, v25, v109
	v_mul_f32_e32 v26, v26, v109
	v_mul_f32_e32 v27, v27, v109
	v_mov_b32_e32 v109, v76

; DEVI float opq(float x) { asm("" : "+v"(x)); return x; }
; DEVI float fexp2(float x) { return __builtin_amdgcn_exp2f(x); }
; template <int DK, int MODE, int RBM, class SF, class FF, class POST>
; DEVI void attn_tile_body(const bf16x8 (&qf)[2][DK / 32], const char* Ks, const char* Vs, SF& sf, FF& ff, POST& post,
;                          int cur, int c0, int c1, float (&m)[2], float (&l)[2], f32x4 (&o)[5][2], int fr, int fq) {
;     ...
;     if (cm == 2) {
;       const float cl = ff.cl(rb, cur);
;       const float fsc = ff.sc;
;       if (FF::HASVEC) {
; #pragma unroll
;         for (int kb = 0; kb < 4; ++kb) {
;           const f32x4 av = ff.vec(kb);
; #pragma unroll
;           for (int j = 0; j < 4; ++j) s[kb][rb][j] = opq(fmaf(s[kb][rb][j], fsc, av[j]));
;         }
;       }
;       if (MODE == 2) {
;         const float c = cl - m[rb];
; #pragma unroll
;         for (int kb = 0; kb < 4; ++kb)
; #pragma unroll
;           for (int j = 0; j < 4; ++j) {
;             const float e = FF::HASVEC ? opq(s[kb][rb][j] + c) : opq(fmaf(s[kb][rb][j], fsc, c));
;             s[kb][rb][j] = opq(fexp2(e) * l[rb]);
;           }
;       } else if (MODE == 0) {
;         float mx = max16(s[0][rb], s[1][rb], s[2][rb], s[3][rb]);
;         mx = xmax16(mx); mx = xmax32(mx);
;         const float cand = FF::HASVEC ? (mx + cl) : fmaf(mx, fsc, cl);
;         if (__builtin_amdgcn_ballot_w64(cand > m[rb] + DEFER_THR) != 0) {
;           const float mn = fmaxf(m[rb], cand);
;           const float alpha = fexp2(m[rb] - mn);
;           m[rb] = mn;
; #pragma unroll
;           for (int db = 0; db < 5; ++db)
; #pragma unroll
;             for (int j = 0; j < 4; ++j) o[db][rb][j] = opq(o[db][rb][j] * alpha);
;         }
.LBB0_567:
	s_or_b64 exec, exec, s[94:95]
	v_or_b32_e32 v80, 47, v196
	v_cmp_le_i32_e32 vcc, v80, v113
	s_and_saveexec_b64 s[82:83], vcc
	s_xor_b64 s[94:95], exec, s[82:83]
	s_cbranch_execz .LBB0_571
	ds_read_b128 v[78:81], v143 offset:33024
	s_waitcnt lgkmcnt(0)
	v_sub_f32_e32 v78, 0, v78
	v_sub_f32_e32 v77, 0, v79
	v_fmac_f32_e32 v78, 0x3e38aa3b, v72
	v_fmac_f32_e32 v77, 0x3e38aa3b, v73
	v_sub_f32_e32 v73, 0, v80
	v_sub_f32_e32 v72, 0, v81
	ds_read_b128 v[80:83], v143 offset:33088
	v_fmac_f32_e32 v73, 0x3e38aa3b, v74
	v_fmac_f32_e32 v72, 0x3e38aa3b, v75
	s_waitcnt lgkmcnt(0)
	v_sub_f32_e32 v74, 0, v80
	v_fmac_f32_e32 v74, 0x3e38aa3b, v68
	v_sub_f32_e32 v68, 0, v81
	v_fmac_f32_e32 v68, 0x3e38aa3b, v69
	v_sub_f32_e32 v69, 0, v82
	v_fmac_f32_e32 v69, 0x3e38aa3b, v70
	v_sub_f32_e32 v70, 0, v83
	ds_read_b128 v[80:83], v143 offset:33152
	v_fmac_f32_e32 v70, 0x3e38aa3b, v71
	v_max_f32_e32 v2, v77, v77
	v_max_f32_e32 v3, v78, v78
	s_waitcnt lgkmcnt(0)
	v_sub_f32_e32 v75, 0, v80
	v_sub_f32_e32 v71, 0, v81
	v_fmac_f32_e32 v75, 0x3e38aa3b, v64
	v_fmac_f32_e32 v71, 0x3e38aa3b, v65
	v_sub_f32_e32 v65, 0, v82
	v_sub_f32_e32 v64, 0, v83
	ds_read_b128 v[80:83], v143 offset:33216
	v_fmac_f32_e32 v65, 0x3e38aa3b, v66
	v_fmac_f32_e32 v64, 0x3e38aa3b, v67
	s_waitcnt lgkmcnt(0)
	v_sub_f32_e32 v66, 0, v80
	v_fmac_f32_e32 v66, 0x3e38aa3b, v60
	v_sub_f32_e32 v60, 0, v81
	v_fmac_f32_e32 v60, 0x3e38aa3b, v61
	v_sub_f32_e32 v61, 0, v82
	v_fmac_f32_e32 v61, 0x3e38aa3b, v62
	v_sub_f32_e32 v62, 0, v83
	v_fmac_f32_e32 v62, 0x3e38aa3b, v63
	v_max_f32_e32 v2, v3, v2
	v_max3_f32 v3, v72, v74, v68
	v_max3_f32 v67, v71, v65, v64
	v_max3_f32 v79, v66, v60, v61
	s_nop 0
	v_max3_f32 v63, v69, v70, v75
	v_max3_f32 v2, v2, v73, v3
	v_max3_f32 v3, v67, v79, v62
	v_max3_f32 v2, v2, v63, v3
	v_mov_b32_e32 v3, v2
	s_nop 1
	v_permlane16_swap_b32_e32 v2, v3
	v_max_f32_e32 v2, v2, v3
	v_mov_b32_e32 v3, v2
	s_nop 1
	v_permlane32_swap_b32_e32 v2, v3
	v_max_f32_e32 v124, v2, v3
	v_pk_add_f32 v[2:3], v[110:111], v[124:125]
	s_nop 0
	v_cmp_gt_f32_e32 vcc, v2, v3
	s_cbranch_vccz .LBB0_570
	v_max_f32_e32 v3, v111, v111
	v_max_f32_e32 v2, v3, v2
	v_sub_f32_e32 v3, v111, v2
	v_exp_f32_e32 v3, v3
	v_mov_b32_e32 v111, v2
	v_mul_f32_e32 v40, v40, v3
	v_mul_f32_e32 v41, v41, v3
	v_mul_f32_e32 v42, v42, v3
	v_mul_f32_e32 v43, v43, v3
	v_mul_f32_e32 v36, v36, v3
	v_mul_f32_e32 v37, v37, v3
	v_mul_f32_e32 v38, v38, v3
	v_mul_f32_e32 v39, v39, v3
	v_mul_f32_e32 v32, v32, v3
	v_mul_f32_e32 v33, v33, v3
	v_mul_f32_e32 v34, v34, v3
	v_mul_f32_e32 v35, v35, v3
	v_mul_f32_e32 v28, v28, v3
	v_mul_f32_e32 v29, v29, v3
	v_mul_f32_e32 v30, v30, v3
	v_mul_f32_e32 v31, v31, v3
	v_mul_f32_e32 v20, v20, v3
	v_mul_f32_e32 v21, v21, v3
	v_mul_f32_e32 v22, v22, v3
	v_mul_f32_e32 v23, v23, v3

; DEVI float opq(float x) { asm("" : "+v"(x)); return x; }
; DEVI float fexp2(float x) { return __builtin_amdgcn_exp2f(x); }
; template <int DK, int MODE, int RBM, class SF, class FF, class POST>
; DEVI void attn_tile_body(const bf16x8 (&qf)[2][DK / 32], const char* Ks, const char* Vs, SF& sf, FF& ff, POST& post,
;                          int cur, int c0, int c1, float (&m)[2], float (&l)[2], f32x4 (&o)[5][2], int fr, int fq) {
;     ...
; #pragma unroll
;     for (int kb = 0; kb < 4; ++kb)
; #pragma unroll
;       for (int j = 0; j < 4; ++j) s[kb][rb][j] = sf(rb, kb, j, cur, s[kb][rb][j]);
;     if (MODE == 2) {
; #pragma unroll
;       for (int kb = 0; kb < 4; ++kb)
; #pragma unroll
;         for (int j = 0; j < 4; ++j) s[kb][rb][j] = fexp2(s[kb][rb][j] - m[rb]) * l[rb];
;     } else if (MODE == 0) {
;       float mx = max16(s[0][rb], s[1][rb], s[2][rb], s[3][rb]);
;       mx = xmax16(mx); mx = xmax32(mx);
;       if (__builtin_amdgcn_ballot_w64(mx > m[rb] + DEFER_THR) != 0) {
;         const float mn = fmaxf(m[rb], mx);
;         const float alpha = fexp2(m[rb] - mn);
;         m[rb] = mn;
; #pragma unroll
;         for (int db = 0; db < 5; ++db)
; #pragma unroll
;           for (int j = 0; j < 4; ++j) o[db][rb][j] = opq(o[db][rb][j] * alpha);
;       }
;       const float mm = m[rb];
; #pragma unroll
;       for (int kb = 0; kb < 4; ++kb)
; #pragma unroll
;         for (int j = 0; j < 4; ++j) s[kb][rb][j] = fexp2(s[kb][rb][j] - mm);
.LBB0_571:
	s_andn2_saveexec_b64 s[94:95], s[94:95]
	s_cbranch_execz .LBB0_528
	ds_read_b128 v[80:83], v143 offset:33024
	v_cmp_le_i32_e32 vcc, v204, v104
	v_sub_f32_e32 v77, v110, v77
	v_fmac_f32_e32 v77, 0x3e38aa3b, v65
	s_waitcnt lgkmcnt(0)
	v_sub_f32_e32 v80, v110, v80
	v_fmac_f32_e32 v80, 0x3e38aa3b, v72
	v_cndmask_b32_e32 v72, v181, v80, vcc
	v_sub_f32_e32 v80, v110, v81
	v_fmac_f32_e32 v80, 0x3e38aa3b, v73
	v_cmp_lt_i32_e32 vcc, v204, v104
	s_nop 1
	v_cndmask_b32_e32 v73, v181, v80, vcc
	v_sub_f32_e32 v80, v110, v82
	v_fmac_f32_e32 v80, 0x3e38aa3b, v74
	v_cmp_le_i32_e32 vcc, v204, v140
	s_nop 1
	v_cndmask_b32_e32 v74, v181, v80, vcc
	v_sub_f32_e32 v80, v110, v83
	v_fmac_f32_e32 v80, 0x3e38aa3b, v75
	v_cmp_le_i32_e32 vcc, v204, v141
	s_nop 1
	v_cndmask_b32_e32 v75, v181, v80, vcc
	ds_read_b128 v[80:83], v143 offset:33088
	v_cmp_le_i32_e32 vcc, v204, v102
	s_waitcnt lgkmcnt(0)
	v_sub_f32_e32 v80, v110, v80
	v_fmac_f32_e32 v80, 0x3e38aa3b, v68
	v_cndmask_b32_e32 v68, v181, v80, vcc
	v_sub_f32_e32 v80, v110, v81
	v_fmac_f32_e32 v80, 0x3e38aa3b, v69
	v_cmp_lt_i32_e32 vcc, v204, v102
	s_nop 1
	v_cndmask_b32_e32 v69, v181, v80, vcc
	v_sub_f32_e32 v80, v110, v82
	v_fmac_f32_e32 v80, 0x3e38aa3b, v70
	v_cmp_le_i32_e32 vcc, v203, v102
	s_nop 1
	v_cndmask_b32_e32 v70, v181, v80, vcc
	v_sub_f32_e32 v80, v110, v83
	v_fmac_f32_e32 v80, 0x3e38aa3b, v71
	v_cmp_le_i32_e32 vcc, v202, v102
	s_nop 1
	v_cndmask_b32_e32 v71, v181, v80, vcc
	ds_read_b32 v80, v143 offset:33152
	v_cmp_le_i32_e32 vcc, v201, v102
	s_waitcnt lgkmcnt(0)
	v_sub_f32_e32 v80, v110, v80
	v_fmac_f32_e32 v80, 0x3e38aa3b, v64
	v_cndmask_b32_e32 v64, v181, v80, vcc
	v_cmp_le_i32_e32 vcc, v200, v102
	s_nop 1
	v_cndmask_b32_e32 v65, v181, v77, vcc
	v_sub_f32_e32 v77, v110, v78
	v_fmac_f32_e32 v77, 0x3e38aa3b, v66
	v_cmp_le_i32_e32 vcc, v199, v102
	s_nop 1
	v_cndmask_b32_e32 v66, v181, v77, vcc
	v_sub_f32_e32 v77, v110, v79
	ds_read_b128 v[78:81], v143 offset:33216
	v_fmac_f32_e32 v77, 0x3e38aa3b, v67
	v_cmp_le_i32_e32 vcc, v198, v102
	s_nop 1
	v_cndmask_b32_e32 v67, v181, v77, vcc
	s_waitcnt lgkmcnt(0)
	v_sub_f32_e32 v77, v110, v78
	v_fmac_f32_e32 v77, 0x3e38aa3b, v60
	v_cmp_le_i32_e32 vcc, v124, v102
	v_max3_f32 v78, v65, v66, v67
	s_nop 0
	v_cndmask_b32_e32 v60, v181, v77, vcc
	v_sub_f32_e32 v77, v110, v79
	v_fmac_f32_e32 v77, 0x3e38aa3b, v61
	v_cmp_le_i32_e32 vcc, v3, v102
	v_sub_f32_e32 v61, v110, v80
	v_fmac_f32_e32 v61, 0x3e38aa3b, v62
	v_cndmask_b32_e32 v3, v181, v77, vcc
	v_cmp_le_i32_e32 vcc, v2, v102
	v_max_f32_e32 v62, v72, v73
	v_max3_f32 v77, v70, v71, v64
	v_cndmask_b32_e32 v2, v181, v61, vcc
	v_sub_f32_e32 v61, v110, v81
	v_fmac_f32_e32 v61, 0x3e38aa3b, v63
	v_cmp_le_i32_e32 vcc, v197, v102
	v_max3_f32 v63, v75, v68, v69
	v_max3_f32 v79, v60, v3, v2
	v_cndmask_b32_e32 v61, v181, v61, vcc
	v_max3_f32 v62, v62, v74, v63
	v_max3_f32 v63, v78, v79, v61
	v_max3_f32 v62, v62, v77, v63
	v_mov_b32_e32 v63, v62
	s_nop 1
	v_permlane16_swap_b32_e32 v62, v63
	v_max_f32_e32 v62, v62, v63
	v_mov_b32_e32 v63, v62
	s_nop 1
	v_permlane32_swap_b32_e32 v62, v63
	v_max_f32_e32 v62, v62, v63
	v_add_f32_e32 v63, 0x41000000, v111
	v_cmp_gt_f32_e32 vcc, v62, v63
	s_cbranch_vccz .LBB0_527
	v_max_f32_e32 v63, v111, v111
	v_max_f32_e32 v62, v63, v62
	v_sub_f32_e32 v63, v111, v62
	v_exp_f32_e32 v63, v63
	v_mov_b32_e32 v111, v62
	v_mul_f32_e32 v40, v40, v63
	v_mul_f32_e32 v41, v41, v63
	v_mul_f32_e32 v42, v42, v63
	v_mul_f32_e32 v43, v43, v63
	v_mul_f32_e32 v36, v36, v63
	v_mul_f32_e32 v37, v37, v63
	v_mul_f32_e32 v38, v38, v63
	v_mul_f32_e32 v39, v39, v63
	v_mul_f32_e32 v32, v32, v63
	v_mul_f32_e32 v33, v33, v63
	v_mul_f32_e32 v34, v34, v63
	v_mul_f32_e32 v35, v35, v63
	v_mul_f32_e32 v28, v28, v63
	v_mul_f32_e32 v29, v29, v63
	v_mul_f32_e32 v30, v30, v63
	v_mul_f32_e32 v31, v31, v63
	v_mul_f32_e32 v20, v20, v63
	v_mul_f32_e32 v21, v21, v63
	v_mul_f32_e32 v22, v22, v63
	v_mul_f32_e32 v23, v23, v63
	s_branch .LBB0_527

; DEVI float opq(float x) { asm("" : "+v"(x)); return x; }
; template <int DK, int MODE, int RBM, class SF, class FF, class POST>
; DEVI void attn_tile_body(const bf16x8 (&qf)[2][DK / 32], const char* Ks, const char* Vs, SF& sf, FF& ff, POST& post,
;                          int cur, int c0, int c1, float (&m)[2], float (&l)[2], f32x4 (&o)[5][2], int fr, int fq) {
;     ...
; #pragma unroll
;   for (int ks = 0; ks < NKC; ++ks)
; #pragma unroll
;     for (int kb = 0; kb < 4; ++kb) {
;       const int koff = DK == 64 ? (kb * 16 + fr) * 128 + (((ks * 4 + fq) ^ (fr & 7)) * 16)
;                                 : (kb * 16 + fr) * 192 + ((ks * 4 + (fq ^ ((fr >> 2) & 3))) * 16);
;       bf16x8 kf = *(const bf16x8*)(Ks + koff);
;       if (RBM & 1) s[kb][0] = __builtin_amdgcn_mfma_f32_16x16x32_bf16(kf, qf[0][ks], s[kb][0], 0, 0, 0);
;       if (RBM & 2) s[kb][1] = __builtin_amdgcn_mfma_f32_16x16x32_bf16(kf, qf[1][ks], s[kb][1], 0, 0, 0);
;     }
; #pragma unroll
;   for (int rb = 0; rb < 2; ++rb) {
;     if (!(RBM & (1 << rb))) continue;
;     const int cm = rb == 0 ? c0 : c1;
;     if (cm == 2) {
;       const float cl = ff.cl(rb, cur);
;       const float fsc = ff.sc;
;       if (FF::HASVEC) {
; #pragma unroll
;         for (int kb = 0; kb < 4; ++kb) {
;           const f32x4 av = ff.vec(kb);
; #pragma unroll
;           for (int j = 0; j < 4; ++j) s[kb][rb][j] = opq(fmaf(s[kb][rb][j], fsc, av[j]));
;         }
;       }
;       if (MODE == 2) {
;         const float c = cl - m[rb];
; #pragma unroll
;         for (int kb = 0; kb < 4; ++kb)
; #pragma unroll
;           for (int j = 0; j < 4; ++j) {
;             const float e = FF::HASVEC ? opq(s[kb][rb][j] + c) : opq(fmaf(s[kb][rb][j], fsc, c));
;             s[kb][rb][j] = opq(fexp2(e) * l[rb]);
;           }
;       } else if (MODE == 0) {
;         float mx = max16(s[0][rb], s[1][rb], s[2][rb], s[3][rb]);
;         mx = xmax16(mx); mx = xmax32(mx);
;         const float cand = FF::HASVEC ? (mx + cl) : fmaf(mx, fsc, cl);
;         if (__builtin_amdgcn_ballot_w64(cand > m[rb] + DEFER_THR) != 0) {
;           const float mn = fmaxf(m[rb], cand);
;           const float alpha = fexp2(m[rb] - mn);
;           m[rb] = mn;
; #pragma unroll
;           for (int db = 0; db < 5; ++db)
; #pragma unroll
;             for (int j = 0; j < 4; ++j) o[db][rb][j] = opq(o[db][rb][j] * alpha);
;         }
.LBB0_592:
	s_or_b64 exec, exec, s[42:43]
	v_lshrrev_b64 v[68:69], v66, v[112:113]
	v_and_b32_e32 v0, 1, v68
	v_cmp_eq_u32_e32 vcc, 1, v0
	s_and_saveexec_b64 s[52:53], vcc
	s_cbranch_execz .LBB0_585
	v_lshlrev_b32_e32 v195, 6, v66
	v_or_b32_e32 v0, 63, v195
	v_cmp_le_i32_e32 vcc, v0, v137
	v_or_b32_e32 v0, s6, v129
	v_add_u32_e32 v0, v0, v130
	ds_read_b128 v[66:69], v0
	ds_read_b128 v[144:147], v0 offset:64
	ds_read_b128 v[74:77], v0 offset:3072
	ds_read_b128 v[82:85], v0 offset:6144
	ds_read_b128 v[90:93], v0 offset:9216
	v_add_f32_e32 v207, 0x41000000, v141
	s_waitcnt lgkmcnt(0)
	v_mfma_f32_16x16x32_bf16 v[70:73], v[66:69], v[18:21], 0
	v_mfma_f32_16x16x32_bf16 v[66:69], v[66:69], v[10:13], 0
	v_mfma_f32_16x16x32_bf16 v[70:73], v[144:147], v[2:5], v[70:73]
	v_mfma_f32_16x16x32_bf16 v[66:69], v[144:147], v[14:17], v[66:69]
	ds_read_b128 v[144:147], v0 offset:3136
	v_mfma_f32_16x16x32_bf16 v[78:81], v[74:77], v[18:21], 0
	s_waitcnt lgkmcnt(0)
	v_mfma_f32_16x16x32_bf16 v[148:151], v[144:147], v[2:5], v[78:81]
	s_nop 5
	ds_read_b128 v[78:81], v0 offset:6208
	v_mfma_f32_16x16x32_bf16 v[74:77], v[74:77], v[10:13], 0
	v_mfma_f32_16x16x32_bf16 v[86:89], v[82:85], v[18:21], 0
	v_mfma_f32_16x16x32_bf16 v[82:85], v[82:85], v[10:13], 0
	v_mfma_f32_16x16x32_bf16 v[74:77], v[144:147], v[14:17], v[74:77]
	s_waitcnt lgkmcnt(0)
	v_mfma_f32_16x16x32_bf16 v[86:89], v[78:81], v[2:5], v[86:89]
	v_mfma_f32_16x16x32_bf16 v[144:147], v[78:81], v[14:17], v[82:85]
	ds_read_b128 v[78:81], v0 offset:9280
	v_mfma_f32_16x16x32_bf16 v[94:97], v[90:93], v[18:21], 0
	v_mfma_f32_16x16x32_bf16 v[90:93], v[90:93], v[10:13], 0
	s_waitcnt lgkmcnt(0)
	v_mfma_f32_16x16x32_bf16 v[196:199], v[78:81], v[2:5], v[94:97]
	v_mfma_f32_16x16x32_bf16 v[200:203], v[78:81], v[14:17], v[90:93]
	ds_read_b128 v[78:81], v0 offset:128
	s_waitcnt lgkmcnt(0)
	v_mfma_f32_16x16x32_bf16 v[94:97], v[78:81], v[6:9], v[70:73]
	s_nop 2
	ds_read_b128 v[70:73], v0 offset:6272
	v_mfma_f32_16x16x32_bf16 v[78:81], v[78:81], v[22:25], v[66:69]
	s_nop 2
	ds_read_b128 v[66:69], v0 offset:3200
	s_waitcnt lgkmcnt(0)
	v_mfma_f32_16x16x32_bf16 v[82:85], v[66:69], v[6:9], v[148:151]
	v_mfma_f32_16x16x32_bf16 v[66:69], v[66:69], v[22:25], v[74:77]
	s_nop 2
	ds_read_b128 v[74:77], v0 offset:9344
	v_mfma_f32_16x16x32_bf16 v[86:89], v[70:73], v[6:9], v[86:89]
	v_mfma_f32_16x16x32_bf16 v[70:73], v[70:73], v[22:25], v[144:147]
	s_waitcnt lgkmcnt(0)
	v_mfma_f32_16x16x32_bf16 v[90:93], v[74:77], v[6:9], v[196:199]
	v_mfma_f32_16x16x32_bf16 v[74:77], v[74:77], v[22:25], v[200:203]
	s_and_saveexec_b64 s[42:43], vcc
	s_xor_b64 s[54:55], exec, s[42:43]
	s_cbranch_execz .LBB0_597
	v_max_f32_e32 v0, v94, v95
	v_max3_f32 v143, v97, v82, v83
	v_max3_f32 v145, v87, v88, v89
	v_max3_f32 v146, v90, v91, v92
	v_max3_f32 v144, v84, v85, v86
	v_max3_f32 v0, v0, v96, v143
	v_max3_f32 v143, v145, v146, v93
	v_max3_f32 v0, v0, v144, v143
	v_mov_b32_e32 v143, v0
	s_nop 1
	v_permlane16_swap_b32_e32 v0, v143
	v_max_f32_e32 v0, v0, v143
	v_mov_b32_e32 v143, v0
	s_nop 1
	v_permlane32_swap_b32_e32 v0, v143
	v_max_f32_e32 v0, v0, v143
	s_mov_b32 s7, 0x3e16c740
	v_fma_f32 v0, v0, s7, 0
	v_cmp_gt_f32_e32 vcc, v0, v207
	s_cbranch_vccz .LBB0_596
	v_max_f32_e32 v143, v141, v141
	v_max_f32_e32 v0, v143, v0
	v_sub_f32_e32 v141, v141, v0
	v_exp_f32_e32 v141, v141
	s_nop 0
	v_mul_f32_e32 v62, v62, v141
	v_mul_f32_e32 v63, v63, v141
	v_mul_f32_e32 v64, v64, v141
	v_mul_f32_e32 v65, v65, v141
	v_mul_f32_e32 v58, v58, v141
	v_mul_f32_e32 v59, v59, v141
	v_mul_f32_e32 v60, v60, v141
	v_mul_f32_e32 v61, v61, v141
	v_mul_f32_e32 v54, v54, v141
	v_mul_f32_e32 v55, v55, v141
	v_mul_f32_e32 v56, v56, v141
	v_mul_f32_e32 v57, v57, v141
	v_mul_f32_e32 v50, v50, v141
	v_mul_f32_e32 v51, v51, v141
	v_mul_f32_e32 v52, v52, v141
	v_mul_f32_e32 v53, v53, v141
	v_mul_f32_e32 v42, v42, v141
	v_mul_f32_e32 v43, v43, v141
	v_mul_f32_e32 v44, v44, v141
	v_mul_f32_e32 v45, v45, v141
	v_mov_b32_e32 v141, v0

; DEVI float opq(float x) { asm("" : "+v"(x)); return x; }
; DEVI float fexp2(float x) { return __builtin_amdgcn_exp2f(x); }
; template <int DK, int MODE, int RBM, class SF, class FF, class POST>
; DEVI void attn_tile_body(const bf16x8 (&qf)[2][DK / 32], const char* Ks, const char* Vs, SF& sf, FF& ff, POST& post,
;                          int cur, int c0, int c1, float (&m)[2], float (&l)[2], f32x4 (&o)[5][2], int fr, int fq) {
;     ...
; #pragma unroll
;     for (int kb = 0; kb < 4; ++kb)
; #pragma unroll
;       for (int j = 0; j < 4; ++j) s[kb][rb][j] = sf(rb, kb, j, cur, s[kb][rb][j]);
;     if (MODE == 2) {
; #pragma unroll
;       for (int kb = 0; kb < 4; ++kb)
; #pragma unroll
;         for (int j = 0; j < 4; ++j) s[kb][rb][j] = fexp2(s[kb][rb][j] - m[rb]) * l[rb];
;     } else if (MODE == 0) {
;       float mx = max16(s[0][rb], s[1][rb], s[2][rb], s[3][rb]);
;       mx = xmax16(mx); mx = xmax32(mx);
;       if (__builtin_amdgcn_ballot_w64(mx > m[rb] + DEFER_THR) != 0) {
;         const float mn = fmaxf(m[rb], mx);
;         const float alpha = fexp2(m[rb] - mn);
;         m[rb] = mn;
; #pragma unroll
;         for (int db = 0; db < 5; ++db)
; #pragma unroll
;           for (int j = 0; j < 4; ++j) o[db][rb][j] = opq(o[db][rb][j] * alpha);
;       }
;       const float mm = m[rb];
; #pragma unroll
;       for (int kb = 0; kb < 4; ++kb)
; #pragma unroll
;         for (int j = 0; j < 4; ++j) s[kb][rb][j] = fexp2(s[kb][rb][j] - mm);
.LBB0_597:
	s_or_saveexec_b64 s[54:55], s[54:55]
	v_or_b32_e32 v205, v195, v108
	v_or_b32_e32 v204, 2, v205
	v_or_b32_e32 v203, 3, v205
	v_or_b32_e32 v202, 16, v205
	v_or_b32_e32 v201, 17, v205
	v_or_b32_e32 v200, 18, v205
	v_or_b32_e32 v199, 19, v205
	v_or_b32_e32 v198, 32, v205
	v_or_b32_e32 v197, 33, v205
	v_or_b32_e32 v196, 34, v205
	v_or_b32_e32 v206, 35, v205
	s_xor_b64 exec, exec, s[54:55]
	s_cbranch_execz .LBB0_601
	v_mul_f32_e32 v0, 0x3e16c740, v94
	v_cmp_le_i32_e32 vcc, v205, v104
	v_mul_f32_e32 v94, 0x3e16c740, v95
	v_mul_f32_e32 v95, 0x3e16c740, v96
	v_cndmask_b32_e32 v0, v181, v0, vcc
	v_cmp_lt_i32_e32 vcc, v205, v104
	v_mul_f32_e32 v96, 0x3e16c740, v97
	v_mul_f32_e32 v82, 0x3e16c740, v82
	v_cndmask_b32_e32 v94, v181, v94, vcc
	v_cmp_le_i32_e32 vcc, v204, v104
	v_mul_f32_e32 v83, 0x3e16c740, v83
	v_mul_f32_e32 v84, 0x3e16c740, v84
	v_cndmask_b32_e32 v95, v181, v95, vcc
	v_cmp_le_i32_e32 vcc, v203, v104
	v_mul_f32_e32 v85, 0x3e16c740, v85
	v_mul_f32_e32 v86, 0x3e16c740, v86
	v_cndmask_b32_e32 v96, v181, v96, vcc
	v_cmp_le_i32_e32 vcc, v202, v104
	v_mul_f32_e32 v87, 0x3e16c740, v87
	v_mul_f32_e32 v88, 0x3e16c740, v88
	v_cndmask_b32_e32 v82, v181, v82, vcc
	v_cmp_le_i32_e32 vcc, v201, v104
	v_mul_f32_e32 v89, 0x3e16c740, v89
	v_or_b32_e32 v97, 48, v205
	v_cndmask_b32_e32 v83, v181, v83, vcc
	v_cmp_le_i32_e32 vcc, v200, v104
	v_mul_f32_e32 v90, 0x3e16c740, v90
	v_mul_f32_e32 v91, 0x3e16c740, v91
	v_cndmask_b32_e32 v84, v181, v84, vcc
	v_cmp_le_i32_e32 vcc, v199, v104
	v_mul_f32_e32 v92, 0x3e16c740, v92
	v_mul_f32_e32 v93, 0x3e16c740, v93
	v_cndmask_b32_e32 v85, v181, v85, vcc
	v_cmp_le_i32_e32 vcc, v198, v104
	v_max3_f32 v143, v96, v82, v83
	s_nop 0
	v_cndmask_b32_e32 v86, v181, v86, vcc
	v_cmp_le_i32_e32 vcc, v197, v104
	v_max3_f32 v144, v84, v85, v86
	s_nop 0
	v_cndmask_b32_e32 v87, v181, v87, vcc
	v_cmp_le_i32_e32 vcc, v196, v104
	s_nop 1
	v_cndmask_b32_e32 v88, v181, v88, vcc
	v_cmp_le_i32_e32 vcc, v206, v104
	s_nop 1
	v_cndmask_b32_e32 v89, v181, v89, vcc
	v_cmp_le_i32_e32 vcc, v97, v104
	v_or_b32_e32 v97, 49, v205
	v_max3_f32 v145, v87, v88, v89
	v_cndmask_b32_e32 v90, v181, v90, vcc
	v_cmp_le_i32_e32 vcc, v97, v104
	v_or_b32_e32 v97, 50, v205
	s_nop 0
	v_cndmask_b32_e32 v91, v181, v91, vcc
	v_cmp_le_i32_e32 vcc, v97, v104
	v_or_b32_e32 v97, 51, v205
	s_nop 0
	v_cndmask_b32_e32 v92, v181, v92, vcc
	v_cmp_le_i32_e32 vcc, v97, v104
	v_max_f32_e32 v97, v0, v94
	v_max3_f32 v146, v90, v91, v92
	v_cndmask_b32_e32 v93, v181, v93, vcc
	v_max3_f32 v97, v97, v95, v143
	v_max3_f32 v143, v145, v146, v93
	v_max3_f32 v97, v97, v144, v143
	v_mov_b32_e32 v143, v97
	s_nop 1
	v_permlane16_swap_b32_e32 v97, v143
	v_max_f32_e32 v97, v97, v143
	v_mov_b32_e32 v143, v97
	s_nop 1
	v_permlane32_swap_b32_e32 v97, v143
	v_max_f32_e32 v97, v97, v143
	v_cmp_gt_f32_e32 vcc, v97, v207
	s_cbranch_vccz .LBB0_600
	v_max_f32_e32 v143, v141, v141
	v_max_f32_e32 v97, v143, v97
	v_sub_f32_e32 v141, v141, v97
	v_exp_f32_e32 v141, v141
	s_nop 0
	v_mul_f32_e32 v62, v62, v141
	v_mul_f32_e32 v63, v63, v141
	v_mul_f32_e32 v64, v64, v141
	v_mul_f32_e32 v65, v65, v141
	v_mul_f32_e32 v58, v58, v141
	v_mul_f32_e32 v59, v59, v141
	v_mul_f32_e32 v60, v60, v141
	v_mul_f32_e32 v61, v61, v141
	v_mul_f32_e32 v54, v54, v141
	v_mul_f32_e32 v55, v55, v141
	v_mul_f32_e32 v56, v56, v141
	v_mul_f32_e32 v57, v57, v141
	v_mul_f32_e32 v50, v50, v141
	v_mul_f32_e32 v51, v51, v141
	v_mul_f32_e32 v52, v52, v141
	v_mul_f32_e32 v53, v53, v141
	v_mul_f32_e32 v42, v42, v141
	v_mul_f32_e32 v43, v43, v141
	v_mul_f32_e32 v44, v44, v141
	v_mul_f32_e32 v45, v45, v141
	v_mov_b32_e32 v141, v97

; DEVI float opq(float x) { asm("" : "+v"(x)); return x; }
; DEVI float fexp2(float x) { return __builtin_amdgcn_exp2f(x); }
; template <int DK, int MODE, int RBM, class SF, class FF, class POST>
; DEVI void attn_tile_body(const bf16x8 (&qf)[2][DK / 32], const char* Ks, const char* Vs, SF& sf, FF& ff, POST& post,
;                          int cur, int c0, int c1, float (&m)[2], float (&l)[2], f32x4 (&o)[5][2], int fr, int fq) {
;     ...
;     if (cm == 2) {
;       const float cl = ff.cl(rb, cur);
;       const float fsc = ff.sc;
;       if (FF::HASVEC) {
; #pragma unroll
;         for (int kb = 0; kb < 4; ++kb) {
;           const f32x4 av = ff.vec(kb);
; #pragma unroll
;           for (int j = 0; j < 4; ++j) s[kb][rb][j] = opq(fmaf(s[kb][rb][j], fsc, av[j]));
;         }
;       }
;       if (MODE == 2) {
;         const float c = cl - m[rb];
; #pragma unroll
;         for (int kb = 0; kb < 4; ++kb)
; #pragma unroll
;           for (int j = 0; j < 4; ++j) {
;             const float e = FF::HASVEC ? opq(s[kb][rb][j] + c) : opq(fmaf(s[kb][rb][j], fsc, c));
;             s[kb][rb][j] = opq(fexp2(e) * l[rb]);
;           }
;       } else if (MODE == 0) {
;         float mx = max16(s[0][rb], s[1][rb], s[2][rb], s[3][rb]);
;         mx = xmax16(mx); mx = xmax32(mx);
;         const float cand = FF::HASVEC ? (mx + cl) : fmaf(mx, fsc, cl);
;         if (__builtin_amdgcn_ballot_w64(cand > m[rb] + DEFER_THR) != 0) {
;           const float mn = fmaxf(m[rb], cand);
;           const float alpha = fexp2(m[rb] - mn);
;           m[rb] = mn;
; #pragma unroll
;           for (int db = 0; db < 5; ++db)
; #pragma unroll
;             for (int j = 0; j < 4; ++j) o[db][rb][j] = opq(o[db][rb][j] * alpha);
;         }
.LBB0_601:
	s_or_b64 exec, exec, s[54:55]
	v_or_b32_e32 v82, 47, v195
	v_cmp_le_i32_e32 vcc, v82, v137
	v_add_f32_e32 v195, 0x41000000, v142
	s_and_saveexec_b64 s[42:43], vcc
	s_xor_b64 s[54:55], exec, s[42:43]
	s_cbranch_execz .LBB0_605
	v_max_f32_e32 v82, v78, v79
	v_max3_f32 v83, v81, v66, v67
	v_max3_f32 v85, v71, v72, v73
	v_max3_f32 v86, v74, v75, v76
	v_max3_f32 v84, v68, v69, v70
	v_max3_f32 v82, v82, v80, v83
	v_max3_f32 v83, v85, v86, v77
	v_max3_f32 v82, v82, v84, v83
	v_mov_b32_e32 v83, v82
	s_nop 1
	v_permlane16_swap_b32_e32 v82, v83
	v_max_f32_e32 v82, v82, v83
	v_mov_b32_e32 v83, v82
	s_nop 1
	v_permlane32_swap_b32_e32 v82, v83
	v_max_f32_e32 v82, v82, v83
	s_mov_b32 s7, 0x3e16c740
	v_fma_f32 v82, v82, s7, 0
	v_cmp_gt_f32_e32 vcc, v82, v195
	s_cbranch_vccz .LBB0_604
	v_max_f32_e32 v83, v142, v142
	v_max_f32_e32 v82, v83, v82
	v_sub_f32_e32 v83, v142, v82
	v_exp_f32_e32 v83, v83
	v_mov_b32_e32 v142, v82
	v_mul_f32_e32 v46, v46, v83
	v_mul_f32_e32 v47, v47, v83
	v_mul_f32_e32 v48, v48, v83
	v_mul_f32_e32 v49, v49, v83
	v_mul_f32_e32 v38, v38, v83
	v_mul_f32_e32 v39, v39, v83
	v_mul_f32_e32 v40, v40, v83
	v_mul_f32_e32 v41, v41, v83
	v_mul_f32_e32 v34, v34, v83
	v_mul_f32_e32 v35, v35, v83
	v_mul_f32_e32 v36, v36, v83
	v_mul_f32_e32 v37, v37, v83
	v_mul_f32_e32 v30, v30, v83
	v_mul_f32_e32 v31, v31, v83
	v_mul_f32_e32 v32, v32, v83
	v_mul_f32_e32 v33, v33, v83
	v_mul_f32_e32 v26, v26, v83
	v_mul_f32_e32 v27, v27, v83
	v_mul_f32_e32 v28, v28, v83
	v_mul_f32_e32 v29, v29, v83

; DEVI float opq(float x) { asm("" : "+v"(x)); return x; }
; DEVI float fexp2(float x) { return __builtin_amdgcn_exp2f(x); }
; template <int DK, int MODE, int RBM, class SF, class FF, class POST>
; DEVI void attn_tile_body(const bf16x8 (&qf)[2][DK / 32], const char* Ks, const char* Vs, SF& sf, FF& ff, POST& post,
;                          int cur, int c0, int c1, float (&m)[2], float (&l)[2], f32x4 (&o)[5][2], int fr, int fq) {
;     ...
; #pragma unroll
;     for (int kb = 0; kb < 4; ++kb)
; #pragma unroll
;       for (int j = 0; j < 4; ++j) s[kb][rb][j] = sf(rb, kb, j, cur, s[kb][rb][j]);
;     if (MODE == 2) {
; #pragma unroll
;       for (int kb = 0; kb < 4; ++kb)
; #pragma unroll
;         for (int j = 0; j < 4; ++j) s[kb][rb][j] = fexp2(s[kb][rb][j] - m[rb]) * l[rb];
;     } else if (MODE == 0) {
;       float mx = max16(s[0][rb], s[1][rb], s[2][rb], s[3][rb]);
;       mx = xmax16(mx); mx = xmax32(mx);
;       if (__builtin_amdgcn_ballot_w64(mx > m[rb] + DEFER_THR) != 0) {
;         const float mn = fmaxf(m[rb], mx);
;         const float alpha = fexp2(m[rb] - mn);
;         m[rb] = mn;
; #pragma unroll
;         for (int db = 0; db < 5; ++db)
; #pragma unroll
;           for (int j = 0; j < 4; ++j) o[db][rb][j] = opq(o[db][rb][j] * alpha);
;       }
;       const float mm = m[rb];
; #pragma unroll
;       for (int kb = 0; kb < 4; ++kb)
; #pragma unroll
;         for (int j = 0; j < 4; ++j) s[kb][rb][j] = fexp2(s[kb][rb][j] - mm);
.LBB0_605:
	s_andn2_saveexec_b64 s[54:55], s[54:55]
	s_cbranch_execz .LBB0_584
	v_mul_f32_e32 v78, 0x3e16c740, v78
	v_cmp_le_i32_e32 vcc, v205, v106
	v_mul_f32_e32 v79, 0x3e16c740, v79
	v_mul_f32_e32 v80, 0x3e16c740, v80
	v_cndmask_b32_e32 v78, v181, v78, vcc
	v_cmp_lt_i32_e32 vcc, v205, v106
	v_mul_f32_e32 v81, 0x3e16c740, v81
	v_mul_f32_e32 v66, 0x3e16c740, v66
	v_cndmask_b32_e32 v79, v181, v79, vcc
	v_cmp_le_i32_e32 vcc, v205, v138
	v_mul_f32_e32 v67, 0x3e16c740, v67
	v_mul_f32_e32 v68, 0x3e16c740, v68
	v_cndmask_b32_e32 v80, v181, v80, vcc
	v_cmp_le_i32_e32 vcc, v205, v139
	v_mul_f32_e32 v69, 0x3e16c740, v69
	v_mul_f32_e32 v70, 0x3e16c740, v70
	v_cndmask_b32_e32 v81, v181, v81, vcc
	v_cmp_le_i32_e32 vcc, v205, v104
	v_mul_f32_e32 v71, 0x3e16c740, v71
	v_mul_f32_e32 v72, 0x3e16c740, v72
	v_cndmask_b32_e32 v66, v181, v66, vcc
	v_cmp_lt_i32_e32 vcc, v205, v104
	v_mul_f32_e32 v73, 0x3e16c740, v73
	v_mul_f32_e32 v74, 0x3e16c740, v74
	v_cndmask_b32_e32 v67, v181, v67, vcc
	v_cmp_le_i32_e32 vcc, v204, v104
	v_mul_f32_e32 v75, 0x3e16c740, v75
	v_mul_f32_e32 v76, 0x3e16c740, v76
	v_cndmask_b32_e32 v68, v181, v68, vcc
	v_cmp_le_i32_e32 vcc, v203, v104
	v_mul_f32_e32 v77, 0x3e16c740, v77
	v_max_f32_e32 v82, v78, v79
	v_cndmask_b32_e32 v69, v181, v69, vcc
	v_cmp_le_i32_e32 vcc, v202, v104
	v_max3_f32 v83, v81, v66, v67
	v_max3_f32 v82, v82, v80, v83
	v_cndmask_b32_e32 v70, v181, v70, vcc
	v_cmp_le_i32_e32 vcc, v201, v104
	v_max3_f32 v84, v68, v69, v70
	s_nop 0
	v_cndmask_b32_e32 v71, v181, v71, vcc
	v_cmp_le_i32_e32 vcc, v200, v104
	s_nop 1
	v_cndmask_b32_e32 v72, v181, v72, vcc
	v_cmp_le_i32_e32 vcc, v199, v104
	s_nop 1
	v_cndmask_b32_e32 v73, v181, v73, vcc
	v_cmp_le_i32_e32 vcc, v198, v104
	v_max3_f32 v85, v71, v72, v73
	s_nop 0
	v_cndmask_b32_e32 v74, v181, v74, vcc
	v_cmp_le_i32_e32 vcc, v197, v104
	s_nop 1
	v_cndmask_b32_e32 v75, v181, v75, vcc
	v_cmp_le_i32_e32 vcc, v196, v104
	s_nop 1
	v_cndmask_b32_e32 v76, v181, v76, vcc
	v_cmp_le_i32_e32 vcc, v206, v104
	v_max3_f32 v86, v74, v75, v76
	s_nop 0
	v_cndmask_b32_e32 v77, v181, v77, vcc
	v_max3_f32 v83, v85, v86, v77
	v_max3_f32 v82, v82, v84, v83
	v_mov_b32_e32 v83, v82
	s_nop 1
	v_permlane16_swap_b32_e32 v82, v83
	v_max_f32_e32 v82, v82, v83
	v_mov_b32_e32 v83, v82
	s_nop 1
	v_permlane32_swap_b32_e32 v82, v83
	v_max_f32_e32 v82, v82, v83
	v_cmp_gt_f32_e32 vcc, v82, v195
	s_cbranch_vccz .LBB0_583
	v_max_f32_e32 v83, v142, v142
	v_max_f32_e32 v82, v83, v82
	v_sub_f32_e32 v83, v142, v82
	v_exp_f32_e32 v83, v83
	v_mov_b32_e32 v142, v82
	v_mul_f32_e32 v46, v46, v83
	v_mul_f32_e32 v47, v47, v83
	v_mul_f32_e32 v48, v48, v83
	v_mul_f32_e32 v49, v49, v83
	v_mul_f32_e32 v38, v38, v83
	v_mul_f32_e32 v39, v39, v83
	v_mul_f32_e32 v40, v40, v83
	v_mul_f32_e32 v41, v41, v83
	v_mul_f32_e32 v34, v34, v83
	v_mul_f32_e32 v35, v35, v83
	v_mul_f32_e32 v36, v36, v83
	v_mul_f32_e32 v37, v37, v83
	v_mul_f32_e32 v30, v30, v83
	v_mul_f32_e32 v31, v31, v83
	v_mul_f32_e32 v32, v32, v83
	v_mul_f32_e32 v33, v33, v83
	v_mul_f32_e32 v26, v26, v83
	v_mul_f32_e32 v27, v27, v83
	v_mul_f32_e32 v28, v28, v83
	v_mul_f32_e32 v29, v29, v83
	s_branch .LBB0_583

; DEVI float opq(float x) { asm("" : "+v"(x)); return x; }
; DEVI float fexp2(float x) { return __builtin_amdgcn_exp2f(x); }
; template <int DK, int MODE, int RBM, class SF, class FF, class POST>
; DEVI void attn_tile_body(const bf16x8 (&qf)[2][DK / 32], const char* Ks, const char* Vs, SF& sf, FF& ff, POST& post,
;                          int cur, int c0, int c1, float (&m)[2], float (&l)[2], f32x4 (&o)[5][2], int fr, int fq) {
;     ...
;       } else {
;         float mx = max16(s[0][rb], s[1][rb], s[2][rb], s[3][rb]);
;         mx = xmax16(mx); mx = xmax32(mx);
;         const float cand = FF::HASVEC ? (mx + cl) : fmaf(mx, fsc, cl);
;         const float mn = fmaxf(m[rb], cand);
;         const float alpha = fexp2(m[rb] - mn);
;         m[rb] = mn;
;         const float c = cl - mn;
;         float rs0 = 0.f, rs1 = 0.f;
; #pragma unroll
;         for (int kb = 0; kb < 4; ++kb)
; #pragma unroll
;           for (int j = 0; j < 4; ++j) {
;             const float e = FF::HASVEC ? opq(s[kb][rb][j] + c) : opq(fmaf(s[kb][rb][j], fsc, c));
;             const float pv = fexp2(e);
;             s[kb][rb][j] = pv;
;             if (j & 1) rs1 = opq(rs1 + pv); else rs0 = opq(rs0 + pv);
;           }
;         l[rb] = fmaf(l[rb], alpha, rs0 + rs1);
;       }
;     ...
;     } else {
;       float mx = -INFINITY;
; #pragma unroll
;       for (int kb = 0; kb < 4; ++kb)
; #pragma unroll
;         for (int j = 0; j < 4; ++j) mx = fmaxf(mx, s[kb][rb][j]);
;       mx = xmax16(mx); mx = xmax32(mx);
;       const float mn = fmaxf(m[rb], mx);
;       const float alpha = fexp2(m[rb] - mn);
;       m[rb] = mn;
;       float rs = 0.f;
; #pragma unroll
;       for (int kb = 0; kb < 4; ++kb)
; #pragma unroll
;         for (int j = 0; j < 4; ++j) { float pv = fexp2(s[kb][rb][j] - mn); s[kb][rb][j] = pv; rs += pv; }
;       l[rb] = l[rb] * alpha + rs;
.LBB0_669:
	s_or_b64 exec, exec, s[6:7]
	v_max3_f32 v0, v79, s49, v63
	v_max3_f32 v0, v0, v49, v48
	v_max3_f32 v0, v0, v51, v50
	v_max3_f32 v0, v0, v45, v44
	v_max3_f32 v0, v0, v47, v46
	v_max3_f32 v0, v0, v41, v40
	v_max3_f32 v0, v0, v43, v42
	v_max3_f32 v0, v0, v37, v36
	v_mov_b32_e32 v38, v0
	s_nop 1
	v_permlane16_swap_b32_e32 v0, v38
	v_max_f32_e32 v0, v0, v38
	v_mov_b32_e32 v38, v0
	s_nop 1
	v_permlane32_swap_b32_e32 v0, v38
	v_max3_f32 v0, v148, v0, v38
	v_sub_f32_e32 v38, v79, v0
	v_exp_f32_e32 v38, v38
	v_sub_f32_e32 v63, v63, v0
	v_exp_f32_e32 v63, v63
	v_sub_f32_e32 v49, v49, v0
	v_exp_f32_e32 v49, v49
	v_sub_f32_e32 v48, v48, v0
	v_exp_f32_e32 v48, v48
	v_add_f32_e32 v38, 0, v38
	v_add_f32_e32 v38, v63, v38
	v_sub_f32_e32 v51, v51, v0
	v_add_f32_e32 v38, v49, v38
	v_exp_f32_e32 v51, v51
	v_add_f32_e32 v38, v48, v38
	v_sub_f32_e32 v48, v50, v0
	v_exp_f32_e32 v48, v48
	v_sub_f32_e32 v45, v45, v0
	v_exp_f32_e32 v45, v45
	v_sub_f32_e32 v44, v44, v0
	v_exp_f32_e32 v44, v44
	v_add_f32_e32 v38, v51, v38
	v_add_f32_e32 v38, v48, v38
	v_sub_f32_e32 v47, v47, v0
	v_add_f32_e32 v38, v45, v38
	v_exp_f32_e32 v47, v47
	v_add_f32_e32 v38, v44, v38
	v_sub_f32_e32 v44, v46, v0
	v_exp_f32_e32 v44, v44
	v_sub_f32_e32 v41, v41, v0
	v_exp_f32_e32 v41, v41
	v_sub_f32_e32 v40, v40, v0
	v_exp_f32_e32 v40, v40
	v_add_f32_e32 v38, v47, v38
	v_add_f32_e32 v38, v44, v38
	v_sub_f32_e32 v43, v43, v0
	v_add_f32_e32 v38, v41, v38
	v_exp_f32_e32 v43, v43
	v_add_f32_e32 v38, v40, v38
	v_sub_f32_e32 v40, v42, v0
	v_exp_f32_e32 v40, v40
	v_sub_f32_e32 v37, v37, v0
	v_exp_f32_e32 v37, v37
	v_sub_f32_e32 v36, v36, v0
	v_sub_f32_e32 v39, v148, v0
	v_exp_f32_e32 v36, v36
	v_add_f32_e32 v38, v43, v38
	v_exp_f32_e32 v39, v39
	v_add_f32_e32 v38, v40, v38
	v_add_f32_e32 v37, v37, v38
	v_add_f32_e32 v63, v36, v37
	v_fmac_f32_e32 v63, v61, v39
.LBB0_670:
	s_andn2_saveexec_b64 s[38:39], s[54:55]
	s_cbranch_execz .LBB0_672
	v_max_f32_e32 v0, v48, v49
	v_max3_f32 v63, v51, v44, v45
	v_max3_f32 v80, v41, v42, v43
	v_max3_f32 v81, v36, v37, v38
	v_max3_f32 v79, v46, v47, v40
	v_max3_f32 v0, v0, v50, v63
	v_max3_f32 v63, v80, v81, v39
	v_max3_f32 v0, v0, v79, v63
	v_mov_b32_e32 v63, v0
	s_nop 1
	v_permlane16_swap_b32_e32 v0, v63
	v_max_f32_e32 v0, v0, v63
	v_mov_b32_e32 v63, v0
	s_nop 1
	v_permlane32_swap_b32_e32 v0, v63
	v_max_f32_e32 v0, v0, v63
	v_fmamk_f32 v0, v0, 0x3e38aa3b, v65
	v_max_f32_e32 v63, v148, v148
	v_max_f32_e32 v0, v63, v0
	v_sub_f32_e32 v63, v65, v0
	v_fmamk_f32 v48, v48, 0x3e38aa3b, v63
	v_fmamk_f32 v49, v49, 0x3e38aa3b, v63
	v_exp_f32_e32 v48, v48
	v_fmamk_f32 v50, v50, 0x3e38aa3b, v63
	v_fmamk_f32 v44, v44, 0x3e38aa3b, v63
	v_exp_f32_e32 v49, v49
	v_exp_f32_e32 v50, v50
	v_fmamk_f32 v51, v51, 0x3e38aa3b, v63
	v_fmamk_f32 v45, v45, 0x3e38aa3b, v63
	v_exp_f32_e32 v44, v44
	v_fmamk_f32 v46, v46, 0x3e38aa3b, v63
	v_add_f32_e32 v48, 0, v48
	v_exp_f32_e32 v51, v51
	v_fmamk_f32 v40, v40, 0x3e38aa3b, v63
	v_exp_f32_e32 v45, v45
	v_exp_f32_e32 v46, v46
	v_fmamk_f32 v47, v47, 0x3e38aa3b, v63
	v_add_f32_e32 v49, 0, v49
	v_add_f32_e32 v48, v48, v50
	v_exp_f32_e32 v40, v40
	v_fmamk_f32 v41, v41, 0x3e38aa3b, v63
	v_fmamk_f32 v42, v42, 0x3e38aa3b, v63
	v_exp_f32_e32 v47, v47
	v_add_f32_e32 v44, v48, v44
	v_fmamk_f32 v36, v36, 0x3e38aa3b, v63
	v_add_f32_e32 v49, v49, v51
	v_exp_f32_e32 v41, v41
	v_exp_f32_e32 v42, v42
	v_fmamk_f32 v43, v43, 0x3e38aa3b, v63
	v_add_f32_e32 v44, v44, v46
	v_add_f32_e32 v45, v49, v45
	v_exp_f32_e32 v36, v36
	v_fmamk_f32 v37, v37, 0x3e38aa3b, v63
	v_fmamk_f32 v38, v38, 0x3e38aa3b, v63
	v_exp_f32_e32 v43, v43
	v_add_f32_e32 v40, v44, v40
	v_add_f32_e32 v45, v45, v47
	v_exp_f32_e32 v37, v37
	v_exp_f32_e32 v38, v38
	v_add_f32_e32 v40, v40, v42
	v_add_f32_e32 v41, v45, v41
	v_fmac_f32_e32 v63, 0x3e38aa3b, v39
	v_sub_f32_e32 v79, v148, v0
	v_add_f32_e32 v36, v40, v36
	v_exp_f32_e32 v39, v63
	v_add_f32_e32 v41, v41, v43
	s_nop 0
	v_add_f32_e32 v37, v41, v37
	v_add_f32_e32 v36, v36, v38
	v_exp_f32_e32 v38, v79
	s_nop 0
	v_add_f32_e32 v37, v37, v39
	s_nop 0
	v_add_f32_e32 v63, v36, v37
	v_fmac_f32_e32 v63, v61, v38

; DEVI float opq(float x) { asm("" : "+v"(x)); return x; }
; DEVI float fexp2(float x) { return __builtin_amdgcn_exp2f(x); }
; template <int DK, int MODE, int RBM, class SF, class FF, class POST>
; DEVI void attn_tile_body(const bf16x8 (&qf)[2][DK / 32], const char* Ks, const char* Vs, SF& sf, FF& ff, POST& post,
;                          int cur, int c0, int c1, float (&m)[2], float (&l)[2], f32x4 (&o)[5][2], int fr, int fq) {
;     ...
;       } else {
;         float mx = max16(s[0][rb], s[1][rb], s[2][rb], s[3][rb]);
;         mx = xmax16(mx); mx = xmax32(mx);
;         const float cand = FF::HASVEC ? (mx + cl) : fmaf(mx, fsc, cl);
;         const float mn = fmaxf(m[rb], cand);
;         const float alpha = fexp2(m[rb] - mn);
;         m[rb] = mn;
;         const float c = cl - mn;
;         float rs0 = 0.f, rs1 = 0.f;
; #pragma unroll
;         for (int kb = 0; kb < 4; ++kb)
; #pragma unroll
;           for (int j = 0; j < 4; ++j) {
;             const float e = FF::HASVEC ? opq(s[kb][rb][j] + c) : opq(fmaf(s[kb][rb][j], fsc, c));
;             const float pv = fexp2(e);
;             s[kb][rb][j] = pv;
;             if (j & 1) rs1 = opq(rs1 + pv); else rs0 = opq(rs0 + pv);
;           }
;         l[rb] = fmaf(l[rb], alpha, rs0 + rs1);
;       }
;     ...
;     } else {
;       float mx = -INFINITY;
; #pragma unroll
;       for (int kb = 0; kb < 4; ++kb)
; #pragma unroll
;         for (int j = 0; j < 4; ++j) mx = fmaxf(mx, s[kb][rb][j]);
;       mx = xmax16(mx); mx = xmax32(mx);
;       const float mn = fmaxf(m[rb], mx);
;       const float alpha = fexp2(m[rb] - mn);
;       m[rb] = mn;
;       float rs = 0.f;
; #pragma unroll
;       for (int kb = 0; kb < 4; ++kb)
; #pragma unroll
;         for (int j = 0; j < 4; ++j) { float pv = fexp2(s[kb][rb][j] - mn); s[kb][rb][j] = pv; rs += pv; }
;       l[rb] = l[rb] * alpha + rs;
.LBB0_705:
	s_or_b64 exec, exec, s[6:7]
	v_max3_f32 v22, v37, s49, v36
	v_max3_f32 v22, v22, v33, v32
	v_max3_f32 v22, v22, v35, v34
	v_max3_f32 v22, v22, v29, v28
	v_max3_f32 v22, v22, v31, v30
	v_max3_f32 v22, v22, v25, v24
	v_max3_f32 v22, v22, v27, v26
	v_max3_f32 v22, v22, v21, v20
	v_mov_b32_e32 v23, v22
	s_nop 1
	v_permlane16_swap_b32_e32 v22, v23
	v_max_f32_e32 v22, v22, v23
	v_mov_b32_e32 v23, v22
	s_nop 1
	v_permlane32_swap_b32_e32 v22, v23
	v_max3_f32 v38, v146, v22, v23
	v_sub_f32_e32 v22, v37, v38
	v_exp_f32_e32 v22, v22
	v_sub_f32_e32 v36, v36, v38
	v_exp_f32_e32 v36, v36
	v_sub_f32_e32 v33, v33, v38
	v_exp_f32_e32 v33, v33
	v_sub_f32_e32 v32, v32, v38
	v_exp_f32_e32 v32, v32
	v_add_f32_e32 v22, 0, v22
	v_add_f32_e32 v22, v36, v22
	v_sub_f32_e32 v35, v35, v38
	v_add_f32_e32 v22, v33, v22
	v_exp_f32_e32 v35, v35
	v_add_f32_e32 v22, v32, v22
	v_sub_f32_e32 v32, v34, v38
	v_exp_f32_e32 v32, v32
	v_sub_f32_e32 v29, v29, v38
	v_exp_f32_e32 v29, v29
	v_sub_f32_e32 v28, v28, v38
	v_exp_f32_e32 v28, v28
	v_add_f32_e32 v22, v35, v22
	v_add_f32_e32 v22, v32, v22
	v_sub_f32_e32 v31, v31, v38
	v_add_f32_e32 v22, v29, v22
	v_exp_f32_e32 v31, v31
	v_add_f32_e32 v22, v28, v22
	v_sub_f32_e32 v28, v30, v38
	v_exp_f32_e32 v28, v28
	v_sub_f32_e32 v25, v25, v38
	v_exp_f32_e32 v25, v25
	v_sub_f32_e32 v24, v24, v38
	v_exp_f32_e32 v24, v24
	v_add_f32_e32 v22, v31, v22
	v_add_f32_e32 v22, v28, v22
	v_sub_f32_e32 v27, v27, v38
	v_add_f32_e32 v22, v25, v22
	v_exp_f32_e32 v27, v27
	v_add_f32_e32 v22, v24, v22
	v_sub_f32_e32 v24, v26, v38
	v_exp_f32_e32 v24, v24
	v_sub_f32_e32 v21, v21, v38
	v_exp_f32_e32 v21, v21
	v_sub_f32_e32 v20, v20, v38
	v_sub_f32_e32 v23, v146, v38
	v_exp_f32_e32 v20, v20
	v_add_f32_e32 v22, v27, v22
	v_exp_f32_e32 v23, v23
	v_add_f32_e32 v22, v24, v22
	v_add_f32_e32 v21, v21, v22
	v_add_f32_e32 v62, v20, v21
	v_fmac_f32_e32 v62, v60, v23
.LBB0_706:
	s_andn2_saveexec_b64 s[38:39], s[54:55]
	s_cbranch_execz .LBB0_708
	v_max_f32_e32 v36, v32, v33
	v_max3_f32 v37, v35, v28, v29
	v_max3_f32 v39, v25, v26, v27
	v_max3_f32 v40, v20, v21, v22
	v_max3_f32 v38, v30, v31, v24
	v_max3_f32 v36, v36, v34, v37
	v_max3_f32 v37, v39, v40, v23
	v_max3_f32 v36, v36, v38, v37
	v_mov_b32_e32 v37, v36
	s_nop 1
	v_permlane16_swap_b32_e32 v36, v37
	v_max_f32_e32 v36, v36, v37
	v_mov_b32_e32 v37, v36
	s_nop 1
	v_permlane32_swap_b32_e32 v36, v37
	v_max_f32_e32 v36, v36, v37
	v_fmamk_f32 v36, v36, 0x3e38aa3b, v65
	v_max_f32_e32 v37, v146, v146
	v_max_f32_e32 v38, v37, v36
	v_sub_f32_e32 v36, v65, v38
	v_fmamk_f32 v32, v32, 0x3e38aa3b, v36
	v_fmamk_f32 v33, v33, 0x3e38aa3b, v36
	v_exp_f32_e32 v32, v32
	v_fmamk_f32 v34, v34, 0x3e38aa3b, v36
	v_fmamk_f32 v28, v28, 0x3e38aa3b, v36
	v_exp_f32_e32 v33, v33
	v_exp_f32_e32 v34, v34
	v_fmamk_f32 v35, v35, 0x3e38aa3b, v36
	v_fmamk_f32 v29, v29, 0x3e38aa3b, v36
	v_exp_f32_e32 v28, v28
	v_fmamk_f32 v30, v30, 0x3e38aa3b, v36
	v_add_f32_e32 v32, 0, v32
	v_exp_f32_e32 v35, v35
	v_fmamk_f32 v24, v24, 0x3e38aa3b, v36
	v_exp_f32_e32 v29, v29
	v_exp_f32_e32 v30, v30
	v_fmamk_f32 v31, v31, 0x3e38aa3b, v36
	v_add_f32_e32 v33, 0, v33
	v_add_f32_e32 v32, v32, v34
	v_exp_f32_e32 v24, v24
	v_fmamk_f32 v25, v25, 0x3e38aa3b, v36
	v_fmamk_f32 v26, v26, 0x3e38aa3b, v36
	v_exp_f32_e32 v31, v31
	v_add_f32_e32 v28, v32, v28
	v_fmamk_f32 v20, v20, 0x3e38aa3b, v36
	v_add_f32_e32 v33, v33, v35
	v_exp_f32_e32 v25, v25
	v_exp_f32_e32 v26, v26
	v_fmamk_f32 v27, v27, 0x3e38aa3b, v36
	v_add_f32_e32 v28, v28, v30
	v_add_f32_e32 v29, v33, v29
	v_exp_f32_e32 v20, v20
	v_fmamk_f32 v21, v21, 0x3e38aa3b, v36
	v_fmamk_f32 v22, v22, 0x3e38aa3b, v36
	v_exp_f32_e32 v27, v27
	v_add_f32_e32 v24, v28, v24
	v_add_f32_e32 v29, v29, v31
	v_exp_f32_e32 v21, v21
	v_exp_f32_e32 v22, v22
	v_add_f32_e32 v24, v24, v26
	v_add_f32_e32 v25, v29, v25
	v_fmac_f32_e32 v36, 0x3e38aa3b, v23
	v_sub_f32_e32 v37, v146, v38
	v_add_f32_e32 v20, v24, v20
	v_exp_f32_e32 v23, v36
	v_add_f32_e32 v25, v25, v27
	s_nop 0
	v_add_f32_e32 v21, v25, v21
	v_add_f32_e32 v20, v20, v22
	v_exp_f32_e32 v22, v37
	s_nop 0
	v_add_f32_e32 v21, v21, v23
	s_nop 0
	v_add_f32_e32 v62, v20, v21
	v_fmac_f32_e32 v62, v60, v22

; DEVI float opq(float x) { asm("" : "+v"(x)); return x; }
; DEVI float fexp2(float x) { return __builtin_amdgcn_exp2f(x); }
; template <int DK, int MODE, int RBM, class SF, class FF, class POST>
; DEVI void attn_tile_body(const bf16x8 (&qf)[2][DK / 32], const char* Ks, const char* Vs, SF& sf, FF& ff, POST& post,
;                          int cur, int c0, int c1, float (&m)[2], float (&l)[2], f32x4 (&o)[5][2], int fr, int fq) {
;     ...
;       } else {
;         float mx = max16(s[0][rb], s[1][rb], s[2][rb], s[3][rb]);
;         mx = xmax16(mx); mx = xmax32(mx);
;         const float cand = FF::HASVEC ? (mx + cl) : fmaf(mx, fsc, cl);
;         const float mn = fmaxf(m[rb], cand);
;         const float alpha = fexp2(m[rb] - mn);
;         m[rb] = mn;
;         const float c = cl - mn;
;         float rs0 = 0.f, rs1 = 0.f;
; #pragma unroll
;         for (int kb = 0; kb < 4; ++kb)
; #pragma unroll
;           for (int j = 0; j < 4; ++j) {
;             const float e = FF::HASVEC ? opq(s[kb][rb][j] + c) : opq(fmaf(s[kb][rb][j], fsc, c));
;             const float pv = fexp2(e);
;             s[kb][rb][j] = pv;
;             if (j & 1) rs1 = opq(rs1 + pv); else rs0 = opq(rs0 + pv);
;           }
;         l[rb] = fmaf(l[rb], alpha, rs0 + rs1);
;       }
;     ...
;     } else {
;       float mx = -INFINITY;
; #pragma unroll
;       for (int kb = 0; kb < 4; ++kb)
; #pragma unroll
;         for (int j = 0; j < 4; ++j) mx = fmaxf(mx, s[kb][rb][j]);
;       mx = xmax16(mx); mx = xmax32(mx);
;       const float mn = fmaxf(m[rb], mx);
;       const float alpha = fexp2(m[rb] - mn);
;       m[rb] = mn;
;       float rs = 0.f;
; #pragma unroll
;       for (int kb = 0; kb < 4; ++kb)
; #pragma unroll
;         for (int j = 0; j < 4; ++j) { float pv = fexp2(s[kb][rb][j] - mn); s[kb][rb][j] = pv; rs += pv; }
;       l[rb] = l[rb] * alpha + rs;
.LBB0_744:
	s_or_b64 exec, exec, s[6:7]
	v_max3_f32 v0, v78, s49, v63
	v_max3_f32 v0, v0, v49, v48
	v_max3_f32 v0, v0, v51, v50
	v_max3_f32 v0, v0, v45, v44
	v_max3_f32 v0, v0, v47, v46
	v_max3_f32 v0, v0, v41, v40
	v_max3_f32 v0, v0, v43, v42
	v_max3_f32 v0, v0, v37, v36
	v_mov_b32_e32 v38, v0
	s_nop 1
	v_permlane16_swap_b32_e32 v0, v38
	v_max_f32_e32 v0, v0, v38
	v_mov_b32_e32 v38, v0
	s_nop 1
	v_permlane32_swap_b32_e32 v0, v38
	v_max3_f32 v0, v148, v0, v38
	v_sub_f32_e32 v38, v78, v0
	v_exp_f32_e32 v38, v38
	v_sub_f32_e32 v63, v63, v0
	v_exp_f32_e32 v63, v63
	v_sub_f32_e32 v49, v49, v0
	v_exp_f32_e32 v49, v49
	v_sub_f32_e32 v48, v48, v0
	v_exp_f32_e32 v48, v48
	v_add_f32_e32 v38, 0, v38
	v_add_f32_e32 v38, v63, v38
	v_sub_f32_e32 v51, v51, v0
	v_add_f32_e32 v38, v49, v38
	v_exp_f32_e32 v51, v51
	v_add_f32_e32 v38, v48, v38
	v_sub_f32_e32 v48, v50, v0
	v_exp_f32_e32 v48, v48
	v_sub_f32_e32 v45, v45, v0
	v_exp_f32_e32 v45, v45
	v_sub_f32_e32 v44, v44, v0
	v_exp_f32_e32 v44, v44
	v_add_f32_e32 v38, v51, v38
	v_add_f32_e32 v38, v48, v38
	v_sub_f32_e32 v47, v47, v0
	v_add_f32_e32 v38, v45, v38
	v_exp_f32_e32 v47, v47
	v_add_f32_e32 v38, v44, v38
	v_sub_f32_e32 v44, v46, v0
	v_exp_f32_e32 v44, v44
	v_sub_f32_e32 v41, v41, v0
	v_exp_f32_e32 v41, v41
	v_sub_f32_e32 v40, v40, v0
	v_exp_f32_e32 v40, v40
	v_add_f32_e32 v38, v47, v38
	v_add_f32_e32 v38, v44, v38
	v_sub_f32_e32 v43, v43, v0
	v_add_f32_e32 v38, v41, v38
	v_exp_f32_e32 v43, v43
	v_add_f32_e32 v38, v40, v38
	v_sub_f32_e32 v40, v42, v0
	v_exp_f32_e32 v40, v40
	v_sub_f32_e32 v37, v37, v0
	v_exp_f32_e32 v37, v37
	v_sub_f32_e32 v36, v36, v0
	v_sub_f32_e32 v39, v148, v0
	v_exp_f32_e32 v36, v36
	v_add_f32_e32 v38, v43, v38
	v_exp_f32_e32 v39, v39
	v_add_f32_e32 v38, v40, v38
	v_add_f32_e32 v37, v37, v38
	v_add_f32_e32 v63, v36, v37
	v_fmac_f32_e32 v63, v61, v39
.LBB0_745:
	s_andn2_saveexec_b64 s[36:37], s[54:55]
	s_cbranch_execz .LBB0_747
	v_max_f32_e32 v0, v48, v49
	v_max3_f32 v63, v51, v44, v45
	v_max3_f32 v79, v41, v42, v43
	v_max3_f32 v80, v36, v37, v38
	v_max3_f32 v78, v46, v47, v40
	v_max3_f32 v0, v0, v50, v63
	v_max3_f32 v63, v79, v80, v39
	v_max3_f32 v0, v0, v78, v63
	v_mov_b32_e32 v63, v0
	s_nop 1
	v_permlane16_swap_b32_e32 v0, v63
	v_max_f32_e32 v0, v0, v63
	v_mov_b32_e32 v63, v0
	s_nop 1
	v_permlane32_swap_b32_e32 v0, v63
	v_max_f32_e32 v0, v0, v63
	v_fmamk_f32 v0, v0, 0x3e38aa3b, v65
	v_max_f32_e32 v63, v148, v148
	v_max_f32_e32 v0, v63, v0
	v_sub_f32_e32 v63, v65, v0
	v_fmamk_f32 v48, v48, 0x3e38aa3b, v63
	v_fmamk_f32 v49, v49, 0x3e38aa3b, v63
	v_exp_f32_e32 v48, v48
	v_fmamk_f32 v50, v50, 0x3e38aa3b, v63
	v_fmamk_f32 v44, v44, 0x3e38aa3b, v63
	v_exp_f32_e32 v49, v49
	v_exp_f32_e32 v50, v50
	v_fmamk_f32 v51, v51, 0x3e38aa3b, v63
	v_fmamk_f32 v45, v45, 0x3e38aa3b, v63
	v_exp_f32_e32 v44, v44
	v_fmamk_f32 v46, v46, 0x3e38aa3b, v63
	v_add_f32_e32 v48, 0, v48
	v_exp_f32_e32 v51, v51
	v_fmamk_f32 v40, v40, 0x3e38aa3b, v63
	v_exp_f32_e32 v45, v45
	v_exp_f32_e32 v46, v46
	v_fmamk_f32 v47, v47, 0x3e38aa3b, v63
	v_add_f32_e32 v49, 0, v49
	v_add_f32_e32 v48, v48, v50
	v_exp_f32_e32 v40, v40
	v_fmamk_f32 v41, v41, 0x3e38aa3b, v63
	v_fmamk_f32 v42, v42, 0x3e38aa3b, v63
	v_exp_f32_e32 v47, v47
	v_add_f32_e32 v44, v48, v44
	v_fmamk_f32 v36, v36, 0x3e38aa3b, v63
	v_add_f32_e32 v49, v49, v51
	v_exp_f32_e32 v41, v41
	v_exp_f32_e32 v42, v42
	v_fmamk_f32 v43, v43, 0x3e38aa3b, v63
	v_add_f32_e32 v44, v44, v46
	v_add_f32_e32 v45, v49, v45
	v_exp_f32_e32 v36, v36
	v_fmamk_f32 v37, v37, 0x3e38aa3b, v63
	v_fmamk_f32 v38, v38, 0x3e38aa3b, v63
	v_exp_f32_e32 v43, v43
	v_add_f32_e32 v40, v44, v40
	v_add_f32_e32 v45, v45, v47
	v_exp_f32_e32 v37, v37
	v_exp_f32_e32 v38, v38
	v_add_f32_e32 v40, v40, v42
	v_add_f32_e32 v41, v45, v41
	v_fmac_f32_e32 v63, 0x3e38aa3b, v39
	v_sub_f32_e32 v78, v148, v0
	v_add_f32_e32 v36, v40, v36
	v_exp_f32_e32 v39, v63
	v_add_f32_e32 v41, v41, v43
	s_nop 0
	v_add_f32_e32 v37, v41, v37
	v_add_f32_e32 v36, v36, v38
	v_exp_f32_e32 v38, v78
	s_nop 0
	v_add_f32_e32 v37, v37, v39
	s_nop 0
	v_add_f32_e32 v63, v36, v37
	v_fmac_f32_e32 v63, v61, v38

; DEVI float opq(float x) { asm("" : "+v"(x)); return x; }
; DEVI float fexp2(float x) { return __builtin_amdgcn_exp2f(x); }
; template <int DK, int MODE, int RBM, class SF, class FF, class POST>
; DEVI void attn_tile_body(const bf16x8 (&qf)[2][DK / 32], const char* Ks, const char* Vs, SF& sf, FF& ff, POST& post,
;                          int cur, int c0, int c1, float (&m)[2], float (&l)[2], f32x4 (&o)[5][2], int fr, int fq) {
;     ...
;       } else {
;         float mx = max16(s[0][rb], s[1][rb], s[2][rb], s[3][rb]);
;         mx = xmax16(mx); mx = xmax32(mx);
;         const float cand = FF::HASVEC ? (mx + cl) : fmaf(mx, fsc, cl);
;         const float mn = fmaxf(m[rb], cand);
;         const float alpha = fexp2(m[rb] - mn);
;         m[rb] = mn;
;         const float c = cl - mn;
;         float rs0 = 0.f, rs1 = 0.f;
; #pragma unroll
;         for (int kb = 0; kb < 4; ++kb)
; #pragma unroll
;           for (int j = 0; j < 4; ++j) {
;             const float e = FF::HASVEC ? opq(s[kb][rb][j] + c) : opq(fmaf(s[kb][rb][j], fsc, c));
;             const float pv = fexp2(e);
;             s[kb][rb][j] = pv;
;             if (j & 1) rs1 = opq(rs1 + pv); else rs0 = opq(rs0 + pv);
;           }
;         l[rb] = fmaf(l[rb], alpha, rs0 + rs1);
;       }
.LBB0_781:
	s_andn2_saveexec_b64 s[36:37], s[54:55]
	s_cbranch_execz .LBB0_628
	v_max_f32_e32 v36, v32, v33
	v_max3_f32 v37, v35, v28, v29
	v_max3_f32 v39, v25, v26, v27
	v_max3_f32 v40, v20, v21, v22
	v_max3_f32 v38, v30, v31, v24
	v_max3_f32 v36, v36, v34, v37
	v_max3_f32 v37, v39, v40, v23
	v_max3_f32 v36, v36, v38, v37
	v_mov_b32_e32 v37, v36
	s_nop 1
	v_permlane16_swap_b32_e32 v36, v37
	v_max_f32_e32 v36, v36, v37
	v_mov_b32_e32 v37, v36
	s_nop 1
	v_permlane32_swap_b32_e32 v36, v37
	v_max_f32_e32 v36, v36, v37
	v_fmamk_f32 v36, v36, 0x3e38aa3b, v65
	v_max_f32_e32 v37, v146, v146
	v_max_f32_e32 v38, v37, v36
	v_sub_f32_e32 v36, v65, v38
	v_fmamk_f32 v32, v32, 0x3e38aa3b, v36
	v_fmamk_f32 v33, v33, 0x3e38aa3b, v36
	v_exp_f32_e32 v32, v32
	v_fmamk_f32 v34, v34, 0x3e38aa3b, v36
	v_fmamk_f32 v28, v28, 0x3e38aa3b, v36
	v_exp_f32_e32 v33, v33
	v_exp_f32_e32 v34, v34
	v_fmamk_f32 v35, v35, 0x3e38aa3b, v36
	v_fmamk_f32 v29, v29, 0x3e38aa3b, v36
	v_exp_f32_e32 v28, v28
	v_fmamk_f32 v30, v30, 0x3e38aa3b, v36
	v_add_f32_e32 v32, 0, v32
	v_exp_f32_e32 v35, v35
	v_fmamk_f32 v24, v24, 0x3e38aa3b, v36
	v_exp_f32_e32 v29, v29
	v_exp_f32_e32 v30, v30
	v_fmamk_f32 v31, v31, 0x3e38aa3b, v36
	v_add_f32_e32 v33, 0, v33
	v_add_f32_e32 v32, v32, v34
	v_exp_f32_e32 v24, v24
	v_fmamk_f32 v25, v25, 0x3e38aa3b, v36
	v_fmamk_f32 v26, v26, 0x3e38aa3b, v36
	v_exp_f32_e32 v31, v31
	v_add_f32_e32 v28, v32, v28
	v_fmamk_f32 v20, v20, 0x3e38aa3b, v36
	v_add_f32_e32 v33, v33, v35
	v_exp_f32_e32 v25, v25
	v_exp_f32_e32 v26, v26
	v_fmamk_f32 v27, v27, 0x3e38aa3b, v36
	v_add_f32_e32 v28, v28, v30
	v_add_f32_e32 v29, v33, v29
	v_exp_f32_e32 v20, v20
	v_fmamk_f32 v21, v21, 0x3e38aa3b, v36
	v_fmamk_f32 v22, v22, 0x3e38aa3b, v36
	v_exp_f32_e32 v27, v27
	v_add_f32_e32 v24, v28, v24
	v_add_f32_e32 v29, v29, v31
	v_exp_f32_e32 v21, v21
	v_exp_f32_e32 v22, v22
	v_add_f32_e32 v24, v24, v26
	v_add_f32_e32 v25, v29, v25
	v_fmac_f32_e32 v36, 0x3e38aa3b, v23
	v_sub_f32_e32 v37, v146, v38
	v_add_f32_e32 v20, v24, v20
	v_exp_f32_e32 v23, v36
	v_add_f32_e32 v25, v25, v27
	s_nop 0
	v_add_f32_e32 v21, v25, v21
	v_add_f32_e32 v20, v20, v22
	v_exp_f32_e32 v22, v37
	s_nop 0
	v_add_f32_e32 v21, v21, v23
	s_nop 0
	v_add_f32_e32 v62, v20, v21
	v_fmac_f32_e32 v62, v60, v22
	s_branch .LBB0_628

; template <int DK, int MODE, int RBM, class SF, class FF, class POST>
; DEVI void attn_tile_body(const bf16x8 (&qf)[2][DK / 32], const char* Ks, const char* Vs, SF& sf, FF& ff, POST& post,
;                          int cur, int c0, int c1, float (&m)[2], float (&l)[2], f32x4 (&o)[5][2], int fr, int fq) {
;     ...
;     bf16x8 pf[2][2];
; #pragma unroll
;     for (int rb = 0; rb < 2; ++rb) {
;       if (!(RBM & (1 << rb))) continue;
; #pragma unroll
;       for (int kp2 = 0; kp2 < 2; ++kp2) {
;         u32x4 w;
;         w[0] = pack2(s[2 * kp2][rb][0], s[2 * kp2][rb][1]); w[1] = pack2(s[2 * kp2][rb][2], s[2 * kp2][rb][3]);
;         w[2] = pack2(s[2 * kp2 + 1][rb][0], s[2 * kp2 + 1][rb][1]); w[3] = pack2(s[2 * kp2 + 1][rb][2], s[2 * kp2 + 1][rb][3]);
;         pf[rb][kp2] = __builtin_bit_cast(bf16x8, w);
;       }
;     }
; #pragma unroll
;     for (int kp2 = 0; kp2 < 2; ++kp2)
; #pragma unroll
;       for (int db = 0; db < 4; ++db) {
;         const char* base = Vs + (db * 16 + fr) * 128 + (fq & 1) * 8;
;         const int c = kp2 * 4 + (fq >> 1);
;         u32x2 lo = *(const u32x2*)(base + ((c ^ (fr & 7)) * 16));
;         u32x2 hi = *(const u32x2*)(base + (((c + 2) ^ (fr & 7)) * 16));
;         u32x4 w; w[0] = lo[0]; w[1] = lo[1]; w[2] = hi[0]; w[3] = hi[1];
;         bf16x8 vf = __builtin_bit_cast(bf16x8, w);
;         if (RBM & 1) o[db][0] = __builtin_amdgcn_mfma_f32_16x16x32_bf16(vf, pf[0][kp2], o[db][0], 0, 0, 0);
;         if (RBM & 2) o[db][1] = __builtin_amdgcn_mfma_f32_16x16x32_bf16(vf, pf[1][kp2], o[db][1], 0, 0, 0);
;       }
.LBB0_786:
	s_or_b64 exec, exec, s[6:7]
	v_add3_u32 v0, s82, v194, v191
	v_cvt_pk_bf16_f32 v52, v2, v3
	v_add_u32_e32 v2, v0, v195
	v_add_u32_e32 v3, v0, v196
	v_add_u32_e32 v2, 0x100, v2
	v_add_u32_e32 v3, 0x100, v3
	v_cvt_pk_bf16_f32 v60, v68, v69
	v_cvt_pk_bf16_f32 v61, v70, v71
	v_cvt_pk_bf16_f32 v62, v72, v73
	v_cvt_pk_bf16_f32 v63, v74, v75
	ds_read_b64 v[232:233], v2 offset:24576
	ds_read_b64 v[236:237], v2 offset:26624
	ds_read_b64 v[234:235], v3 offset:24576
	ds_read_b64 v[238:239], v3 offset:26624
	v_cvt_pk_bf16_f32 v65, v78, v79
	v_cvt_pk_bf16_f32 v53, v100, v101
	v_cvt_pk_bf16_f32 v54, v118, v119
	v_cvt_pk_bf16_f32 v55, v120, v121
	s_waitcnt lgkmcnt(0)
	v_cvt_pk_bf16_f32 v64, v76, v77
	v_mfma_f32_16x16x32_bf16 v[44:47], v[236:239], v[52:55], v[44:47]
	v_cvt_pk_bf16_f32 v56, v126, v127
	v_cvt_pk_bf16_f32 v57, v128, v129
	v_cvt_pk_bf16_f32 v58, v130, v131
	v_mfma_f32_16x16x32_bf16 v[28:31], v[236:239], v[60:63], v[28:31]
	ds_read_b64 v[240:241], v2 offset:28672
	ds_read_b64 v[244:245], v2 offset:30720
	ds_read_b64 v[242:243], v3 offset:28672
	ds_read_b64 v[246:247], v3 offset:30720
	v_add_u32_e32 v2, v0, v197
	v_add_u32_e32 v0, v0, v198
	v_mfma_f32_16x16x32_bf16 v[48:51], v[232:235], v[52:55], v[48:51]
	v_add_u32_e32 v2, 0x100, v2
	v_add_u32_e32 v0, 0x100, v0
	v_cvt_pk_bf16_f32 v59, v132, v133
	v_mfma_f32_16x16x32_bf16 v[32:35], v[232:235], v[60:63], v[32:35]
	s_waitcnt lgkmcnt(0)
	v_mfma_f32_16x16x32_bf16 v[40:43], v[240:243], v[52:55], v[40:43]
	v_cvt_pk_bf16_f32 v66, v80, v81
	v_cvt_pk_bf16_f32 v67, v82, v83
	v_mfma_f32_16x16x32_bf16 v[24:27], v[240:243], v[60:63], v[24:27]
	v_mfma_f32_16x16x32_bf16 v[36:39], v[244:247], v[52:55], v[36:39]
	ds_read_b64 v[232:233], v2 offset:24576
	ds_read_b64 v[236:237], v2 offset:26624
	s_waitcnt lgkmcnt(0)
	v_mfma_f32_16x16x32_bf16 v[20:23], v[244:247], v[60:63], v[20:23]
	ds_read_b64 v[234:235], v0 offset:24576
	ds_read_b64 v[238:239], v0 offset:26624
	s_waitcnt lgkmcnt(0)
	v_mfma_f32_16x16x32_bf16 v[48:51], v[232:235], v[56:59], v[48:51]
	s_nop 0
	v_mfma_f32_16x16x32_bf16 v[44:47], v[236:239], v[56:59], v[44:47]
	v_mfma_f32_16x16x32_bf16 v[28:31], v[236:239], v[64:67], v[28:31]
	ds_read_b64 v[240:241], v2 offset:28672
	ds_read_b64 v[244:245], v2 offset:30720
	ds_read_b64 v[242:243], v0 offset:28672
	ds_read_b64 v[246:247], v0 offset:30720
	v_mfma_f32_16x16x32_bf16 v[32:35], v[232:235], v[64:67], v[32:35]
	s_waitcnt lgkmcnt(0)
	v_mfma_f32_16x16x32_bf16 v[40:43], v[240:243], v[56:59], v[40:43]
	v_mfma_f32_16x16x32_bf16 v[24:27], v[240:243], v[64:67], v[24:27]
	v_mfma_f32_16x16x32_bf16 v[36:39], v[244:247], v[56:59], v[36:39]
	v_mfma_f32_16x16x32_bf16 v[20:23], v[244:247], v[64:67], v[20:23]

; template <int DK, int MODE, int RBM, class SF, class FF, class POST>
; DEVI void attn_tile_body(const bf16x8 (&qf)[2][DK / 32], const char* Ks, const char* Vs, SF& sf, FF& ff, POST& post,
;                          int cur, int c0, int c1, float (&m)[2], float (&l)[2], f32x4 (&o)[5][2], int fr, int fq) {
;     ...
;     bf16x8 pf[2][2];
; #pragma unroll
;     for (int rb = 0; rb < 2; ++rb) {
;       if (!(RBM & (1 << rb))) continue;
; #pragma unroll
;       for (int kp2 = 0; kp2 < 2; ++kp2) {
;         u32x4 w;
;         w[0] = pack2(s[2 * kp2][rb][0], s[2 * kp2][rb][1]); w[1] = pack2(s[2 * kp2][rb][2], s[2 * kp2][rb][3]);
;         w[2] = pack2(s[2 * kp2 + 1][rb][0], s[2 * kp2 + 1][rb][1]); w[3] = pack2(s[2 * kp2 + 1][rb][2], s[2 * kp2 + 1][rb][3]);
;         pf[rb][kp2] = __builtin_bit_cast(bf16x8, w);
;       }
;     }
; #pragma unroll
;     for (int kp2 = 0; kp2 < 2; ++kp2)
; #pragma unroll
;       for (int db = 0; db < 4; ++db) {
;         const char* base = Vs + (db * 16 + fr) * 128 + (fq & 1) * 8;
;         const int c = kp2 * 4 + (fq >> 1);
;         u32x2 lo = *(const u32x2*)(base + ((c ^ (fr & 7)) * 16));
;         u32x2 hi = *(const u32x2*)(base + (((c + 2) ^ (fr & 7)) * 16));
;         u32x4 w; w[0] = lo[0]; w[1] = lo[1]; w[2] = hi[0]; w[3] = hi[1];
;         bf16x8 vf = __builtin_bit_cast(bf16x8, w);
;         if (RBM & 1) o[db][0] = __builtin_amdgcn_mfma_f32_16x16x32_bf16(vf, pf[0][kp2], o[db][0], 0, 0, 0);
;         if (RBM & 2) o[db][1] = __builtin_amdgcn_mfma_f32_16x16x32_bf16(vf, pf[1][kp2], o[db][1], 0, 0, 0);
;       }
.LBB0_891:
	s_or_b64 exec, exec, s[6:7]
	v_add3_u32 v0, s82, v194, v191
	v_cvt_pk_bf16_f32 v52, v2, v3
	v_add_u32_e32 v2, v0, v195
	v_add_u32_e32 v3, v0, v196
	v_cvt_pk_bf16_f32 v60, v68, v69
	v_cvt_pk_bf16_f32 v61, v70, v71
	v_cvt_pk_bf16_f32 v62, v72, v73
	v_cvt_pk_bf16_f32 v63, v74, v75
	ds_read_b64 v[232:233], v2 offset:8192
	ds_read_b64 v[236:237], v2 offset:10240
	ds_read_b64 v[234:235], v3 offset:8192
	ds_read_b64 v[238:239], v3 offset:10240
	v_cvt_pk_bf16_f32 v65, v78, v79
	v_cvt_pk_bf16_f32 v53, v118, v119
	v_cvt_pk_bf16_f32 v54, v120, v121
	v_cvt_pk_bf16_f32 v55, v126, v127
	s_waitcnt lgkmcnt(0)
	v_cvt_pk_bf16_f32 v64, v76, v77
	v_mfma_f32_16x16x32_bf16 v[44:47], v[236:239], v[52:55], v[44:47]
	v_cvt_pk_bf16_f32 v56, v128, v129
	v_cvt_pk_bf16_f32 v57, v130, v131
	v_cvt_pk_bf16_f32 v58, v132, v133
	v_mfma_f32_16x16x32_bf16 v[28:31], v[236:239], v[60:63], v[28:31]
	ds_read_b64 v[240:241], v2 offset:12288
	ds_read_b64 v[244:245], v2 offset:14336
	ds_read_b64 v[242:243], v3 offset:12288
	ds_read_b64 v[246:247], v3 offset:14336
	v_add_u32_e32 v2, v0, v197
	v_add_u32_e32 v0, v0, v198
	v_mfma_f32_16x16x32_bf16 v[48:51], v[232:235], v[52:55], v[48:51]
	v_cvt_pk_bf16_f32 v59, v134, v135
	v_cvt_pk_bf16_f32 v66, v80, v81
	v_cvt_pk_bf16_f32 v67, v82, v83
	v_mfma_f32_16x16x32_bf16 v[32:35], v[232:235], v[60:63], v[32:35]
	s_waitcnt lgkmcnt(0)
	v_mfma_f32_16x16x32_bf16 v[40:43], v[240:243], v[52:55], v[40:43]
	v_mfma_f32_16x16x32_bf16 v[24:27], v[240:243], v[60:63], v[24:27]
	v_mfma_f32_16x16x32_bf16 v[36:39], v[244:247], v[52:55], v[36:39]
	ds_read_b64 v[232:233], v2 offset:8192
	ds_read_b64 v[236:237], v2 offset:10240
	s_waitcnt lgkmcnt(0)
	v_mfma_f32_16x16x32_bf16 v[20:23], v[244:247], v[60:63], v[20:23]
	ds_read_b64 v[234:235], v0 offset:8192
	ds_read_b64 v[238:239], v0 offset:10240
	s_waitcnt lgkmcnt(0)
	v_mfma_f32_16x16x32_bf16 v[48:51], v[232:235], v[56:59], v[48:51]
	s_nop 0
	v_mfma_f32_16x16x32_bf16 v[44:47], v[236:239], v[56:59], v[44:47]
	v_mfma_f32_16x16x32_bf16 v[28:31], v[236:239], v[64:67], v[28:31]
	ds_read_b64 v[240:241], v2 offset:12288
	ds_read_b64 v[244:245], v2 offset:14336
	ds_read_b64 v[242:243], v0 offset:12288
	ds_read_b64 v[246:247], v0 offset:14336
	v_mfma_f32_16x16x32_bf16 v[32:35], v[232:235], v[64:67], v[32:35]
	s_waitcnt lgkmcnt(0)
	v_mfma_f32_16x16x32_bf16 v[40:43], v[240:243], v[56:59], v[40:43]
	v_mfma_f32_16x16x32_bf16 v[24:27], v[240:243], v[64:67], v[24:27]
	v_mfma_f32_16x16x32_bf16 v[36:39], v[244:247], v[56:59], v[36:39]
	v_mfma_f32_16x16x32_bf16 v[20:23], v[244:247], v[64:67], v[20:23]

; DEVI float opq(float x) { asm("" : "+v"(x)); return x; }
; DEVI float fexp2(float x) { return __builtin_amdgcn_exp2f(x); }
; template <int DK, int MODE, int RBM, class SF, class FF, class POST>
; DEVI void attn_tile_body(const bf16x8 (&qf)[2][DK / 32], const char* Ks, const char* Vs, SF& sf, FF& ff, POST& post,
;                          int cur, int c0, int c1, float (&m)[2], float (&l)[2], f32x4 (&o)[5][2], int fr, int fq) {
;     ...
;       float mx = max16(s[0][rb], s[1][rb], s[2][rb], s[3][rb]);
;       mx = xmax16(mx); mx = xmax32(mx);
;       if (__builtin_amdgcn_ballot_w64(mx > m[rb] + DEFER_THR) != 0) {
;         const float mn = fmaxf(m[rb], mx);
;         const float alpha = fexp2(m[rb] - mn);
;         m[rb] = mn;
; #pragma unroll
;         for (int db = 0; db < 5; ++db)
; #pragma unroll
;           for (int j = 0; j < 4; ++j) o[db][rb][j] = opq(o[db][rb][j] * alpha);
;       }
.LBB0_1052:
	s_or_b64 exec, exec, s[6:7]
	v_max_f32_e32 v62, v127, v126
	v_max3_f32 v63, v72, v75, v74
	v_max3_f32 v214, v70, v65, v64
	v_max3_f32 v215, v67, v66, v61
	v_max3_f32 v213, v69, v68, v71
	v_max3_f32 v62, v62, v73, v63
	v_max3_f32 v63, v214, v215, v60
	v_max3_f32 v62, v62, v213, v63
	v_mov_b32_e32 v63, v62
	s_nop 1
	v_permlane16_swap_b32_e32 v62, v63
	v_max_f32_e32 v62, v62, v63
	v_mov_b32_e32 v63, v62
	s_nop 1
	v_permlane32_swap_b32_e32 v62, v63
	v_max_f32_e32 v62, v62, v63
	v_add_f32_e32 v63, 0x41000000, v207
	v_cmp_gt_f32_e32 vcc, v62, v63
	s_cbranch_vccz .LBB0_1054
	v_max_f32_e32 v63, v207, v207
	v_max_f32_e32 v62, v63, v62
	v_sub_f32_e32 v63, v207, v62
	v_exp_f32_e32 v63, v63
	v_mov_b32_e32 v207, v62
	v_mul_f32_e32 v56, v56, v63
	v_mul_f32_e32 v57, v57, v63
	v_mul_f32_e32 v58, v58, v63
	v_mul_f32_e32 v59, v59, v63
	v_mul_f32_e32 v52, v52, v63
	v_mul_f32_e32 v53, v53, v63
	v_mul_f32_e32 v54, v54, v63
	v_mul_f32_e32 v55, v55, v63
	v_mul_f32_e32 v48, v48, v63
	v_mul_f32_e32 v49, v49, v63
	v_mul_f32_e32 v50, v50, v63
	v_mul_f32_e32 v51, v51, v63
	v_mul_f32_e32 v44, v44, v63
	v_mul_f32_e32 v45, v45, v63
	v_mul_f32_e32 v46, v46, v63
	v_mul_f32_e32 v47, v47, v63
	v_mul_f32_e32 v36, v36, v63
	v_mul_f32_e32 v37, v37, v63
	v_mul_f32_e32 v38, v38, v63
	v_mul_f32_e32 v39, v39, v63

; DEVI float opq(float x) { asm("" : "+v"(x)); return x; }
; DEVI float fexp2(float x) { return __builtin_amdgcn_exp2f(x); }
; template <int DK, int MODE, int RBM, class SF, class FF, class POST>
; DEVI void attn_tile_body(const bf16x8 (&qf)[2][DK / 32], const char* Ks, const char* Vs, SF& sf, FF& ff, POST& post,
;                          int cur, int c0, int c1, float (&m)[2], float (&l)[2], f32x4 (&o)[5][2], int fr, int fq) {
;     ...
;     if (cm == 2) {
;       const float cl = ff.cl(rb, cur);
;       const float fsc = ff.sc;
;       if (FF::HASVEC) {
; #pragma unroll
;         for (int kb = 0; kb < 4; ++kb) {
;           const f32x4 av = ff.vec(kb);
; #pragma unroll
;           for (int j = 0; j < 4; ++j) s[kb][rb][j] = opq(fmaf(s[kb][rb][j], fsc, av[j]));
;         }
;       }
;       if (MODE == 2) {
;         const float c = cl - m[rb];
; #pragma unroll
;         for (int kb = 0; kb < 4; ++kb)
; #pragma unroll
;           for (int j = 0; j < 4; ++j) {
;             const float e = FF::HASVEC ? opq(s[kb][rb][j] + c) : opq(fmaf(s[kb][rb][j], fsc, c));
;             s[kb][rb][j] = opq(fexp2(e) * l[rb]);
;           }
;       } else if (MODE == 0) {
;         float mx = max16(s[0][rb], s[1][rb], s[2][rb], s[3][rb]);
;         mx = xmax16(mx); mx = xmax32(mx);
;         const float cand = FF::HASVEC ? (mx + cl) : fmaf(mx, fsc, cl);
;         if (__builtin_amdgcn_ballot_w64(cand > m[rb] + DEFER_THR) != 0) {
;           const float mn = fmaxf(m[rb], cand);
;           const float alpha = fexp2(m[rb] - mn);
;           m[rb] = mn;
; #pragma unroll
;           for (int db = 0; db < 5; ++db)
; #pragma unroll
;             for (int j = 0; j < 4; ++j) o[db][rb][j] = opq(o[db][rb][j] * alpha);
;         }
.LBB0_1055:
	s_andn2_saveexec_b64 s[38:39], s[94:95]
	s_cbranch_execz .LBB0_1059
	v_cmp_ne_u64_e32 vcc, 0, v[126:127]
	v_max_f32_e32 v127, v72, v73
	v_max3_f32 v213, v75, v68, v69
	v_max3_f32 v215, v65, v66, v67
	v_max3_f32 v216, v60, v61, v62
	v_max3_f32 v214, v70, v71, v64
	v_max3_f32 v127, v127, v74, v213
	v_max3_f32 v213, v215, v216, v63
	v_max3_f32 v127, v127, v214, v213
	v_mov_b32_e32 v213, v127
	s_nop 1
	v_permlane16_swap_b32_e32 v127, v213
	v_max_f32_e32 v127, v127, v213
	v_mov_b32_e32 v213, v127
	s_nop 1
	v_permlane32_swap_b32_e32 v127, v213
	v_cndmask_b32_e32 v126, v181, v128, vcc
	v_max_f32_e32 v127, v127, v213
	v_fmamk_f32 v127, v127, 0x3e38aa3b, v126
	v_add_f32_e32 v213, 0x41000000, v207
	v_cmp_gt_f32_e32 vcc, v127, v213
	s_cbranch_vccz .LBB0_1058
	v_max_f32_e32 v213, v207, v207
	v_max_f32_e32 v127, v213, v127
	v_sub_f32_e32 v207, v207, v127
	v_exp_f32_e32 v207, v207
	s_nop 0
	v_mul_f32_e32 v56, v56, v207
	v_mul_f32_e32 v57, v57, v207
	v_mul_f32_e32 v58, v58, v207
	v_mul_f32_e32 v59, v59, v207
	v_mul_f32_e32 v52, v52, v207
	v_mul_f32_e32 v53, v53, v207
	v_mul_f32_e32 v54, v54, v207
	v_mul_f32_e32 v55, v55, v207
	v_mul_f32_e32 v48, v48, v207
	v_mul_f32_e32 v49, v49, v207
	v_mul_f32_e32 v50, v50, v207
	v_mul_f32_e32 v51, v51, v207
	v_mul_f32_e32 v44, v44, v207
	v_mul_f32_e32 v45, v45, v207
	v_mul_f32_e32 v46, v46, v207
	v_mul_f32_e32 v47, v47, v207
	v_mul_f32_e32 v36, v36, v207
	v_mul_f32_e32 v37, v37, v207
	v_mul_f32_e32 v38, v38, v207
	v_mul_f32_e32 v39, v39, v207
	v_mov_b32_e32 v207, v127

; DEVI float opq(float x) { asm("" : "+v"(x)); return x; }
; DEVI float fexp2(float x) { return __builtin_amdgcn_exp2f(x); }
; template <int DK, int MODE, int RBM, class SF, class FF, class POST>
; DEVI void attn_tile_body(const bf16x8 (&qf)[2][DK / 32], const char* Ks, const char* Vs, SF& sf, FF& ff, POST& post,
;                          int cur, int c0, int c1, float (&m)[2], float (&l)[2], f32x4 (&o)[5][2], int fr, int fq) {
;     ...
;       float mx = max16(s[0][rb], s[1][rb], s[2][rb], s[3][rb]);
;       mx = xmax16(mx); mx = xmax32(mx);
;       if (__builtin_amdgcn_ballot_w64(mx > m[rb] + DEFER_THR) != 0) {
;         const float mn = fmaxf(m[rb], mx);
;         const float alpha = fexp2(m[rb] - mn);
;         m[rb] = mn;
; #pragma unroll
;         for (int db = 0; db < 5; ++db)
; #pragma unroll
;           for (int j = 0; j < 4; ++j) o[db][rb][j] = opq(o[db][rb][j] * alpha);
;       }
.LBB0_1094:
	s_or_b64 exec, exec, s[6:7]
	v_max_f32_e32 v62, v3, v2
	v_max3_f32 v63, v72, v75, v74
	v_max3_f32 v127, v70, v65, v64
	v_max3_f32 v210, v67, v66, v61
	v_max3_f32 v126, v69, v68, v71
	v_max3_f32 v62, v62, v73, v63
	v_max3_f32 v63, v127, v210, v60
	v_max3_f32 v62, v62, v126, v63
	v_mov_b32_e32 v63, v62
	s_nop 1
	v_permlane16_swap_b32_e32 v62, v63
	v_max_f32_e32 v62, v62, v63
	v_mov_b32_e32 v63, v62
	s_nop 1
	v_permlane32_swap_b32_e32 v62, v63
	v_max_f32_e32 v62, v62, v63
	v_add_f32_e32 v63, 0x41000000, v208
	v_cmp_gt_f32_e32 vcc, v62, v63
	s_cbranch_vccz .LBB0_1096
	v_max_f32_e32 v63, v208, v208
	v_max_f32_e32 v62, v63, v62
	v_sub_f32_e32 v63, v208, v62
	v_exp_f32_e32 v63, v63
	v_mov_b32_e32 v208, v62
	v_mul_f32_e32 v40, v40, v63
	v_mul_f32_e32 v41, v41, v63
	v_mul_f32_e32 v42, v42, v63
	v_mul_f32_e32 v43, v43, v63
	v_mul_f32_e32 v32, v32, v63
	v_mul_f32_e32 v33, v33, v63
	v_mul_f32_e32 v34, v34, v63
	v_mul_f32_e32 v35, v35, v63
	v_mul_f32_e32 v28, v28, v63
	v_mul_f32_e32 v29, v29, v63
	v_mul_f32_e32 v30, v30, v63
	v_mul_f32_e32 v31, v31, v63
	v_mul_f32_e32 v24, v24, v63
	v_mul_f32_e32 v25, v25, v63
	v_mul_f32_e32 v26, v26, v63
	v_mul_f32_e32 v27, v27, v63
	v_mul_f32_e32 v20, v20, v63
	v_mul_f32_e32 v21, v21, v63
	v_mul_f32_e32 v22, v22, v63
	v_mul_f32_e32 v23, v23, v63

; DEVI float opq(float x) { asm("" : "+v"(x)); return x; }
; DEVI float fexp2(float x) { return __builtin_amdgcn_exp2f(x); }
; DEVI float xmax16(float x) {
;   u32x2 r = __builtin_amdgcn_permlane16_swap(__float_as_uint(x), __float_as_uint(x), false, false);
;   return fmaxf(__uint_as_float(r[0]), __uint_as_float(r[1]));
; }
; DEVI float xmax32(float x) {
;   u32x2 r = __builtin_amdgcn_permlane32_swap(__float_as_uint(x), __float_as_uint(x), false, false);
;   return fmaxf(__uint_as_float(r[0]), __uint_as_float(r[1]));
; }
; template <int DK, int MODE, int RBM, class SF, class FF, class POST>
; DEVI void attn_tile_body(const bf16x8 (&qf)[2][DK / 32], const char* Ks, const char* Vs, SF& sf, FF& ff, POST& post,
;                          int cur, int c0, int c1, float (&m)[2], float (&l)[2], f32x4 (&o)[5][2], int fr, int fq) {
;     ...
;       const float cl = ff.cl(rb, cur);
;       const float fsc = ff.sc;
;       if (FF::HASVEC) {
; #pragma unroll
;         for (int kb = 0; kb < 4; ++kb) {
;           const f32x4 av = ff.vec(kb);
; #pragma unroll
;           for (int j = 0; j < 4; ++j) s[kb][rb][j] = opq(fmaf(s[kb][rb][j], fsc, av[j]));
;         }
;       }
;       if (MODE == 2) {
;         const float c = cl - m[rb];
; #pragma unroll
;         for (int kb = 0; kb < 4; ++kb)
; #pragma unroll
;           for (int j = 0; j < 4; ++j) {
;             const float e = FF::HASVEC ? opq(s[kb][rb][j] + c) : opq(fmaf(s[kb][rb][j], fsc, c));
;             s[kb][rb][j] = opq(fexp2(e) * l[rb]);
;           }
;       } else if (MODE == 0) {
;         float mx = max16(s[0][rb], s[1][rb], s[2][rb], s[3][rb]);
;         mx = xmax16(mx); mx = xmax32(mx);
;         const float cand = FF::HASVEC ? (mx + cl) : fmaf(mx, fsc, cl);
;         if (__builtin_amdgcn_ballot_w64(cand > m[rb] + DEFER_THR) != 0) {
;           const float mn = fmaxf(m[rb], cand);
;           const float alpha = fexp2(m[rb] - mn);
;           m[rb] = mn;
; #pragma unroll
;           for (int db = 0; db < 5; ++db)
; #pragma unroll
;             for (int j = 0; j < 4; ++j) o[db][rb][j] = opq(o[db][rb][j] * alpha);
;         }
.LBB0_1097:
	s_andn2_saveexec_b64 s[38:39], s[94:95]
	s_cbranch_execz .LBB0_1101
	v_cmp_ne_u64_e32 vcc, 0, v[2:3]
	v_max_f32_e32 v3, v72, v73
	v_max3_f32 v126, v75, v68, v69
	v_max3_f32 v210, v65, v66, v67
	v_max3_f32 v211, v60, v61, v62
	v_max3_f32 v127, v70, v71, v64
	v_max3_f32 v3, v3, v74, v126
	v_max3_f32 v126, v210, v211, v63
	v_max3_f32 v3, v3, v127, v126
	v_mov_b32_e32 v126, v3
	s_nop 1
	v_permlane16_swap_b32_e32 v3, v126
	v_max_f32_e32 v3, v3, v126
	v_mov_b32_e32 v126, v3
	s_nop 1
	v_permlane32_swap_b32_e32 v3, v126
	v_cndmask_b32_e32 v2, v181, v128, vcc
	v_max_f32_e32 v3, v3, v126
	v_fmamk_f32 v3, v3, 0x3e38aa3b, v2
	v_add_f32_e32 v126, 0x41000000, v208
	v_cmp_gt_f32_e32 vcc, v3, v126
	s_cbranch_vccz .LBB0_1100
	v_max_f32_e32 v126, v208, v208
	v_max_f32_e32 v3, v126, v3
	v_sub_f32_e32 v126, v208, v3
	v_exp_f32_e32 v126, v126
	v_mov_b32_e32 v208, v3
	v_mul_f32_e32 v40, v40, v126
	v_mul_f32_e32 v41, v41, v126
	v_mul_f32_e32 v42, v42, v126
	v_mul_f32_e32 v43, v43, v126
	v_mul_f32_e32 v32, v32, v126
	v_mul_f32_e32 v33, v33, v126
	v_mul_f32_e32 v34, v34, v126
	v_mul_f32_e32 v35, v35, v126
	v_mul_f32_e32 v28, v28, v126
	v_mul_f32_e32 v29, v29, v126
	v_mul_f32_e32 v30, v30, v126
	v_mul_f32_e32 v31, v31, v126
	v_mul_f32_e32 v24, v24, v126
	v_mul_f32_e32 v25, v25, v126
	v_mul_f32_e32 v26, v26, v126
	v_mul_f32_e32 v27, v27, v126
	v_mul_f32_e32 v20, v20, v126
	v_mul_f32_e32 v21, v21, v126
	v_mul_f32_e32 v22, v22, v126
	v_mul_f32_e32 v23, v23, v126

; DEVI float opq(float x) { asm("" : "+v"(x)); return x; }
; DEVI float fexp2(float x) { return __builtin_amdgcn_exp2f(x); }
; DEVI float xmax16(float x) {
;   u32x2 r = __builtin_amdgcn_permlane16_swap(__float_as_uint(x), __float_as_uint(x), false, false);
;   return fmaxf(__uint_as_float(r[0]), __uint_as_float(r[1]));
; }
; DEVI float xmax32(float x) {
;   u32x2 r = __builtin_amdgcn_permlane32_swap(__float_as_uint(x), __float_as_uint(x), false, false);
;   return fmaxf(__uint_as_float(r[0]), __uint_as_float(r[1]));
; }
; template <int DK, int MODE, int RBM, class SF, class FF, class POST>
; DEVI void attn_tile_body(const bf16x8 (&qf)[2][DK / 32], const char* Ks, const char* Vs, SF& sf, FF& ff, POST& post,
;                          int cur, int c0, int c1, float (&m)[2], float (&l)[2], f32x4 (&o)[5][2], int fr, int fq) {
;     ...
;     } else if (MODE == 0) {
;       float mx = max16(s[0][rb], s[1][rb], s[2][rb], s[3][rb]);
;       mx = xmax16(mx); mx = xmax32(mx);
;       if (__builtin_amdgcn_ballot_w64(mx > m[rb] + DEFER_THR) != 0) {
;         const float mn = fmaxf(m[rb], mx);
;         const float alpha = fexp2(m[rb] - mn);
;         m[rb] = mn;
; #pragma unroll
;         for (int db = 0; db < 5; ++db)
; #pragma unroll
;           for (int j = 0; j < 4; ++j) o[db][rb][j] = opq(o[db][rb][j] * alpha);
;       }
.LBB0_1138:
	s_or_b64 exec, exec, s[6:7]
	v_max_f32_e32 v62, v127, v126
	v_max3_f32 v63, v72, v75, v74
	v_max3_f32 v212, v70, v65, v64
	v_max3_f32 v213, v67, v66, v61
	v_max3_f32 v211, v69, v68, v71
	v_max3_f32 v62, v62, v73, v63
	v_max3_f32 v63, v212, v213, v60
	v_max3_f32 v62, v62, v211, v63
	v_mov_b32_e32 v63, v62
	s_nop 1
	v_permlane16_swap_b32_e32 v62, v63
	v_max_f32_e32 v62, v62, v63
	v_mov_b32_e32 v63, v62
	s_nop 1
	v_permlane32_swap_b32_e32 v62, v63
	v_max_f32_e32 v62, v62, v63
	v_add_f32_e32 v63, 0x41000000, v207
	v_cmp_gt_f32_e32 vcc, v62, v63
	s_cbranch_vccz .LBB0_1140
	v_max_f32_e32 v63, v207, v207
	v_max_f32_e32 v62, v63, v62
	v_sub_f32_e32 v63, v207, v62
	v_exp_f32_e32 v63, v63
	v_mov_b32_e32 v207, v62
	v_mul_f32_e32 v56, v56, v63
	v_mul_f32_e32 v57, v57, v63
	v_mul_f32_e32 v58, v58, v63
	v_mul_f32_e32 v59, v59, v63
	v_mul_f32_e32 v52, v52, v63
	v_mul_f32_e32 v53, v53, v63
	v_mul_f32_e32 v54, v54, v63
	v_mul_f32_e32 v55, v55, v63
	v_mul_f32_e32 v48, v48, v63
	v_mul_f32_e32 v49, v49, v63
	v_mul_f32_e32 v50, v50, v63
	v_mul_f32_e32 v51, v51, v63
	v_mul_f32_e32 v44, v44, v63
	v_mul_f32_e32 v45, v45, v63
	v_mul_f32_e32 v46, v46, v63
	v_mul_f32_e32 v47, v47, v63
	v_mul_f32_e32 v36, v36, v63
	v_mul_f32_e32 v37, v37, v63
	v_mul_f32_e32 v38, v38, v63
	v_mul_f32_e32 v39, v39, v63

; DEVI float opq(float x) { asm("" : "+v"(x)); return x; }
; DEVI float fexp2(float x) { return __builtin_amdgcn_exp2f(x); }
; DEVI float xmax16(float x) {
;   u32x2 r = __builtin_amdgcn_permlane16_swap(__float_as_uint(x), __float_as_uint(x), false, false);
;   return fmaxf(__uint_as_float(r[0]), __uint_as_float(r[1]));
; }
; DEVI float xmax32(float x) {
;   u32x2 r = __builtin_amdgcn_permlane32_swap(__float_as_uint(x), __float_as_uint(x), false, false);
;   return fmaxf(__uint_as_float(r[0]), __uint_as_float(r[1]));
; }
; template <int DK, int MODE, int RBM, class SF, class FF, class POST>
; DEVI void attn_tile_body(const bf16x8 (&qf)[2][DK / 32], const char* Ks, const char* Vs, SF& sf, FF& ff, POST& post,
;                          int cur, int c0, int c1, float (&m)[2], float (&l)[2], f32x4 (&o)[5][2], int fr, int fq) {
;     ...
;       const float cl = ff.cl(rb, cur);
;       const float fsc = ff.sc;
;       if (FF::HASVEC) {
; #pragma unroll
;         for (int kb = 0; kb < 4; ++kb) {
;           const f32x4 av = ff.vec(kb);
; #pragma unroll
;           for (int j = 0; j < 4; ++j) s[kb][rb][j] = opq(fmaf(s[kb][rb][j], fsc, av[j]));
;         }
;       }
;       if (MODE == 2) {
;         const float c = cl - m[rb];
; #pragma unroll
;         for (int kb = 0; kb < 4; ++kb)
; #pragma unroll
;           for (int j = 0; j < 4; ++j) {
;             const float e = FF::HASVEC ? opq(s[kb][rb][j] + c) : opq(fmaf(s[kb][rb][j], fsc, c));
;             s[kb][rb][j] = opq(fexp2(e) * l[rb]);
;           }
;       } else if (MODE == 0) {
;         float mx = max16(s[0][rb], s[1][rb], s[2][rb], s[3][rb]);
;         mx = xmax16(mx); mx = xmax32(mx);
;         const float cand = FF::HASVEC ? (mx + cl) : fmaf(mx, fsc, cl);
;         if (__builtin_amdgcn_ballot_w64(cand > m[rb] + DEFER_THR) != 0) {
;           const float mn = fmaxf(m[rb], cand);
;           const float alpha = fexp2(m[rb] - mn);
;           m[rb] = mn;
; #pragma unroll
;           for (int db = 0; db < 5; ++db)
; #pragma unroll
;             for (int j = 0; j < 4; ++j) o[db][rb][j] = opq(o[db][rb][j] * alpha);
;         }
.LBB0_1141:
	s_andn2_saveexec_b64 s[38:39], s[94:95]
	s_cbranch_execz .LBB0_1145
	v_cmp_ne_u64_e32 vcc, 0, v[126:127]
	v_max_f32_e32 v127, v72, v73
	v_max3_f32 v211, v75, v68, v69
	v_max3_f32 v213, v65, v66, v67
	v_max3_f32 v214, v60, v61, v62
	v_max3_f32 v212, v70, v71, v64
	v_max3_f32 v127, v127, v74, v211
	v_max3_f32 v211, v213, v214, v63
	v_max3_f32 v127, v127, v212, v211
	v_mov_b32_e32 v211, v127
	s_nop 1
	v_permlane16_swap_b32_e32 v127, v211
	v_max_f32_e32 v127, v127, v211
	v_mov_b32_e32 v211, v127
	s_nop 1
	v_permlane32_swap_b32_e32 v127, v211
	v_cndmask_b32_e32 v126, v181, v128, vcc
	v_max_f32_e32 v127, v127, v211
	v_fmamk_f32 v127, v127, 0x3e38aa3b, v126
	v_add_f32_e32 v211, 0x41000000, v207
	v_cmp_gt_f32_e32 vcc, v127, v211
	s_cbranch_vccz .LBB0_1144
	v_max_f32_e32 v211, v207, v207
	v_max_f32_e32 v127, v211, v127
	v_sub_f32_e32 v207, v207, v127
	v_exp_f32_e32 v207, v207
	s_nop 0
	v_mul_f32_e32 v56, v56, v207
	v_mul_f32_e32 v57, v57, v207
	v_mul_f32_e32 v58, v58, v207
	v_mul_f32_e32 v59, v59, v207
	v_mul_f32_e32 v52, v52, v207
	v_mul_f32_e32 v53, v53, v207
	v_mul_f32_e32 v54, v54, v207
	v_mul_f32_e32 v55, v55, v207
	v_mul_f32_e32 v48, v48, v207
	v_mul_f32_e32 v49, v49, v207
	v_mul_f32_e32 v50, v50, v207
	v_mul_f32_e32 v51, v51, v207
	v_mul_f32_e32 v44, v44, v207
	v_mul_f32_e32 v45, v45, v207
	v_mul_f32_e32 v46, v46, v207
	v_mul_f32_e32 v47, v47, v207
	v_mul_f32_e32 v36, v36, v207
	v_mul_f32_e32 v37, v37, v207
	v_mul_f32_e32 v38, v38, v207
	v_mul_f32_e32 v39, v39, v207
	v_mov_b32_e32 v207, v127

; template <int DK, int MODE, int RBM, class SF, class FF, class POST>
; DEVI void attn_tile_body(const bf16x8 (&qf)[2][DK / 32], const char* Ks, const char* Vs, SF& sf, FF& ff, POST& post,
;                          int cur, int c0, int c1, float (&m)[2], float (&l)[2], f32x4 (&o)[5][2], int fr, int fq) {
;     ...
;   if (MODE != 1) {
;     bf16x8 pf[2][2];
; #pragma unroll
;     for (int rb = 0; rb < 2; ++rb) {
;       if (!(RBM & (1 << rb))) continue;
; #pragma unroll
;       for (int kp2 = 0; kp2 < 2; ++kp2) {
;         u32x4 w;
;         w[0] = pack2(s[2 * kp2][rb][0], s[2 * kp2][rb][1]); w[1] = pack2(s[2 * kp2][rb][2], s[2 * kp2][rb][3]);
;         w[2] = pack2(s[2 * kp2 + 1][rb][0], s[2 * kp2 + 1][rb][1]); w[3] = pack2(s[2 * kp2 + 1][rb][2], s[2 * kp2 + 1][rb][3]);
;         pf[rb][kp2] = __builtin_bit_cast(bf16x8, w);
;       }
;     }
; #pragma unroll
;     for (int kp2 = 0; kp2 < 2; ++kp2)
; #pragma unroll
;       for (int db = 0; db < 4; ++db) {
;         const char* base = Vs + (db * 16 + fr) * 128 + (fq & 1) * 8;
;         const int c = kp2 * 4 + (fq >> 1);
;         u32x2 lo = *(const u32x2*)(base + ((c ^ (fr & 7)) * 16));
;         u32x2 hi = *(const u32x2*)(base + (((c + 2) ^ (fr & 7)) * 16));
;         u32x4 w; w[0] = lo[0]; w[1] = lo[1]; w[2] = hi[0]; w[3] = hi[1];
;         bf16x8 vf = __builtin_bit_cast(bf16x8, w);
;         if (RBM & 1) o[db][0] = __builtin_amdgcn_mfma_f32_16x16x32_bf16(vf, pf[0][kp2], o[db][0], 0, 0, 0);
;         if (RBM & 2) o[db][1] = __builtin_amdgcn_mfma_f32_16x16x32_bf16(vf, pf[1][kp2], o[db][1], 0, 0, 0);
;       }
;     if (MODE == 0) {
;       u32x4 w1; w1[0] = w1[1] = w1[2] = w1[3] = 0x3F803F80u;
;       const bf16x8 ones = __builtin_bit_cast(bf16x8, w1);
; #pragma unroll
;       for (int kp2 = 0; kp2 < 2; ++kp2) {
;         if (RBM & 1) o[4][0] = __builtin_amdgcn_mfma_f32_16x16x32_bf16(ones, pf[0][kp2], o[4][0], 0, 0, 0);
;         if (RBM & 2) o[4][1] = __builtin_amdgcn_mfma_f32_16x16x32_bf16(ones, pf[1][kp2], o[4][1], 0, 0, 0);
;       }
;     }
.LBB0_1145:
	s_or_b64 exec, exec, s[38:39]
	v_add3_u32 v126, s43, v135, v132
	v_add_u32_e32 v68, v126, v138
	v_add_u32_e32 v72, v126, v139
	v_cvt_pk_bf16_f32 v64, v211, v212
	v_add_u32_e32 v127, 0x100, v68
	v_add_u32_e32 v211, 0x100, v72
	ds_read_b64 v[232:233], v127 offset:24576
	ds_read_b64 v[236:237], v127 offset:26624
	ds_read_b64 v[234:235], v211 offset:24576
	ds_read_b64 v[238:239], v211 offset:26624
	v_cvt_pk_bf16_f32 v65, v213, v214
	v_cvt_pk_bf16_f32 v66, v215, v216
	v_cvt_pk_bf16_f32 v67, v217, v218
	s_waitcnt lgkmcnt(0)
	v_exp_f32_e32 v63, v219
	v_mfma_f32_16x16x32_bf16 v[52:55], v[236:239], v[64:67], v[52:55]
	ds_read_b64 v[240:241], v127 offset:28672
	ds_read_b64 v[244:245], v127 offset:30720
	ds_read_b64 v[242:243], v211 offset:28672
	ds_read_b64 v[246:247], v211 offset:30720
	v_cvt_pk_bf16_f32 v60, v220, v221
	v_cvt_pk_bf16_f32 v61, v222, v223
	v_mfma_f32_16x16x32_bf16 v[56:59], v[232:235], v[64:67], v[56:59]
	s_waitcnt lgkmcnt(0)
	v_add_u32_e32 v68, v126, v140
	v_add_u32_e32 v127, 0x100, v68
	v_mfma_f32_16x16x32_bf16 v[44:47], v[244:247], v[64:67], v[44:47]
	v_add_u32_e32 v72, v126, v141
	v_add_u32_e32 v126, 0x100, v72
	ds_read_b64 v[232:233], v127 offset:24576
	ds_read_b64 v[236:237], v127 offset:26624
	ds_read_b64 v[234:235], v126 offset:24576
	ds_read_b64 v[238:239], v126 offset:26624
	v_mfma_f32_16x16x32_bf16 v[48:51], v[240:243], v[64:67], v[48:51]
	v_cvt_pk_bf16_f32 v62, v224, v225
	s_waitcnt lgkmcnt(0)
	v_cvt_pk_bf16_f32 v63, v226, v63
	s_nop 1
	v_mfma_f32_16x16x32_bf16 v[52:55], v[236:239], v[60:63], v[52:55]
	ds_read_b64 v[240:241], v127 offset:28672
	ds_read_b64 v[244:245], v127 offset:30720
	ds_read_b64 v[242:243], v126 offset:28672
	ds_read_b64 v[246:247], v126 offset:30720
	s_mov_b32 s93, s92
	s_mov_b32 s94, s92
	v_mfma_f32_16x16x32_bf16 v[56:59], v[232:235], v[60:63], v[56:59]
	s_waitcnt lgkmcnt(0)
	s_mov_b32 s95, s92
	v_mov_b64_e32 v[68:69], s[92:93]
	v_mov_b64_e32 v[70:71], s[94:95]
	v_mfma_f32_16x16x32_bf16 v[48:51], v[240:243], v[60:63], v[48:51]
	s_nop 0
	v_mfma_f32_16x16x32_bf16 v[36:39], v[68:71], v[64:67], v[36:39]
	v_mfma_f32_16x16x32_bf16 v[44:47], v[244:247], v[60:63], v[44:47]
	v_mfma_f32_16x16x32_bf16 v[36:39], v[68:71], v[60:63], v[36:39]

; DEVI float opq(float x) { asm("" : "+v"(x)); return x; }
; DEVI float fexp2(float x) { return __builtin_amdgcn_exp2f(x); }
; DEVI float xmax16(float x) {
;   u32x2 r = __builtin_amdgcn_permlane16_swap(__float_as_uint(x), __float_as_uint(x), false, false);
;   return fmaxf(__uint_as_float(r[0]), __uint_as_float(r[1]));
; }
; DEVI float xmax32(float x) {
;   u32x2 r = __builtin_amdgcn_permlane32_swap(__float_as_uint(x), __float_as_uint(x), false, false);
;   return fmaxf(__uint_as_float(r[0]), __uint_as_float(r[1]));
; }
; template <int DK, int MODE, int RBM, class SF, class FF, class POST>
; DEVI void attn_tile_body(const bf16x8 (&qf)[2][DK / 32], const char* Ks, const char* Vs, SF& sf, FF& ff, POST& post,
;                          int cur, int c0, int c1, float (&m)[2], float (&l)[2], f32x4 (&o)[5][2], int fr, int fq) {
;     ...
;     } else if (MODE == 0) {
;       float mx = max16(s[0][rb], s[1][rb], s[2][rb], s[3][rb]);
;       mx = xmax16(mx); mx = xmax32(mx);
;       if (__builtin_amdgcn_ballot_w64(mx > m[rb] + DEFER_THR) != 0) {
;         const float mn = fmaxf(m[rb], mx);
;         const float alpha = fexp2(m[rb] - mn);
;         m[rb] = mn;
; #pragma unroll
;         for (int db = 0; db < 5; ++db)
; #pragma unroll
;           for (int j = 0; j < 4; ++j) o[db][rb][j] = opq(o[db][rb][j] * alpha);
;       }
.LBB0_1180:
	s_or_b64 exec, exec, s[6:7]
	v_max_f32_e32 v62, v2, v0
	v_max3_f32 v63, v3, v74, v73
	v_max3_f32 v126, v70, v65, v64
	v_max3_f32 v127, v67, v66, v61
	v_max3_f32 v75, v69, v68, v71
	v_max3_f32 v62, v62, v72, v63
	v_max3_f32 v63, v126, v127, v60
	v_max3_f32 v62, v62, v75, v63
	v_mov_b32_e32 v63, v62
	s_nop 1
	v_permlane16_swap_b32_e32 v62, v63
	v_max_f32_e32 v62, v62, v63
	v_mov_b32_e32 v63, v62
	s_nop 1
	v_permlane32_swap_b32_e32 v62, v63
	v_max_f32_e32 v62, v62, v63
	v_add_f32_e32 v63, 0x41000000, v208
	v_cmp_gt_f32_e32 vcc, v62, v63
	s_cbranch_vccz .LBB0_1182
	v_max_f32_e32 v63, v208, v208
	v_max_f32_e32 v62, v63, v62
	v_sub_f32_e32 v63, v208, v62
	v_exp_f32_e32 v63, v63
	v_mov_b32_e32 v208, v62
	v_mul_f32_e32 v40, v40, v63
	v_mul_f32_e32 v41, v41, v63
	v_mul_f32_e32 v42, v42, v63
	v_mul_f32_e32 v43, v43, v63
	v_mul_f32_e32 v32, v32, v63
	v_mul_f32_e32 v33, v33, v63
	v_mul_f32_e32 v34, v34, v63
	v_mul_f32_e32 v35, v35, v63
	v_mul_f32_e32 v28, v28, v63
	v_mul_f32_e32 v29, v29, v63
	v_mul_f32_e32 v30, v30, v63
	v_mul_f32_e32 v31, v31, v63
	v_mul_f32_e32 v24, v24, v63
	v_mul_f32_e32 v25, v25, v63
	v_mul_f32_e32 v26, v26, v63
	v_mul_f32_e32 v27, v27, v63
	v_mul_f32_e32 v20, v20, v63
	v_mul_f32_e32 v21, v21, v63
	v_mul_f32_e32 v22, v22, v63
	v_mul_f32_e32 v23, v23, v63

; DEVI float opq(float x) { asm("" : "+v"(x)); return x; }
; DEVI float fexp2(float x) { return __builtin_amdgcn_exp2f(x); }
; DEVI float xmax16(float x) {
;   u32x2 r = __builtin_amdgcn_permlane16_swap(__float_as_uint(x), __float_as_uint(x), false, false);
;   return fmaxf(__uint_as_float(r[0]), __uint_as_float(r[1]));
; }
; DEVI float xmax32(float x) {
;   u32x2 r = __builtin_amdgcn_permlane32_swap(__float_as_uint(x), __float_as_uint(x), false, false);
;   return fmaxf(__uint_as_float(r[0]), __uint_as_float(r[1]));
; }
; template <int DK, int MODE, int RBM, class SF, class FF, class POST>
; DEVI void attn_tile_body(const bf16x8 (&qf)[2][DK / 32], const char* Ks, const char* Vs, SF& sf, FF& ff, POST& post,
;                          int cur, int c0, int c1, float (&m)[2], float (&l)[2], f32x4 (&o)[5][2], int fr, int fq) {
;     ...
;       const float cl = ff.cl(rb, cur);
;       const float fsc = ff.sc;
;       if (FF::HASVEC) {
; #pragma unroll
;         for (int kb = 0; kb < 4; ++kb) {
;           const f32x4 av = ff.vec(kb);
; #pragma unroll
;           for (int j = 0; j < 4; ++j) s[kb][rb][j] = opq(fmaf(s[kb][rb][j], fsc, av[j]));
;         }
;       }
;       if (MODE == 2) {
;         const float c = cl - m[rb];
; #pragma unroll
;         for (int kb = 0; kb < 4; ++kb)
; #pragma unroll
;           for (int j = 0; j < 4; ++j) {
;             const float e = FF::HASVEC ? opq(s[kb][rb][j] + c) : opq(fmaf(s[kb][rb][j], fsc, c));
;             s[kb][rb][j] = opq(fexp2(e) * l[rb]);
;           }
;       } else if (MODE == 0) {
;         float mx = max16(s[0][rb], s[1][rb], s[2][rb], s[3][rb]);
;         mx = xmax16(mx); mx = xmax32(mx);
;         const float cand = FF::HASVEC ? (mx + cl) : fmaf(mx, fsc, cl);
;         if (__builtin_amdgcn_ballot_w64(cand > m[rb] + DEFER_THR) != 0) {
;           const float mn = fmaxf(m[rb], cand);
;           const float alpha = fexp2(m[rb] - mn);
;           m[rb] = mn;
; #pragma unroll
;           for (int db = 0; db < 5; ++db)
; #pragma unroll
;             for (int j = 0; j < 4; ++j) o[db][rb][j] = opq(o[db][rb][j] * alpha);
;         }
.LBB0_1183:
	s_andn2_saveexec_b64 s[38:39], s[94:95]
	s_cbranch_execz .LBB0_1187
	v_cmp_ne_u64_e32 vcc, 0, v[2:3]
	v_max_f32_e32 v2, v72, v73
	v_max3_f32 v3, v75, v68, v69
	v_max3_f32 v127, v65, v66, v67
	v_max3_f32 v209, v60, v61, v62
	v_max3_f32 v126, v70, v71, v64
	v_max3_f32 v2, v2, v74, v3
	v_max3_f32 v3, v127, v209, v63
	v_max3_f32 v2, v2, v126, v3
	v_mov_b32_e32 v3, v2
	s_nop 1
	v_permlane16_swap_b32_e32 v2, v3
	v_max_f32_e32 v2, v2, v3
	v_mov_b32_e32 v3, v2
	s_nop 1
	v_permlane32_swap_b32_e32 v2, v3
	v_cndmask_b32_e32 v0, v181, v128, vcc
	v_max_f32_e32 v2, v2, v3
	v_fmamk_f32 v2, v2, 0x3e38aa3b, v0
	v_add_f32_e32 v3, 0x41000000, v208
	v_cmp_gt_f32_e32 vcc, v2, v3
	s_cbranch_vccz .LBB0_1186
	v_max_f32_e32 v3, v208, v208
	v_max_f32_e32 v2, v3, v2
	v_sub_f32_e32 v3, v208, v2
	v_exp_f32_e32 v3, v3
	v_mov_b32_e32 v208, v2
	v_mul_f32_e32 v40, v40, v3
	v_mul_f32_e32 v41, v41, v3
	v_mul_f32_e32 v42, v42, v3
	v_mul_f32_e32 v43, v43, v3
	v_mul_f32_e32 v32, v32, v3
	v_mul_f32_e32 v33, v33, v3
	v_mul_f32_e32 v34, v34, v3
	v_mul_f32_e32 v35, v35, v3
	v_mul_f32_e32 v28, v28, v3
	v_mul_f32_e32 v29, v29, v3
	v_mul_f32_e32 v30, v30, v3
	v_mul_f32_e32 v31, v31, v3
	v_mul_f32_e32 v24, v24, v3
	v_mul_f32_e32 v25, v25, v3
	v_mul_f32_e32 v26, v26, v3
	v_mul_f32_e32 v27, v27, v3
	v_mul_f32_e32 v20, v20, v3
	v_mul_f32_e32 v21, v21, v3
	v_mul_f32_e32 v22, v22, v3
	v_mul_f32_e32 v23, v23, v3

; template <int DK, int MODE, int RBM, class SF, class FF, class POST>
; DEVI void attn_tile_body(const bf16x8 (&qf)[2][DK / 32], const char* Ks, const char* Vs, SF& sf, FF& ff, POST& post,
;                          int cur, int c0, int c1, float (&m)[2], float (&l)[2], f32x4 (&o)[5][2], int fr, int fq) {
;     ...
;   if (MODE != 1) {
;     bf16x8 pf[2][2];
; #pragma unroll
;     for (int rb = 0; rb < 2; ++rb) {
;       if (!(RBM & (1 << rb))) continue;
; #pragma unroll
;       for (int kp2 = 0; kp2 < 2; ++kp2) {
;         u32x4 w;
;         w[0] = pack2(s[2 * kp2][rb][0], s[2 * kp2][rb][1]); w[1] = pack2(s[2 * kp2][rb][2], s[2 * kp2][rb][3]);
;         w[2] = pack2(s[2 * kp2 + 1][rb][0], s[2 * kp2 + 1][rb][1]); w[3] = pack2(s[2 * kp2 + 1][rb][2], s[2 * kp2 + 1][rb][3]);
;         pf[rb][kp2] = __builtin_bit_cast(bf16x8, w);
;       }
;     }
; #pragma unroll
;     for (int kp2 = 0; kp2 < 2; ++kp2)
; #pragma unroll
;       for (int db = 0; db < 4; ++db) {
;         const char* base = Vs + (db * 16 + fr) * 128 + (fq & 1) * 8;
;         const int c = kp2 * 4 + (fq >> 1);
;         u32x2 lo = *(const u32x2*)(base + ((c ^ (fr & 7)) * 16));
;         u32x2 hi = *(const u32x2*)(base + (((c + 2) ^ (fr & 7)) * 16));
;         u32x4 w; w[0] = lo[0]; w[1] = lo[1]; w[2] = hi[0]; w[3] = hi[1];
;         bf16x8 vf = __builtin_bit_cast(bf16x8, w);
;         if (RBM & 1) o[db][0] = __builtin_amdgcn_mfma_f32_16x16x32_bf16(vf, pf[0][kp2], o[db][0], 0, 0, 0);
;         if (RBM & 2) o[db][1] = __builtin_amdgcn_mfma_f32_16x16x32_bf16(vf, pf[1][kp2], o[db][1], 0, 0, 0);
;       }
;     if (MODE == 0) {
;       u32x4 w1; w1[0] = w1[1] = w1[2] = w1[3] = 0x3F803F80u;
;       const bf16x8 ones = __builtin_bit_cast(bf16x8, w1);
; #pragma unroll
;       for (int kp2 = 0; kp2 < 2; ++kp2) {
;         if (RBM & 1) o[4][0] = __builtin_amdgcn_mfma_f32_16x16x32_bf16(ones, pf[0][kp2], o[4][0], 0, 0, 0);
;         if (RBM & 2) o[4][1] = __builtin_amdgcn_mfma_f32_16x16x32_bf16(ones, pf[1][kp2], o[4][1], 0, 0, 0);
;       }
;     }
.LBB0_1201:
	s_or_b64 exec, exec, s[36:37]
	v_cvt_pk_bf16_f32 v73, v87, v88
	v_add3_u32 v88, s42, v145, v142
	v_cvt_pk_bf16_f32 v68, v77, v76
	v_cvt_pk_bf16_f32 v70, v80, v81
	v_add_u32_e32 v76, v88, v146
	v_add_u32_e32 v80, v88, v147
	v_cvt_pk_bf16_f32 v74, v89, v90
	v_add_u32_e32 v89, 0x100, v76
	v_add_u32_e32 v90, 0x100, v80
	v_cvt_pk_bf16_f32 v69, v78, v79
	v_cvt_pk_bf16_f32 v71, v82, v84
	v_cvt_pk_bf16_f32 v72, v83, v86
	ds_read_b64 v[232:233], v89 offset:24576
	ds_read_b64 v[236:237], v89 offset:26624
	ds_read_b64 v[234:235], v90 offset:24576
	ds_read_b64 v[238:239], v90 offset:26624
	v_cvt_pk_bf16_f32 v60, v213, v214
	v_cvt_pk_bf16_f32 v61, v215, v216
	v_cvt_pk_bf16_f32 v62, v217, v218
	v_cvt_pk_bf16_f32 v63, v219, v222
	s_waitcnt lgkmcnt(0)
	v_exp_f32_e32 v75, v85
	v_mfma_f32_16x16x32_bf16 v[48:51], v[236:239], v[60:63], v[48:51]
	v_exp_f32_e32 v67, v220
	v_cvt_pk_bf16_f32 v64, v221, v223
	v_cvt_pk_bf16_f32 v65, v224, v225
	v_mfma_f32_16x16x32_bf16 v[40:43], v[236:239], v[68:71], v[40:43]
	ds_read_b64 v[240:241], v89 offset:28672
	ds_read_b64 v[244:245], v89 offset:30720
	ds_read_b64 v[242:243], v90 offset:28672
	ds_read_b64 v[246:247], v90 offset:30720
	v_cvt_pk_bf16_f32 v66, v226, v227
	v_cvt_pk_bf16_f32 v67, v228, v67
	v_mfma_f32_16x16x32_bf16 v[52:55], v[232:235], v[60:63], v[52:55]
	v_cvt_pk_bf16_f32 v75, v91, v75
	s_mov_b32 s93, s92
	s_mov_b32 s94, s92
	v_mfma_f32_16x16x32_bf16 v[32:35], v[232:235], v[68:71], v[32:35]
	s_waitcnt lgkmcnt(0)
	v_add_u32_e32 v76, v88, v148
	v_mfma_f32_16x16x32_bf16 v[44:47], v[244:247], v[60:63], v[44:47]
	v_add_u32_e32 v89, 0x100, v76
	ds_read_b64 v[232:233], v89 offset:24576
	ds_read_b64 v[236:237], v89 offset:26624
	v_mfma_f32_16x16x32_bf16 v[28:31], v[244:247], v[68:71], v[28:31]
	v_add_u32_e32 v80, v88, v149
	v_add_u32_e32 v88, 0x100, v80
	ds_read_b64 v[234:235], v88 offset:24576
	ds_read_b64 v[238:239], v88 offset:26624
	v_mfma_f32_16x16x32_bf16 v[56:59], v[240:243], v[60:63], v[56:59]
	s_mov_b32 s95, s92
	v_mfma_f32_16x16x32_bf16 v[36:39], v[240:243], v[68:71], v[36:39]
	s_waitcnt lgkmcnt(0)
	v_mfma_f32_16x16x32_bf16 v[48:51], v[236:239], v[64:67], v[48:51]
	v_mfma_f32_16x16x32_bf16 v[40:43], v[236:239], v[72:75], v[40:43]
	ds_read_b64 v[240:241], v89 offset:28672
	ds_read_b64 v[244:245], v89 offset:30720
	ds_read_b64 v[242:243], v88 offset:28672
	ds_read_b64 v[246:247], v88 offset:30720
	v_mfma_f32_16x16x32_bf16 v[52:55], v[232:235], v[64:67], v[52:55]
	v_mfma_f32_16x16x32_bf16 v[32:35], v[232:235], v[72:75], v[32:35]
	s_waitcnt lgkmcnt(0)
	v_mov_b64_e32 v[76:77], s[92:93]
	v_mov_b64_e32 v[78:79], s[94:95]
	v_mfma_f32_16x16x32_bf16 v[56:59], v[240:243], v[64:67], v[56:59]
	s_nop 0
	v_mfma_f32_16x16x32_bf16 v[24:27], v[76:79], v[60:63], v[24:27]
	v_mfma_f32_16x16x32_bf16 v[20:23], v[76:79], v[68:71], v[20:23]
	v_mfma_f32_16x16x32_bf16 v[36:39], v[240:243], v[72:75], v[36:39]
	v_mfma_f32_16x16x32_bf16 v[44:47], v[244:247], v[64:67], v[44:47]
	v_mfma_f32_16x16x32_bf16 v[28:31], v[244:247], v[72:75], v[28:31]
	v_mfma_f32_16x16x32_bf16 v[24:27], v[76:79], v[64:67], v[24:27]
	v_mfma_f32_16x16x32_bf16 v[20:23], v[76:79], v[72:75], v[20:23]

; DEVI float opq(float x) { asm("" : "+v"(x)); return x; }
; DEVI float fexp2(float x) { return __builtin_amdgcn_exp2f(x); }
; DEVI float xmax16(float x) {
;   u32x2 r = __builtin_amdgcn_permlane16_swap(__float_as_uint(x), __float_as_uint(x), false, false);
;   return fmaxf(__uint_as_float(r[0]), __uint_as_float(r[1]));
; }
; DEVI float xmax32(float x) {
;   u32x2 r = __builtin_amdgcn_permlane32_swap(__float_as_uint(x), __float_as_uint(x), false, false);
;   return fmaxf(__uint_as_float(r[0]), __uint_as_float(r[1]));
; }
; template <int DK, int MODE, int RBM, class SF, class FF, class POST>
; DEVI void attn_tile_body(const bf16x8 (&qf)[2][DK / 32], const char* Ks, const char* Vs, SF& sf, FF& ff, POST& post,
;                          int cur, int c0, int c1, float (&m)[2], float (&l)[2], f32x4 (&o)[5][2], int fr, int fq) {
;     ...
;     } else if (MODE == 0) {
;       float mx = max16(s[0][rb], s[1][rb], s[2][rb], s[3][rb]);
;       mx = xmax16(mx); mx = xmax32(mx);
;       if (__builtin_amdgcn_ballot_w64(mx > m[rb] + DEFER_THR) != 0) {
;         const float mn = fmaxf(m[rb], mx);
;         const float alpha = fexp2(m[rb] - mn);
;         m[rb] = mn;
; #pragma unroll
;         for (int db = 0; db < 5; ++db)
; #pragma unroll
;           for (int j = 0; j < 4; ++j) o[db][rb][j] = opq(o[db][rb][j] * alpha);
;       }
.LBB0_1242:
	s_or_b64 exec, exec, s[6:7]
	v_max_f32_e32 v78, v214, v215
	v_max3_f32 v79, v88, v91, v90
	v_max3_f32 v217, v86, v81, v80
	v_max3_f32 v218, v83, v82, v77
	v_max3_f32 v216, v85, v84, v87
	v_max3_f32 v78, v78, v89, v79
	v_max3_f32 v79, v217, v218, v76
	v_max3_f32 v78, v78, v216, v79
	v_mov_b32_e32 v79, v78
	s_nop 1
	v_permlane16_swap_b32_e32 v78, v79
	v_max_f32_e32 v78, v78, v79
	v_mov_b32_e32 v79, v78
	s_nop 1
	v_permlane32_swap_b32_e32 v78, v79
	v_max_f32_e32 v78, v78, v79
	v_add_f32_e32 v79, 0x41000000, v211
	v_cmp_gt_f32_e32 vcc, v78, v79
	s_cbranch_vccz .LBB0_1244
	v_max_f32_e32 v79, v211, v211
	v_max_f32_e32 v78, v79, v78
	v_sub_f32_e32 v79, v211, v78
	v_exp_f32_e32 v79, v79
	v_mov_b32_e32 v211, v78
	v_mul_f32_e32 v52, v52, v79
	v_mul_f32_e32 v53, v53, v79
	v_mul_f32_e32 v54, v54, v79
	v_mul_f32_e32 v55, v55, v79
	v_mul_f32_e32 v48, v48, v79
	v_mul_f32_e32 v49, v49, v79
	v_mul_f32_e32 v50, v50, v79
	v_mul_f32_e32 v51, v51, v79
	v_mul_f32_e32 v56, v56, v79
	v_mul_f32_e32 v57, v57, v79
	v_mul_f32_e32 v58, v58, v79
	v_mul_f32_e32 v59, v59, v79
	v_mul_f32_e32 v44, v44, v79
	v_mul_f32_e32 v45, v45, v79
	v_mul_f32_e32 v46, v46, v79
	v_mul_f32_e32 v47, v47, v79
	v_mul_f32_e32 v24, v24, v79
	v_mul_f32_e32 v25, v25, v79
	v_mul_f32_e32 v26, v26, v79
	v_mul_f32_e32 v27, v27, v79

; DEVI float opq(float x) { asm("" : "+v"(x)); return x; }
; DEVI float fexp2(float x) { return __builtin_amdgcn_exp2f(x); }
; DEVI float xmax16(float x) {
;   u32x2 r = __builtin_amdgcn_permlane16_swap(__float_as_uint(x), __float_as_uint(x), false, false);
;   return fmaxf(__uint_as_float(r[0]), __uint_as_float(r[1]));
; }
; DEVI float xmax32(float x) {
;   u32x2 r = __builtin_amdgcn_permlane32_swap(__float_as_uint(x), __float_as_uint(x), false, false);
;   return fmaxf(__uint_as_float(r[0]), __uint_as_float(r[1]));
; }
; template <int DK, int MODE, int RBM, class SF, class FF, class POST>
; DEVI void attn_tile_body(const bf16x8 (&qf)[2][DK / 32], const char* Ks, const char* Vs, SF& sf, FF& ff, POST& post,
;                          int cur, int c0, int c1, float (&m)[2], float (&l)[2], f32x4 (&o)[5][2], int fr, int fq) {
;     ...
;       } else if (MODE == 0) {
;         float mx = max16(s[0][rb], s[1][rb], s[2][rb], s[3][rb]);
;         mx = xmax16(mx); mx = xmax32(mx);
;         const float cand = FF::HASVEC ? (mx + cl) : fmaf(mx, fsc, cl);
;         if (__builtin_amdgcn_ballot_w64(cand > m[rb] + DEFER_THR) != 0) {
;           const float mn = fmaxf(m[rb], cand);
;           const float alpha = fexp2(m[rb] - mn);
;           m[rb] = mn;
; #pragma unroll
;           for (int db = 0; db < 5; ++db)
; #pragma unroll
;             for (int j = 0; j < 4; ++j) o[db][rb][j] = opq(o[db][rb][j] * alpha);
;         }
.LBB0_1245:
	s_andn2_saveexec_b64 s[38:39], s[38:39]
	s_cbranch_execz .LBB0_1249
	v_max_f32_e32 v214, v88, v89
	v_max3_f32 v215, v91, v84, v85
	v_max3_f32 v217, v81, v82, v83
	v_max3_f32 v218, v76, v77, v78
	v_max3_f32 v216, v86, v87, v80
	v_max3_f32 v214, v214, v90, v215
	v_max3_f32 v215, v217, v218, v79
	v_max3_f32 v214, v214, v216, v215
	v_mov_b32_e32 v215, v214
	s_nop 1
	v_permlane16_swap_b32_e32 v214, v215
	v_max_f32_e32 v214, v214, v215
	v_mov_b32_e32 v215, v214
	s_nop 1
	v_permlane32_swap_b32_e32 v214, v215
	v_max_f32_e32 v214, v214, v215
	v_fmamk_f32 v214, v214, 0x3e38aa3b, v136
	v_add_f32_e32 v215, 0x41000000, v211
	v_cmp_gt_f32_e32 vcc, v214, v215
	s_cbranch_vccz .LBB0_1248
	v_max_f32_e32 v215, v211, v211
	v_max_f32_e32 v214, v215, v214
	v_sub_f32_e32 v211, v211, v214
	v_exp_f32_e32 v211, v211
	s_nop 0
	v_mul_f32_e32 v52, v52, v211
	v_mul_f32_e32 v53, v53, v211
	v_mul_f32_e32 v54, v54, v211
	v_mul_f32_e32 v55, v55, v211
	v_mul_f32_e32 v48, v48, v211
	v_mul_f32_e32 v49, v49, v211
	v_mul_f32_e32 v50, v50, v211
	v_mul_f32_e32 v51, v51, v211
	v_mul_f32_e32 v56, v56, v211
	v_mul_f32_e32 v57, v57, v211
	v_mul_f32_e32 v58, v58, v211
	v_mul_f32_e32 v59, v59, v211
	v_mul_f32_e32 v44, v44, v211
	v_mul_f32_e32 v45, v45, v211
	v_mul_f32_e32 v46, v46, v211
	v_mul_f32_e32 v47, v47, v211
	v_mul_f32_e32 v24, v24, v211
	v_mul_f32_e32 v25, v25, v211
	v_mul_f32_e32 v26, v26, v211
	v_mul_f32_e32 v27, v27, v211
	v_mov_b32_e32 v211, v214

; DEVI float opq(float x) { asm("" : "+v"(x)); return x; }
; DEVI float fexp2(float x) { return __builtin_amdgcn_exp2f(x); }
; DEVI float xmax16(float x) {
;   u32x2 r = __builtin_amdgcn_permlane16_swap(__float_as_uint(x), __float_as_uint(x), false, false);
;   return fmaxf(__uint_as_float(r[0]), __uint_as_float(r[1]));
; }
; DEVI float xmax32(float x) {
;   u32x2 r = __builtin_amdgcn_permlane32_swap(__float_as_uint(x), __float_as_uint(x), false, false);
;   return fmaxf(__uint_as_float(r[0]), __uint_as_float(r[1]));
; }
; template <int DK, int MODE, int RBM, class SF, class FF, class POST>
; DEVI void attn_tile_body(const bf16x8 (&qf)[2][DK / 32], const char* Ks, const char* Vs, SF& sf, FF& ff, POST& post,
;                          int cur, int c0, int c1, float (&m)[2], float (&l)[2], f32x4 (&o)[5][2], int fr, int fq) {
;     ...
;     } else if (MODE == 0) {
;       float mx = max16(s[0][rb], s[1][rb], s[2][rb], s[3][rb]);
;       mx = xmax16(mx); mx = xmax32(mx);
;       if (__builtin_amdgcn_ballot_w64(mx > m[rb] + DEFER_THR) != 0) {
;         const float mn = fmaxf(m[rb], mx);
;         const float alpha = fexp2(m[rb] - mn);
;         m[rb] = mn;
; #pragma unroll
;         for (int db = 0; db < 5; ++db)
; #pragma unroll
;           for (int j = 0; j < 4; ++j) o[db][rb][j] = opq(o[db][rb][j] * alpha);
;       }
.LBB0_1282:
	s_or_b64 exec, exec, s[6:7]
	v_max_f32_e32 v62, v77, v76
	v_max3_f32 v63, v72, v75, v74
	v_max3_f32 v79, v70, v65, v64
	v_max3_f32 v80, v67, v66, v61
	v_max3_f32 v78, v69, v68, v71
	v_max3_f32 v62, v62, v73, v63
	v_max3_f32 v63, v79, v80, v60
	v_max3_f32 v62, v62, v78, v63
	v_mov_b32_e32 v63, v62
	s_nop 1
	v_permlane16_swap_b32_e32 v62, v63
	v_max_f32_e32 v62, v62, v63
	v_mov_b32_e32 v63, v62
	s_nop 1
	v_permlane32_swap_b32_e32 v62, v63
	v_max_f32_e32 v62, v62, v63
	v_add_f32_e32 v63, 0x41000000, v3
	v_cmp_gt_f32_e32 vcc, v62, v63
	s_cbranch_vccz .LBB0_1284
	v_max_f32_e32 v63, v3, v3
	v_max_f32_e32 v62, v63, v62
	v_sub_f32_e32 v3, v3, v62
	v_exp_f32_e32 v3, v3
	s_nop 0
	v_mul_f32_e32 v32, v32, v3
	v_mul_f32_e32 v33, v33, v3
	v_mul_f32_e32 v34, v34, v3
	v_mul_f32_e32 v35, v35, v3
	v_mul_f32_e32 v40, v40, v3
	v_mul_f32_e32 v41, v41, v3
	v_mul_f32_e32 v42, v42, v3
	v_mul_f32_e32 v43, v43, v3
	v_mul_f32_e32 v36, v36, v3
	v_mul_f32_e32 v37, v37, v3
	v_mul_f32_e32 v38, v38, v3
	v_mul_f32_e32 v39, v39, v3
	v_mul_f32_e32 v28, v28, v3
	v_mul_f32_e32 v29, v29, v3
	v_mul_f32_e32 v30, v30, v3
	v_mul_f32_e32 v31, v31, v3
	v_mul_f32_e32 v20, v20, v3
	v_mul_f32_e32 v21, v21, v3
	v_mul_f32_e32 v22, v22, v3
	v_mul_f32_e32 v23, v23, v3
	v_mov_b32_e32 v3, v62

; DEVI float opq(float x) { asm("" : "+v"(x)); return x; }
; DEVI float fexp2(float x) { return __builtin_amdgcn_exp2f(x); }
; DEVI float xmax16(float x) {
;   u32x2 r = __builtin_amdgcn_permlane16_swap(__float_as_uint(x), __float_as_uint(x), false, false);
;   return fmaxf(__uint_as_float(r[0]), __uint_as_float(r[1]));
; }
; DEVI float xmax32(float x) {
;   u32x2 r = __builtin_amdgcn_permlane32_swap(__float_as_uint(x), __float_as_uint(x), false, false);
;   return fmaxf(__uint_as_float(r[0]), __uint_as_float(r[1]));
; }
; template <int DK, int MODE, int RBM, class SF, class FF, class POST>
; DEVI void attn_tile_body(const bf16x8 (&qf)[2][DK / 32], const char* Ks, const char* Vs, SF& sf, FF& ff, POST& post,
;                          int cur, int c0, int c1, float (&m)[2], float (&l)[2], f32x4 (&o)[5][2], int fr, int fq) {
;     ...
;       } else if (MODE == 0) {
;         float mx = max16(s[0][rb], s[1][rb], s[2][rb], s[3][rb]);
;         mx = xmax16(mx); mx = xmax32(mx);
;         const float cand = FF::HASVEC ? (mx + cl) : fmaf(mx, fsc, cl);
;         if (__builtin_amdgcn_ballot_w64(cand > m[rb] + DEFER_THR) != 0) {
;           const float mn = fmaxf(m[rb], cand);
;           const float alpha = fexp2(m[rb] - mn);
;           m[rb] = mn;
; #pragma unroll
;           for (int db = 0; db < 5; ++db)
; #pragma unroll
;             for (int j = 0; j < 4; ++j) o[db][rb][j] = opq(o[db][rb][j] * alpha);
;         }
.LBB0_1285:
	s_andn2_saveexec_b64 s[38:39], s[38:39]
	s_cbranch_execz .LBB0_1289
	v_max_f32_e32 v76, v72, v73
	v_max3_f32 v77, v75, v68, v69
	v_max3_f32 v79, v65, v66, v67
	v_max3_f32 v80, v60, v61, v62
	v_max3_f32 v78, v70, v71, v64
	v_max3_f32 v76, v76, v74, v77
	v_max3_f32 v77, v79, v80, v63
	v_max3_f32 v76, v76, v78, v77
	v_mov_b32_e32 v77, v76
	s_nop 1
	v_permlane16_swap_b32_e32 v76, v77
	v_max_f32_e32 v76, v76, v77
	v_mov_b32_e32 v77, v76
	s_nop 1
	v_permlane32_swap_b32_e32 v76, v77
	v_max_f32_e32 v76, v76, v77
	v_fmamk_f32 v76, v76, 0x3e38aa3b, v136
	v_add_f32_e32 v77, 0x41000000, v3
	v_cmp_gt_f32_e32 vcc, v76, v77
	s_cbranch_vccz .LBB0_1288
	v_max_f32_e32 v77, v3, v3
	v_max_f32_e32 v76, v77, v76
	v_sub_f32_e32 v3, v3, v76
	v_exp_f32_e32 v3, v3
	s_nop 0
	v_mul_f32_e32 v32, v32, v3
	v_mul_f32_e32 v33, v33, v3
	v_mul_f32_e32 v34, v34, v3
	v_mul_f32_e32 v35, v35, v3
	v_mul_f32_e32 v40, v40, v3
	v_mul_f32_e32 v41, v41, v3
	v_mul_f32_e32 v42, v42, v3
	v_mul_f32_e32 v43, v43, v3
	v_mul_f32_e32 v36, v36, v3
	v_mul_f32_e32 v37, v37, v3
	v_mul_f32_e32 v38, v38, v3
	v_mul_f32_e32 v39, v39, v3
	v_mul_f32_e32 v28, v28, v3
	v_mul_f32_e32 v29, v29, v3
	v_mul_f32_e32 v30, v30, v3
	v_mul_f32_e32 v31, v31, v3
	v_mul_f32_e32 v20, v20, v3
	v_mul_f32_e32 v21, v21, v3
	v_mul_f32_e32 v22, v22, v3
	v_mul_f32_e32 v23, v23, v3
	v_mov_b32_e32 v3, v76

; DEVI float opq(float x) { asm("" : "+v"(x)); return x; }
; DEVI float fexp2(float x) { return __builtin_amdgcn_exp2f(x); }
; DEVI float xmax16(float x) {
;   u32x2 r = __builtin_amdgcn_permlane16_swap(__float_as_uint(x), __float_as_uint(x), false, false);
;   return fmaxf(__uint_as_float(r[0]), __uint_as_float(r[1]));
; }
; DEVI float xmax32(float x) {
;   u32x2 r = __builtin_amdgcn_permlane32_swap(__float_as_uint(x), __float_as_uint(x), false, false);
;   return fmaxf(__uint_as_float(r[0]), __uint_as_float(r[1]));
; }
; template <int DK, int MODE, int RBM, class SF, class FF, class POST>
; DEVI void attn_tile_body(const bf16x8 (&qf)[2][DK / 32], const char* Ks, const char* Vs, SF& sf, FF& ff, POST& post,
;                          int cur, int c0, int c1, float (&m)[2], float (&l)[2], f32x4 (&o)[5][2], int fr, int fq) {
;     ...
;     } else if (MODE == 0) {
;       float mx = max16(s[0][rb], s[1][rb], s[2][rb], s[3][rb]);
;       mx = xmax16(mx); mx = xmax32(mx);
;       if (__builtin_amdgcn_ballot_w64(mx > m[rb] + DEFER_THR) != 0) {
;         const float mn = fmaxf(m[rb], mx);
;         const float alpha = fexp2(m[rb] - mn);
;         m[rb] = mn;
; #pragma unroll
;         for (int db = 0; db < 5; ++db)
; #pragma unroll
;           for (int j = 0; j < 4; ++j) o[db][rb][j] = opq(o[db][rb][j] * alpha);
;       }
.LBB0_1325:
	s_or_b64 exec, exec, s[6:7]
	v_max_f32_e32 v78, v213, v214
	v_max3_f32 v79, v88, v91, v90
	v_max3_f32 v216, v86, v81, v80
	v_max3_f32 v217, v83, v82, v77
	v_max3_f32 v215, v85, v84, v87
	v_max3_f32 v78, v78, v89, v79
	v_max3_f32 v79, v216, v217, v76
	v_max3_f32 v78, v78, v215, v79
	v_mov_b32_e32 v79, v78
	s_nop 1
	v_permlane16_swap_b32_e32 v78, v79
	v_max_f32_e32 v78, v78, v79
	v_mov_b32_e32 v79, v78
	s_nop 1
	v_permlane32_swap_b32_e32 v78, v79
	v_max_f32_e32 v78, v78, v79
	v_add_f32_e32 v79, 0x41000000, v211
	v_cmp_gt_f32_e32 vcc, v78, v79
	s_cbranch_vccz .LBB0_1327
	v_max_f32_e32 v79, v211, v211
	v_max_f32_e32 v78, v79, v78
	v_sub_f32_e32 v79, v211, v78
	v_exp_f32_e32 v79, v79
	v_mov_b32_e32 v211, v78
	v_mul_f32_e32 v52, v52, v79
	v_mul_f32_e32 v53, v53, v79
	v_mul_f32_e32 v54, v54, v79
	v_mul_f32_e32 v55, v55, v79
	v_mul_f32_e32 v48, v48, v79
	v_mul_f32_e32 v49, v49, v79
	v_mul_f32_e32 v50, v50, v79
	v_mul_f32_e32 v51, v51, v79
	v_mul_f32_e32 v56, v56, v79
	v_mul_f32_e32 v57, v57, v79
	v_mul_f32_e32 v58, v58, v79
	v_mul_f32_e32 v59, v59, v79
	v_mul_f32_e32 v44, v44, v79
	v_mul_f32_e32 v45, v45, v79
	v_mul_f32_e32 v46, v46, v79
	v_mul_f32_e32 v47, v47, v79
	v_mul_f32_e32 v24, v24, v79
	v_mul_f32_e32 v25, v25, v79
	v_mul_f32_e32 v26, v26, v79
	v_mul_f32_e32 v27, v27, v79

; DEVI float opq(float x) { asm("" : "+v"(x)); return x; }
; DEVI float fexp2(float x) { return __builtin_amdgcn_exp2f(x); }
; DEVI float xmax16(float x) {
;   u32x2 r = __builtin_amdgcn_permlane16_swap(__float_as_uint(x), __float_as_uint(x), false, false);
;   return fmaxf(__uint_as_float(r[0]), __uint_as_float(r[1]));
; }
; DEVI float xmax32(float x) {
;   u32x2 r = __builtin_amdgcn_permlane32_swap(__float_as_uint(x), __float_as_uint(x), false, false);
;   return fmaxf(__uint_as_float(r[0]), __uint_as_float(r[1]));
; }
; template <int DK, int MODE, int RBM, class SF, class FF, class POST>
; DEVI void attn_tile_body(const bf16x8 (&qf)[2][DK / 32], const char* Ks, const char* Vs, SF& sf, FF& ff, POST& post,
;                          int cur, int c0, int c1, float (&m)[2], float (&l)[2], f32x4 (&o)[5][2], int fr, int fq) {
;     ...
;       } else if (MODE == 0) {
;         float mx = max16(s[0][rb], s[1][rb], s[2][rb], s[3][rb]);
;         mx = xmax16(mx); mx = xmax32(mx);
;         const float cand = FF::HASVEC ? (mx + cl) : fmaf(mx, fsc, cl);
;         if (__builtin_amdgcn_ballot_w64(cand > m[rb] + DEFER_THR) != 0) {
;           const float mn = fmaxf(m[rb], cand);
;           const float alpha = fexp2(m[rb] - mn);
;           m[rb] = mn;
; #pragma unroll
;           for (int db = 0; db < 5; ++db)
; #pragma unroll
;             for (int j = 0; j < 4; ++j) o[db][rb][j] = opq(o[db][rb][j] * alpha);
;         }
.LBB0_1328:
	s_andn2_saveexec_b64 s[36:37], s[36:37]
	s_cbranch_execz .LBB0_1332
	v_max_f32_e32 v213, v88, v89
	v_max3_f32 v214, v91, v84, v85
	v_max3_f32 v216, v81, v82, v83
	v_max3_f32 v217, v76, v77, v78
	v_max3_f32 v215, v86, v87, v80
	v_max3_f32 v213, v213, v90, v214
	v_max3_f32 v214, v216, v217, v79
	v_max3_f32 v213, v213, v215, v214
	v_mov_b32_e32 v214, v213
	s_nop 1
	v_permlane16_swap_b32_e32 v213, v214
	v_max_f32_e32 v213, v213, v214
	v_mov_b32_e32 v214, v213
	s_nop 1
	v_permlane32_swap_b32_e32 v213, v214
	v_max_f32_e32 v213, v213, v214
	v_fmamk_f32 v213, v213, 0x3e38aa3b, v136
	v_add_f32_e32 v214, 0x41000000, v211
	v_cmp_gt_f32_e32 vcc, v213, v214
	s_cbranch_vccz .LBB0_1331
	v_max_f32_e32 v214, v211, v211
	v_max_f32_e32 v213, v214, v213
	v_sub_f32_e32 v211, v211, v213
	v_exp_f32_e32 v211, v211
	s_nop 0
	v_mul_f32_e32 v52, v52, v211
	v_mul_f32_e32 v53, v53, v211
	v_mul_f32_e32 v54, v54, v211
	v_mul_f32_e32 v55, v55, v211
	v_mul_f32_e32 v48, v48, v211
	v_mul_f32_e32 v49, v49, v211
	v_mul_f32_e32 v50, v50, v211
	v_mul_f32_e32 v51, v51, v211
	v_mul_f32_e32 v56, v56, v211
	v_mul_f32_e32 v57, v57, v211
	v_mul_f32_e32 v58, v58, v211
	v_mul_f32_e32 v59, v59, v211
	v_mul_f32_e32 v44, v44, v211
	v_mul_f32_e32 v45, v45, v211
	v_mul_f32_e32 v46, v46, v211
	v_mul_f32_e32 v47, v47, v211
	v_mul_f32_e32 v24, v24, v211
	v_mul_f32_e32 v25, v25, v211
	v_mul_f32_e32 v26, v26, v211
	v_mul_f32_e32 v27, v27, v211
	v_mov_b32_e32 v211, v213

; DEVI float opq(float x) { asm("" : "+v"(x)); return x; }
; DEVI float fexp2(float x) { return __builtin_amdgcn_exp2f(x); }
; DEVI float xmax16(float x) {
;   u32x2 r = __builtin_amdgcn_permlane16_swap(__float_as_uint(x), __float_as_uint(x), false, false);
;   return fmaxf(__uint_as_float(r[0]), __uint_as_float(r[1]));
; }
; DEVI float xmax32(float x) {
;   u32x2 r = __builtin_amdgcn_permlane32_swap(__float_as_uint(x), __float_as_uint(x), false, false);
;   return fmaxf(__uint_as_float(r[0]), __uint_as_float(r[1]));
; }
; template <int DK, int MODE, int RBM, class SF, class FF, class POST>
; DEVI void attn_tile_body(const bf16x8 (&qf)[2][DK / 32], const char* Ks, const char* Vs, SF& sf, FF& ff, POST& post,
;                          int cur, int c0, int c1, float (&m)[2], float (&l)[2], f32x4 (&o)[5][2], int fr, int fq) {
;     ...
;       } else if (MODE == 0) {
;         float mx = max16(s[0][rb], s[1][rb], s[2][rb], s[3][rb]);
;         mx = xmax16(mx); mx = xmax32(mx);
;         const float cand = FF::HASVEC ? (mx + cl) : fmaf(mx, fsc, cl);
;         if (__builtin_amdgcn_ballot_w64(cand > m[rb] + DEFER_THR) != 0) {
;           const float mn = fmaxf(m[rb], cand);
;           const float alpha = fexp2(m[rb] - mn);
;           m[rb] = mn;
; #pragma unroll
;           for (int db = 0; db < 5; ++db)
; #pragma unroll
;             for (int j = 0; j < 4; ++j) o[db][rb][j] = opq(o[db][rb][j] * alpha);
;         }
.LBB0_1368:
	s_andn2_saveexec_b64 s[36:37], s[36:37]
	s_cbranch_execz .LBB0_1201
	v_max_f32_e32 v76, v72, v73
	v_max3_f32 v77, v75, v68, v69
	v_max3_f32 v79, v65, v66, v67
	v_max3_f32 v80, v60, v61, v62
	v_max3_f32 v78, v70, v71, v64
	v_max3_f32 v76, v76, v74, v77
	v_max3_f32 v77, v79, v80, v63
	v_max3_f32 v76, v76, v78, v77
	v_mov_b32_e32 v77, v76
	s_nop 1
	v_permlane16_swap_b32_e32 v76, v77
	v_max_f32_e32 v76, v76, v77
	v_mov_b32_e32 v77, v76
	s_nop 1
	v_permlane32_swap_b32_e32 v76, v77
	v_max_f32_e32 v76, v76, v77
	v_fmamk_f32 v76, v76, 0x3e38aa3b, v136
	v_add_f32_e32 v77, 0x41000000, v3
	v_cmp_gt_f32_e32 vcc, v76, v77
	s_cbranch_vccz .LBB0_1200
	v_max_f32_e32 v77, v3, v3
	v_max_f32_e32 v76, v77, v76
	v_sub_f32_e32 v3, v3, v76
	v_exp_f32_e32 v3, v3
	s_nop 0
	v_mul_f32_e32 v32, v32, v3
	v_mul_f32_e32 v33, v33, v3
	v_mul_f32_e32 v34, v34, v3
	v_mul_f32_e32 v35, v35, v3
	v_mul_f32_e32 v40, v40, v3
	v_mul_f32_e32 v41, v41, v3
	v_mul_f32_e32 v42, v42, v3
	v_mul_f32_e32 v43, v43, v3
	v_mul_f32_e32 v36, v36, v3
	v_mul_f32_e32 v37, v37, v3
	v_mul_f32_e32 v38, v38, v3
	v_mul_f32_e32 v39, v39, v3
	v_mul_f32_e32 v28, v28, v3
	v_mul_f32_e32 v29, v29, v3
	v_mul_f32_e32 v30, v30, v3
	v_mul_f32_e32 v31, v31, v3
	v_mul_f32_e32 v20, v20, v3
	v_mul_f32_e32 v21, v21, v3
	v_mul_f32_e32 v22, v22, v3
	v_mul_f32_e32 v23, v23, v3
	v_mov_b32_e32 v3, v76
	s_branch .LBB0_1200

; template <int DK, int MODE, int RBM, class SF, class FF, class POST>
; DEVI void attn_tile_body(const bf16x8 (&qf)[2][DK / 32], const char* Ks, const char* Vs, SF& sf, FF& ff, POST& post,
;                          int cur, int c0, int c1, float (&m)[2], float (&l)[2], f32x4 (&o)[5][2], int fr, int fq) {
;     ...
;   for (int ks = 0; ks < NKC; ++ks)
; #pragma unroll
;     for (int kb = 0; kb < 4; ++kb) {
;       const int koff = DK == 64 ? (kb * 16 + fr) * 128 + (((ks * 4 + fq) ^ (fr & 7)) * 16)
;                                 : (kb * 16 + fr) * 192 + ((ks * 4 + (fq ^ ((fr >> 2) & 3))) * 16);
;       bf16x8 kf = *(const bf16x8*)(Ks + koff);
;       if (RBM & 1) s[kb][0] = __builtin_amdgcn_mfma_f32_16x16x32_bf16(kf, qf[0][ks], s[kb][0], 0, 0, 0);
;       if (RBM & 2) s[kb][1] = __builtin_amdgcn_mfma_f32_16x16x32_bf16(kf, qf[1][ks], s[kb][1], 0, 0, 0);
;     }
; #pragma unroll
;   for (int rb = 0; rb < 2; ++rb) {
;     if (!(RBM & (1 << rb))) continue;
;     const int cm = rb == 0 ? c0 : c1;
;     if (cm == 2) {
;       const float cl = ff.cl(rb, cur);
;       const float fsc = ff.sc;
;       if (FF::HASVEC) {
; #pragma unroll
;         for (int kb = 0; kb < 4; ++kb) {
;           const f32x4 av = ff.vec(kb);
; #pragma unroll
;           for (int j = 0; j < 4; ++j) s[kb][rb][j] = opq(fmaf(s[kb][rb][j], fsc, av[j]));
;         }
;       }
;       if (MODE == 2) {
;         const float c = cl - m[rb];
; #pragma unroll
;         for (int kb = 0; kb < 4; ++kb)
; #pragma unroll
;           for (int j = 0; j < 4; ++j) {
;             const float e = FF::HASVEC ? opq(s[kb][rb][j] + c) : opq(fmaf(s[kb][rb][j], fsc, c));
;             s[kb][rb][j] = opq(fexp2(e) * l[rb]);
;           }
;       } else if (MODE == 0) {
;         float mx = max16(s[0][rb], s[1][rb], s[2][rb], s[3][rb]);
;         mx = xmax16(mx); mx = xmax32(mx);
;         const float cand = FF::HASVEC ? (mx + cl) : fmaf(mx, fsc, cl);
;         if (__builtin_amdgcn_ballot_w64(cand > m[rb] + DEFER_THR) != 0) {
;           const float mn = fmaxf(m[rb], cand);
;           const float alpha = fexp2(m[rb] - mn);
;           m[rb] = mn;
; #pragma unroll
;           for (int db = 0; db < 5; ++db)
; #pragma unroll
;             for (int j = 0; j < 4; ++j) o[db][rb][j] = opq(o[db][rb][j] * alpha);
;         }
;         const float c = cl - m[rb];
; #pragma unroll
;         for (int kb = 0; kb < 4; ++kb)
.LBB0_1672:
	s_mul_i32 s7, s43, 0x4100
	v_add_u32_e32 v74, s7, v0
	v_add_u32_e32 v90, v74, v124
	ds_read_b128 v[70:73], v90 offset:4096
	ds_read_b128 v[58:61], v90
	v_add_u32_e32 v94, v74, v130
	ds_read_b128 v[66:69], v90 offset:2048
	s_waitcnt lgkmcnt(0)
	v_mfma_f32_16x16x32_bf16 v[82:85], v[70:73], v[2:5], 0
	v_mfma_f32_16x16x32_bf16 v[86:89], v[70:73], v[10:13], 0
	ds_read_b128 v[70:73], v90 offset:6144
	v_mfma_f32_16x16x32_bf16 v[62:65], v[58:61], v[2:5], 0
	s_waitcnt lgkmcnt(0)
	v_mfma_f32_16x16x32_bf16 v[96:99], v[70:73], v[2:5], 0
	v_mfma_f32_16x16x32_bf16 v[100:103], v[70:73], v[10:13], 0
	ds_read_b128 v[70:73], v94
	v_mfma_f32_16x16x32_bf16 v[58:61], v[58:61], v[10:13], 0
	s_waitcnt lgkmcnt(0)
	v_mfma_f32_16x16x32_bf16 v[74:77], v[70:73], v[6:9], v[62:65]
	v_mfma_f32_16x16x32_bf16 v[70:73], v[70:73], v[14:17], v[58:61]
	s_nop 6
	v_max_f32_e32 v91, v74, v75
	ds_read_b128 v[58:61], v94 offset:2048
	v_mfma_f32_16x16x32_bf16 v[78:81], v[66:69], v[2:5], 0
	v_mfma_f32_16x16x32_bf16 v[66:69], v[66:69], v[10:13], 0
	s_waitcnt lgkmcnt(0)
	v_mfma_f32_16x16x32_bf16 v[78:81], v[58:61], v[6:9], v[78:81]
	v_mfma_f32_16x16x32_bf16 v[66:69], v[58:61], v[14:17], v[66:69]
	ds_read_b128 v[58:61], v94 offset:4096
	s_nop 5
	v_max3_f32 v92, v77, v78, v79
	v_max3_f32 v91, v91, v76, v92
	s_waitcnt lgkmcnt(0)
	v_mfma_f32_16x16x32_bf16 v[82:85], v[58:61], v[6:9], v[82:85]
	s_nop 7
	v_max3_f32 v95, v83, v84, v85
	v_mfma_f32_16x16x32_bf16 v[62:65], v[58:61], v[14:17], v[86:89]
	ds_read_b128 v[58:61], v94 offset:6144
	v_max3_f32 v93, v80, v81, v82
	s_waitcnt lgkmcnt(0)
	v_mfma_f32_16x16x32_bf16 v[86:89], v[58:61], v[6:9], v[96:99]
	s_nop 7
	v_max3_f32 v96, v86, v87, v88
	v_max3_f32 v92, v95, v96, v89
	v_max3_f32 v91, v91, v93, v92
	v_mov_b32_e32 v92, v91
	s_nop 1
	v_permlane16_swap_b32_e32 v91, v92
	v_max_f32_e32 v91, v91, v92
	v_mov_b32_e32 v92, v91
	s_nop 1
	v_permlane32_swap_b32_e32 v91, v92
	v_mfma_f32_16x16x32_bf16 v[58:61], v[58:61], v[14:17], v[100:103]
	v_max_f32_e32 v91, v91, v92
	v_fma_f32 v91, v91, s0, 0
	v_add_f32_e32 v92, 0x41000000, v137
	v_cmp_gt_f32_e32 vcc, v91, v92
	s_cbranch_vccz .LBB0_1674
	v_max_f32_e32 v92, v137, v137
	v_max_f32_e32 v91, v92, v91
	v_sub_f32_e32 v92, v137, v91
	v_exp_f32_e32 v92, v92
	v_mov_b32_e32 v137, v91
	v_mul_f32_e32 v50, v50, v92
	v_mul_f32_e32 v51, v51, v92
	v_mul_f32_e32 v52, v52, v92
	v_mul_f32_e32 v53, v53, v92
	v_mul_f32_e32 v54, v54, v92
	v_mul_f32_e32 v55, v55, v92
	v_mul_f32_e32 v56, v56, v92
	v_mul_f32_e32 v57, v57, v92
	v_mul_f32_e32 v46, v46, v92
	v_mul_f32_e32 v47, v47, v92
	v_mul_f32_e32 v48, v48, v92
	v_mul_f32_e32 v49, v49, v92
	v_mul_f32_e32 v42, v42, v92
	v_mul_f32_e32 v43, v43, v92
	v_mul_f32_e32 v44, v44, v92
	v_mul_f32_e32 v45, v45, v92
	v_mul_f32_e32 v38, v38, v92
	v_mul_f32_e32 v39, v39, v92
	v_mul_f32_e32 v40, v40, v92
	v_mul_f32_e32 v41, v41, v92
.LBB0_1674:
	v_max_f32_e32 v91, v70, v71
	v_max3_f32 v92, v73, v66, v67
	v_max3_f32 v95, v63, v64, v65
	v_max3_f32 v96, v58, v59, v60
	v_max3_f32 v93, v68, v69, v62
	v_max3_f32 v91, v91, v72, v92
	v_max3_f32 v92, v95, v96, v61
	v_max3_f32 v91, v91, v93, v92
	v_mov_b32_e32 v92, v91
	s_nop 1
	v_permlane16_swap_b32_e32 v91, v92
	v_max_f32_e32 v91, v91, v92
	v_mov_b32_e32 v92, v91
	s_nop 1
	v_permlane32_swap_b32_e32 v91, v92
	v_max_f32_e32 v91, v91, v92
	v_sub_f32_e32 v143, 0, v137
	v_fma_f32 v91, v91, s0, 0
	v_add_f32_e32 v92, 0x41000000, v136
	v_fmamk_f32 v74, v74, 0x3e38aa3b, v143
	v_fmamk_f32 v75, v75, 0x3e38aa3b, v143
	v_fmamk_f32 v76, v76, 0x3e38aa3b, v143
	v_fmamk_f32 v77, v77, 0x3e38aa3b, v143
	v_fmamk_f32 v78, v78, 0x3e38aa3b, v143
	v_fmamk_f32 v79, v79, 0x3e38aa3b, v143
	v_fmamk_f32 v80, v80, 0x3e38aa3b, v143
	v_fmamk_f32 v81, v81, 0x3e38aa3b, v143
	v_fmamk_f32 v82, v82, 0x3e38aa3b, v143
	v_fmamk_f32 v83, v83, 0x3e38aa3b, v143
	v_fmamk_f32 v84, v84, 0x3e38aa3b, v143
	v_fmamk_f32 v85, v85, 0x3e38aa3b, v143
	v_fmamk_f32 v86, v86, 0x3e38aa3b, v143
	v_fmamk_f32 v87, v87, 0x3e38aa3b, v143
	v_fmamk_f32 v88, v88, 0x3e38aa3b, v143
	v_fmamk_f32 v89, v89, 0x3e38aa3b, v143
	v_cmp_gt_f32_e32 vcc, v91, v92
	s_cbranch_vccz .LBB0_1676
	v_max_f32_e32 v92, v136, v136
	v_max_f32_e32 v91, v92, v91
	v_sub_f32_e32 v92, v136, v91
	v_exp_f32_e32 v92, v92
	v_mov_b32_e32 v136, v91
	v_mul_f32_e32 v34, v34, v92
	v_mul_f32_e32 v35, v35, v92
	v_mul_f32_e32 v36, v36, v92
	v_mul_f32_e32 v37, v37, v92
	v_mul_f32_e32 v30, v30, v92
	v_mul_f32_e32 v31, v31, v92
	v_mul_f32_e32 v32, v32, v92
	v_mul_f32_e32 v33, v33, v92
	v_mul_f32_e32 v26, v26, v92
	v_mul_f32_e32 v27, v27, v92
	v_mul_f32_e32 v28, v28, v92
	v_mul_f32_e32 v29, v29, v92
	v_mul_f32_e32 v22, v22, v92
	v_mul_f32_e32 v23, v23, v92
	v_mul_f32_e32 v24, v24, v92
	v_mul_f32_e32 v25, v25, v92
	v_mul_f32_e32 v18, v18, v92
	v_mul_f32_e32 v19, v19, v92
	v_mul_f32_e32 v20, v20, v92
	v_mul_f32_e32 v21, v21, v92
; DEVI float opq(float x) { asm("" : "+v"(x)); return x; }
; template <int DK, int MODE, int RBM, class SF, class FF, class POST>
; DEVI void attn_tile_body(const bf16x8 (&qf)[2][DK / 32], const char* Ks, const char* Vs, SF& sf, FF& ff, POST& post,
;                          int cur, int c0, int c1, float (&m)[2], float (&l)[2], f32x4 (&o)[5][2], int fr, int fq) {
;     ...
;         const float c = cl - m[rb];
; #pragma unroll
;         for (int kb = 0; kb < 4; ++kb)
; #pragma unroll
;           for (int j = 0; j < 4; ++j) {
;             const float e = FF::HASVEC ? opq(s[kb][rb][j] + c) : opq(fmaf(s[kb][rb][j], fsc, c));
;             s[kb][rb][j] = fexp2(e);
;     ...
;   if (MODE != 1) {
;     bf16x8 pf[2][2];
; #pragma unroll
;     for (int rb = 0; rb < 2; ++rb) {
;       if (!(RBM & (1 << rb))) continue;
; #pragma unroll
;       for (int kp2 = 0; kp2 < 2; ++kp2) {
;         u32x4 w;
;         w[0] = pack2(s[2 * kp2][rb][0], s[2 * kp2][rb][1]); w[1] = pack2(s[2 * kp2][rb][2], s[2 * kp2][rb][3]);
;         w[2] = pack2(s[2 * kp2 + 1][rb][0], s[2 * kp2 + 1][rb][1]); w[3] = pack2(s[2 * kp2 + 1][rb][2], s[2 * kp2 + 1][rb][3]);
;         pf[rb][kp2] = __builtin_bit_cast(bf16x8, w);
;       }
;     }
; #pragma unroll
;     for (int kp2 = 0; kp2 < 2; ++kp2)
; #pragma unroll
;       for (int db = 0; db < 4; ++db) {
;         const char* base = Vs + (db * 16 + fr) * 128 + (fq & 1) * 8;
;         const int c = kp2 * 4 + (fq >> 1);
;         u32x2 lo = *(const u32x2*)(base + ((c ^ (fr & 7)) * 16));
;         u32x2 hi = *(const u32x2*)(base + (((c + 2) ^ (fr & 7)) * 16));
;         u32x4 w; w[0] = lo[0]; w[1] = lo[1]; w[2] = hi[0]; w[3] = hi[1];
;         bf16x8 vf = __builtin_bit_cast(bf16x8, w);
;         if (RBM & 1) o[db][0] = __builtin_amdgcn_mfma_f32_16x16x32_bf16(vf, pf[0][kp2], o[db][0], 0, 0, 0);
;         if (RBM & 2) o[db][1] = __builtin_amdgcn_mfma_f32_16x16x32_bf16(vf, pf[1][kp2], o[db][1], 0, 0, 0);
;       }
;     if (MODE == 0) {
;       u32x4 w1; w1[0] = w1[1] = w1[2] = w1[3] = 0x3F803F80u;
;       const bf16x8 ones = __builtin_bit_cast(bf16x8, w1);
; #pragma unroll
;       for (int kp2 = 0; kp2 < 2; ++kp2) {
;         if (RBM & 1) o[4][0] = __builtin_amdgcn_mfma_f32_16x16x32_bf16(ones, pf[0][kp2], o[4][0], 0, 0, 0);
;         if (RBM & 2) o[4][1] = __builtin_amdgcn_mfma_f32_16x16x32_bf16(ones, pf[1][kp2], o[4][1], 0, 0, 0);
;       }
;     }
.LBB0_1676:
	v_sub_f32_e32 v142, 0, v136
	v_fmamk_f32 v58, v58, 0x3e38aa3b, v142
	v_exp_f32_e32 v86, v86
	v_exp_f32_e32 v87, v87
	v_fmamk_f32 v62, v62, 0x3e38aa3b, v142
	v_exp_f32_e32 v99, v58
	v_fmamk_f32 v58, v59, 0x3e38aa3b, v142
	v_exp_f32_e32 v81, v81
	v_exp_f32_e32 v78, v78
	v_exp_f32_e32 v79, v79
	v_exp_f32_e32 v80, v80
	v_exp_f32_e32 v77, v77
	v_exp_f32_e32 v74, v74
	v_exp_f32_e32 v75, v75
	v_exp_f32_e32 v76, v76
	v_exp_f32_e32 v95, v62
	v_fmamk_f32 v62, v63, 0x3e38aa3b, v142
	v_exp_f32_e32 v100, v58
	v_fmamk_f32 v58, v60, 0x3e38aa3b, v142
	v_fmamk_f32 v66, v66, 0x3e38aa3b, v142
	v_exp_f32_e32 v96, v62
	v_fmamk_f32 v62, v64, 0x3e38aa3b, v142
	v_exp_f32_e32 v101, v58
	v_fmamk_f32 v58, v61, 0x3e38aa3b, v142
	v_cvt_pk_bf16_f32 v64, v86, v87
	v_add3_u32 v86, s7, v131, v0
	v_add_u32_e32 v138, v86, v132
	v_add_u32_e32 v139, v86, v133
	v_exp_f32_e32 v91, v66
	v_fmamk_f32 v66, v67, 0x3e38aa3b, v142
	v_exp_f32_e32 v102, v58
	v_cvt_pk_bf16_f32 v58, v74, v75
	v_cvt_pk_bf16_f32 v59, v76, v77
	v_cvt_pk_bf16_f32 v60, v78, v79
	v_cvt_pk_bf16_f32 v61, v80, v81
	ds_read_b64 v[232:233], v138 offset:8192
	ds_read_b64 v[236:237], v138 offset:10240
	ds_read_b64 v[234:235], v139 offset:8192
	ds_read_b64 v[238:239], v139 offset:10240
	v_exp_f32_e32 v85, v85
	v_exp_f32_e32 v84, v84
	v_fmamk_f32 v70, v70, 0x3e38aa3b, v142
	v_exp_f32_e32 v92, v66
	v_fmamk_f32 v66, v68, 0x3e38aa3b, v142
	v_fmamk_f32 v71, v71, 0x3e38aa3b, v142
	v_fmamk_f32 v72, v72, 0x3e38aa3b, v142
	v_fmamk_f32 v73, v73, 0x3e38aa3b, v142
	v_cvt_pk_bf16_f32 v63, v84, v85
	v_exp_f32_e32 v93, v66
	v_fmamk_f32 v66, v69, 0x3e38aa3b, v142
	v_exp_f32_e32 v70, v70
	v_exp_f32_e32 v71, v71
	v_exp_f32_e32 v72, v72
	v_exp_f32_e32 v73, v73
	s_waitcnt lgkmcnt(0)
	v_exp_f32_e32 v69, v66
	v_exp_f32_e32 v82, v82
	v_exp_f32_e32 v83, v83
	v_cvt_pk_bf16_f32 v66, v70, v71
	v_exp_f32_e32 v97, v62
	v_fmamk_f32 v62, v65, 0x3e38aa3b, v142
	v_cvt_pk_bf16_f32 v67, v72, v73
	v_cvt_pk_bf16_f32 v68, v91, v92
	v_cvt_pk_bf16_f32 v69, v93, v69
	v_exp_f32_e32 v98, v62
	v_cvt_pk_bf16_f32 v62, v82, v83
	v_mfma_f32_16x16x32_bf16 v[54:57], v[236:239], v[58:61], v[54:57]
	v_add_u32_e32 v140, v86, v134
	v_add_u32_e32 v141, v86, v135
	v_exp_f32_e32 v89, v89
	v_mfma_f32_16x16x32_bf16 v[30:33], v[236:239], v[66:69], v[30:33]
	ds_read_b64 v[240:241], v138 offset:12288
	ds_read_b64 v[244:245], v138 offset:14336
	ds_read_b64 v[242:243], v139 offset:12288
	ds_read_b64 v[246:247], v139 offset:14336
	v_exp_f32_e32 v88, v88
	v_cvt_pk_bf16_f32 v70, v95, v96
	v_mfma_f32_16x16x32_bf16 v[50:53], v[232:235], v[58:61], v[50:53]
	v_cvt_pk_bf16_f32 v71, v97, v98
	v_cvt_pk_bf16_f32 v65, v88, v89
	v_cvt_pk_bf16_f32 v72, v99, v100
	v_mfma_f32_16x16x32_bf16 v[34:37], v[232:235], v[66:69], v[34:37]
	s_waitcnt lgkmcnt(0)
	v_mfma_f32_16x16x32_bf16 v[42:45], v[244:247], v[58:61], v[42:45]
	ds_read_b64 v[232:233], v140 offset:8192
	ds_read_b64 v[236:237], v140 offset:10240
	v_cvt_pk_bf16_f32 v73, v101, v102
	s_mov_b32 s93, s92
	v_mfma_f32_16x16x32_bf16 v[22:25], v[244:247], v[66:69], v[22:25]
	ds_read_b64 v[234:235], v141 offset:8192
	ds_read_b64 v[238:239], v141 offset:10240
	s_mov_b32 s94, s92
	s_mov_b32 s95, s92
	v_mfma_f32_16x16x32_bf16 v[46:49], v[240:243], v[58:61], v[46:49]
	s_cmp_gt_u32 s6, 3
	v_mfma_f32_16x16x32_bf16 v[26:29], v[240:243], v[66:69], v[26:29]
	s_waitcnt lgkmcnt(0)
	v_mfma_f32_16x16x32_bf16 v[54:57], v[236:239], v[62:65], v[54:57]
	v_mfma_f32_16x16x32_bf16 v[30:33], v[236:239], v[70:73], v[30:33]
	ds_read_b64 v[240:241], v140 offset:12288
	ds_read_b64 v[244:245], v140 offset:14336
	ds_read_b64 v[242:243], v141 offset:12288
	ds_read_b64 v[246:247], v141 offset:14336
	v_mfma_f32_16x16x32_bf16 v[50:53], v[232:235], v[62:65], v[50:53]
	v_mfma_f32_16x16x32_bf16 v[34:37], v[232:235], v[70:73], v[34:37]
	s_waitcnt lgkmcnt(0)
	v_mov_b64_e32 v[74:75], s[92:93]
	v_mov_b64_e32 v[76:77], s[94:95]
	v_mfma_f32_16x16x32_bf16 v[46:49], v[240:243], v[62:65], v[46:49]
	s_nop 0
	v_mfma_f32_16x16x32_bf16 v[38:41], v[74:77], v[58:61], v[38:41]
	v_mfma_f32_16x16x32_bf16 v[18:21], v[74:77], v[66:69], v[18:21]
	v_mfma_f32_16x16x32_bf16 v[26:29], v[240:243], v[70:73], v[26:29]
	v_mfma_f32_16x16x32_bf16 v[42:45], v[244:247], v[62:65], v[42:45]
	v_mfma_f32_16x16x32_bf16 v[22:25], v[244:247], v[70:73], v[22:25]
	v_mfma_f32_16x16x32_bf16 v[38:41], v[74:77], v[62:65], v[38:41]
	v_mfma_f32_16x16x32_bf16 v[18:21], v[74:77], v[70:73], v[18:21]
	s_cbranch_scc1 .LBB0_1684
; DEVI float opq(float x) { asm("" : "+v"(x)); return x; }
; DEVI float xmax16(float x) {
; template <int DK, int MODE, int RBM, class SF, class FF, class POST>
; DEVI void attn_tile_body(const bf16x8 (&qf)[2][DK / 32], const char* Ks, const char* Vs, SF& sf, FF& ff, POST& post,
;                          int cur, int c0, int c1, float (&m)[2], float (&l)[2], f32x4 (&o)[5][2], int fr, int fq) {
;     ...
;   for (int ks = 0; ks < NKC; ++ks)
; #pragma unroll
;     for (int kb = 0; kb < 4; ++kb) {
;       const int koff = DK == 64 ? (kb * 16 + fr) * 128 + (((ks * 4 + fq) ^ (fr & 7)) * 16)
;                                 : (kb * 16 + fr) * 192 + ((ks * 4 + (fq ^ ((fr >> 2) & 3))) * 16);
;       bf16x8 kf = *(const bf16x8*)(Ks + koff);
;       if (RBM & 1) s[kb][0] = __builtin_amdgcn_mfma_f32_16x16x32_bf16(kf, qf[0][ks], s[kb][0], 0, 0, 0);
;       if (RBM & 2) s[kb][1] = __builtin_amdgcn_mfma_f32_16x16x32_bf16(kf, qf[1][ks], s[kb][1], 0, 0, 0);
;     }
; #pragma unroll
;   for (int rb = 0; rb < 2; ++rb) {
;     if (!(RBM & (1 << rb))) continue;
;     const int cm = rb == 0 ? c0 : c1;
;     if (cm == 2) {
;       const float cl = ff.cl(rb, cur);
;       const float fsc = ff.sc;
;       if (FF::HASVEC) {
; #pragma unroll
;         for (int kb = 0; kb < 4; ++kb) {
;           const f32x4 av = ff.vec(kb);
; #pragma unroll
;           for (int j = 0; j < 4; ++j) s[kb][rb][j] = opq(fmaf(s[kb][rb][j], fsc, av[j]));
;         }
;       }
;       if (MODE == 2) {
;         const float c = cl - m[rb];
; #pragma unroll
;         for (int kb = 0; kb < 4; ++kb)
; #pragma unroll
;           for (int j = 0; j < 4; ++j) {
;             const float e = FF::HASVEC ? opq(s[kb][rb][j] + c) : opq(fmaf(s[kb][rb][j], fsc, c));
;             s[kb][rb][j] = opq(fexp2(e) * l[rb]);
;           }
;       } else if (MODE == 0) {
;         float mx = max16(s[0][rb], s[1][rb], s[2][rb], s[3][rb]);
;         mx = xmax16(mx); mx = xmax32(mx);
;         const float cand = FF::HASVEC ? (mx + cl) : fmaf(mx, fsc, cl);
;         if (__builtin_amdgcn_ballot_w64(cand > m[rb] + DEFER_THR) != 0) {
;           const float mn = fmaxf(m[rb], cand);
;           const float alpha = fexp2(m[rb] - mn);
;           m[rb] = mn;
; #pragma unroll
;           for (int db = 0; db < 5; ++db)
; #pragma unroll
;             for (int j = 0; j < 4; ++j) o[db][rb][j] = opq(o[db][rb][j] * alpha);
;         }
	ds_read_b128 v[82:85], v90 offset:22784
	ds_read_b128 v[58:61], v90 offset:16640
	ds_read_b128 v[66:69], v90 offset:18688
	ds_read_b128 v[74:77], v90 offset:20736
	s_waitcnt lgkmcnt(0)
	v_mfma_f32_16x16x32_bf16 v[144:147], v[82:85], v[2:5], 0
	v_mfma_f32_16x16x32_bf16 v[148:151], v[82:85], v[10:13], 0
	ds_read_b128 v[82:85], v94 offset:16640
	v_mfma_f32_16x16x32_bf16 v[62:65], v[58:61], v[2:5], 0
	v_mfma_f32_16x16x32_bf16 v[58:61], v[58:61], v[10:13], 0
	s_waitcnt lgkmcnt(0)
	v_mfma_f32_16x16x32_bf16 v[90:93], v[82:85], v[14:17], v[58:61]
	v_mfma_f32_16x16x32_bf16 v[70:73], v[66:69], v[2:5], 0
	s_nop 4
	ds_read_b128 v[58:61], v94 offset:18688
	v_mfma_f32_16x16x32_bf16 v[66:69], v[66:69], v[10:13], 0
	s_waitcnt lgkmcnt(0)
	v_mfma_f32_16x16x32_bf16 v[102:105], v[58:61], v[6:9], v[70:73]
	v_mfma_f32_16x16x32_bf16 v[86:89], v[58:61], v[14:17], v[66:69]
	ds_read_b128 v[58:61], v94 offset:20736
	v_mfma_f32_16x16x32_bf16 v[78:81], v[74:77], v[2:5], 0
	v_mfma_f32_16x16x32_bf16 v[74:77], v[74:77], v[10:13], 0
	v_mfma_f32_16x16x32_bf16 v[98:101], v[82:85], v[6:9], v[62:65]
	s_waitcnt lgkmcnt(0)
	v_mfma_f32_16x16x32_bf16 v[106:109], v[58:61], v[6:9], v[78:81]
	v_mfma_f32_16x16x32_bf16 v[82:85], v[58:61], v[14:17], v[74:77]
	ds_read_b128 v[58:61], v94 offset:22784
	s_waitcnt lgkmcnt(0)
	v_mfma_f32_16x16x32_bf16 v[94:97], v[58:61], v[6:9], v[144:147]
	s_nop 7
	v_max3_f32 v62, v94, v95, v96
	v_mfma_f32_16x16x32_bf16 v[78:81], v[58:61], v[14:17], v[148:151]
	v_max_f32_e32 v58, v98, v99
	v_max3_f32 v59, v101, v102, v103
	v_max3_f32 v61, v107, v108, v109
	v_max3_f32 v60, v104, v105, v106
	v_max3_f32 v58, v58, v100, v59
	v_max3_f32 v59, v61, v62, v97
	v_max3_f32 v58, v58, v60, v59
	v_mov_b32_e32 v59, v58
	s_nop 1
	v_permlane16_swap_b32_e32 v58, v59
	v_max_f32_e32 v58, v58, v59
	v_mov_b32_e32 v59, v58
	s_nop 1
	v_permlane32_swap_b32_e32 v58, v59
	v_max_f32_e32 v58, v58, v59
	v_fma_f32 v58, v58, s0, 0
	v_add_f32_e32 v59, 0x41000000, v137
	v_cmp_gt_f32_e32 vcc, v58, v59
	s_cbranch_vccz .LBB0_1686
	v_max_f32_e32 v59, v137, v137
	v_max_f32_e32 v144, v59, v58
	v_sub_f32_e32 v58, v137, v144
	v_exp_f32_e32 v61, v58
	v_sub_f32_e32 v145, 0, v144
	v_mul_f32_e32 v70, v50, v61
	v_mul_f32_e32 v71, v51, v61
	v_mul_f32_e32 v72, v52, v61
	v_mul_f32_e32 v73, v53, v61
	v_mul_f32_e32 v74, v54, v61
	v_mul_f32_e32 v75, v55, v61
	v_mul_f32_e32 v76, v56, v61
	v_mul_f32_e32 v77, v57, v61
	v_mul_f32_e32 v62, v46, v61
	v_mul_f32_e32 v63, v47, v61
	v_mul_f32_e32 v64, v48, v61
	v_mul_f32_e32 v65, v49, v61
	v_mul_f32_e32 v66, v42, v61
	v_mul_f32_e32 v67, v43, v61
	v_mul_f32_e32 v68, v44, v61
	v_mul_f32_e32 v69, v45, v61
	v_mul_f32_e32 v58, v38, v61
	v_mul_f32_e32 v59, v39, v61
	v_mul_f32_e32 v60, v40, v61
	v_mul_f32_e32 v61, v41, v61
	s_cbranch_execnz .LBB0_1680

; DEVI float opq(float x) { asm("" : "+v"(x)); return x; }
; DEVI float fexp2(float x) { return __builtin_amdgcn_exp2f(x); }
; DEVI float xmax16(float x) {
;   u32x2 r = __builtin_amdgcn_permlane16_swap(__float_as_uint(x), __float_as_uint(x), false, false);
;   return fmaxf(__uint_as_float(r[0]), __uint_as_float(r[1]));
; }
; DEVI float xmax32(float x) {
;   u32x2 r = __builtin_amdgcn_permlane32_swap(__float_as_uint(x), __float_as_uint(x), false, false);
;   return fmaxf(__uint_as_float(r[0]), __uint_as_float(r[1]));
; }
; template <int DK, int MODE, int RBM, class SF, class FF, class POST>
; DEVI void attn_tile_body(const bf16x8 (&qf)[2][DK / 32], const char* Ks, const char* Vs, SF& sf, FF& ff, POST& post,
;                          int cur, int c0, int c1, float (&m)[2], float (&l)[2], f32x4 (&o)[5][2], int fr, int fq) {
;     ...
;       } else if (MODE == 0) {
;         float mx = max16(s[0][rb], s[1][rb], s[2][rb], s[3][rb]);
;         mx = xmax16(mx); mx = xmax32(mx);
;         const float cand = FF::HASVEC ? (mx + cl) : fmaf(mx, fsc, cl);
;         if (__builtin_amdgcn_ballot_w64(cand > m[rb] + DEFER_THR) != 0) {
;           const float mn = fmaxf(m[rb], cand);
;           const float alpha = fexp2(m[rb] - mn);
;           m[rb] = mn;
; #pragma unroll
;           for (int db = 0; db < 5; ++db)
; #pragma unroll
;             for (int j = 0; j < 4; ++j) o[db][rb][j] = opq(o[db][rb][j] * alpha);
;         }
;         const float c = cl - m[rb];
; #pragma unroll
;         for (int kb = 0; kb < 4; ++kb)
; #pragma unroll
;           for (int j = 0; j < 4; ++j) {
;             const float e = FF::HASVEC ? opq(s[kb][rb][j] + c) : opq(fmaf(s[kb][rb][j], fsc, c));
;             s[kb][rb][j] = fexp2(e);
.LBB0_1680:
	v_max_f32_e32 v38, v90, v91
	v_max3_f32 v39, v93, v86, v87
	v_max3_f32 v41, v83, v84, v85
	v_max3_f32 v42, v78, v79, v80
	v_max3_f32 v40, v88, v89, v82
	v_max3_f32 v38, v38, v92, v39
	v_max3_f32 v39, v41, v42, v81
	v_max3_f32 v38, v38, v40, v39
	v_mov_b32_e32 v39, v38
	s_nop 1
	v_permlane16_swap_b32_e32 v38, v39
	v_max_f32_e32 v38, v38, v39
	v_mov_b32_e32 v39, v38
	s_nop 1
	v_permlane32_swap_b32_e32 v38, v39
	v_max_f32_e32 v38, v38, v39
	v_fma_f32 v38, v38, s0, 0
	v_add_f32_e32 v39, 0x41000000, v136
	v_fmamk_f32 v98, v98, 0x3e38aa3b, v145
	v_fmamk_f32 v99, v99, 0x3e38aa3b, v145
	v_fmamk_f32 v100, v100, 0x3e38aa3b, v145
	v_fmamk_f32 v101, v101, 0x3e38aa3b, v145
	v_fmamk_f32 v102, v102, 0x3e38aa3b, v145
	v_fmamk_f32 v103, v103, 0x3e38aa3b, v145
	v_fmamk_f32 v104, v104, 0x3e38aa3b, v145
	v_fmamk_f32 v105, v105, 0x3e38aa3b, v145
	v_fmamk_f32 v106, v106, 0x3e38aa3b, v145
	v_fmamk_f32 v107, v107, 0x3e38aa3b, v145
	v_fmamk_f32 v108, v108, 0x3e38aa3b, v145
	v_fmamk_f32 v109, v109, 0x3e38aa3b, v145
	v_fmamk_f32 v137, v94, 0x3e38aa3b, v145
	v_fmamk_f32 v95, v95, 0x3e38aa3b, v145
	v_fmamk_f32 v96, v96, 0x3e38aa3b, v145
	v_fmac_f32_e32 v145, 0x3e38aa3b, v97
	v_cmp_gt_f32_e32 vcc, v38, v39
	s_cbranch_vccz .LBB0_1687
	v_max_f32_e32 v39, v136, v136
	v_max_f32_e32 v94, v39, v38
	v_sub_f32_e32 v38, v136, v94
	v_exp_f32_e32 v41, v38
	v_sub_f32_e32 v97, 0, v94
	v_mul_f32_e32 v50, v34, v41
	v_mul_f32_e32 v51, v35, v41
	v_mul_f32_e32 v52, v36, v41
	v_mul_f32_e32 v53, v37, v41
	v_mul_f32_e32 v54, v30, v41
	v_mul_f32_e32 v55, v31, v41
	v_mul_f32_e32 v56, v32, v41
	v_mul_f32_e32 v57, v33, v41
	v_mul_f32_e32 v42, v26, v41
	v_mul_f32_e32 v43, v27, v41
	v_mul_f32_e32 v44, v28, v41
	v_mul_f32_e32 v45, v29, v41
	v_mul_f32_e32 v46, v22, v41
	v_mul_f32_e32 v47, v23, v41
	v_mul_f32_e32 v48, v24, v41
	v_mul_f32_e32 v49, v25, v41
	v_mul_f32_e32 v38, v18, v41
	v_mul_f32_e32 v39, v19, v41
	v_mul_f32_e32 v40, v20, v41
	v_mul_f32_e32 v41, v21, v41
	s_cbranch_execnz .LBB0_1683

; DEVI float opq(float x) { asm("" : "+v"(x)); return x; }
; template <int DK, int MODE, int RBM, class SF, class FF, class POST>
; DEVI void attn_tile_body(const bf16x8 (&qf)[2][DK / 32], const char* Ks, const char* Vs, SF& sf, FF& ff, POST& post,
;                          int cur, int c0, int c1, float (&m)[2], float (&l)[2], f32x4 (&o)[5][2], int fr, int fq) {
;     ...
;         const float c = cl - m[rb];
; #pragma unroll
;         for (int kb = 0; kb < 4; ++kb)
; #pragma unroll
;           for (int j = 0; j < 4; ++j) {
;             const float e = FF::HASVEC ? opq(s[kb][rb][j] + c) : opq(fmaf(s[kb][rb][j], fsc, c));
;             s[kb][rb][j] = fexp2(e);
;     ...
;   if (MODE != 1) {
;     bf16x8 pf[2][2];
; #pragma unroll
;     for (int rb = 0; rb < 2; ++rb) {
;       if (!(RBM & (1 << rb))) continue;
; #pragma unroll
;       for (int kp2 = 0; kp2 < 2; ++kp2) {
;         u32x4 w;
;         w[0] = pack2(s[2 * kp2][rb][0], s[2 * kp2][rb][1]); w[1] = pack2(s[2 * kp2][rb][2], s[2 * kp2][rb][3]);
;         w[2] = pack2(s[2 * kp2 + 1][rb][0], s[2 * kp2 + 1][rb][1]); w[3] = pack2(s[2 * kp2 + 1][rb][2], s[2 * kp2 + 1][rb][3]);
;         pf[rb][kp2] = __builtin_bit_cast(bf16x8, w);
;       }
;     }
; #pragma unroll
;     for (int kp2 = 0; kp2 < 2; ++kp2)
; #pragma unroll
;       for (int db = 0; db < 4; ++db) {
;         const char* base = Vs + (db * 16 + fr) * 128 + (fq & 1) * 8;
;         const int c = kp2 * 4 + (fq >> 1);
;         u32x2 lo = *(const u32x2*)(base + ((c ^ (fr & 7)) * 16));
;         u32x2 hi = *(const u32x2*)(base + (((c + 2) ^ (fr & 7)) * 16));
;         u32x4 w; w[0] = lo[0]; w[1] = lo[1]; w[2] = hi[0]; w[3] = hi[1];
;         bf16x8 vf = __builtin_bit_cast(bf16x8, w);
;         if (RBM & 1) o[db][0] = __builtin_amdgcn_mfma_f32_16x16x32_bf16(vf, pf[0][kp2], o[db][0], 0, 0, 0);
;         if (RBM & 2) o[db][1] = __builtin_amdgcn_mfma_f32_16x16x32_bf16(vf, pf[1][kp2], o[db][1], 0, 0, 0);
;       }
;     if (MODE == 0) {
;       u32x4 w1; w1[0] = w1[1] = w1[2] = w1[3] = 0x3F803F80u;
;       const bf16x8 ones = __builtin_bit_cast(bf16x8, w1);
; #pragma unroll
;       for (int kp2 = 0; kp2 < 2; ++kp2) {
;         if (RBM & 1) o[4][0] = __builtin_amdgcn_mfma_f32_16x16x32_bf16(ones, pf[0][kp2], o[4][0], 0, 0, 0);
;         if (RBM & 2) o[4][1] = __builtin_amdgcn_mfma_f32_16x16x32_bf16(ones, pf[1][kp2], o[4][1], 0, 0, 0);
;       }
;     }
.LBB0_1683:
	v_fmamk_f32 v82, v82, 0x3e38aa3b, v97
	v_fmamk_f32 v86, v86, 0x3e38aa3b, v97
	v_fmamk_f32 v87, v87, 0x3e38aa3b, v97
	v_fmamk_f32 v34, v90, 0x3e38aa3b, v97
	v_exp_f32_e32 v90, v82
	v_fmamk_f32 v82, v83, 0x3e38aa3b, v97
	v_fmamk_f32 v78, v78, 0x3e38aa3b, v97
	v_fmamk_f32 v35, v91, 0x3e38aa3b, v97
	v_exp_f32_e32 v86, v86
	v_exp_f32_e32 v87, v87
	v_exp_f32_e32 v22, v145
	v_exp_f32_e32 v91, v82
	v_exp_f32_e32 v23, v137
	v_exp_f32_e32 v24, v95
	v_exp_f32_e32 v25, v96
	v_exp_f32_e32 v26, v109
	v_exp_f32_e32 v27, v106
	v_exp_f32_e32 v28, v107
	v_exp_f32_e32 v29, v108
	v_exp_f32_e32 v95, v78
	v_fmamk_f32 v78, v79, 0x3e38aa3b, v97
	v_fmamk_f32 v82, v84, 0x3e38aa3b, v97
	v_exp_f32_e32 v96, v78
	v_fmamk_f32 v78, v80, 0x3e38aa3b, v97
	v_cvt_pk_bf16_f32 v84, v86, v87
	v_cvt_pk_bf16_f32 v86, v90, v91
	v_add_u32_e32 v90, 0x100, v138
	v_add_u32_e32 v91, 0x100, v139
	v_exp_f32_e32 v18, v98
	v_fmamk_f32 v36, v92, 0x3e38aa3b, v97
	v_fmamk_f32 v37, v93, 0x3e38aa3b, v97
	v_fmamk_f32 v88, v88, 0x3e38aa3b, v97
	v_fmamk_f32 v89, v89, 0x3e38aa3b, v97
	v_exp_f32_e32 v92, v82
	v_fmamk_f32 v82, v85, 0x3e38aa3b, v97
	v_exp_f32_e32 v98, v78
	v_fmac_f32_e32 v97, 0x3e38aa3b, v81
	v_cvt_pk_bf16_f32 v78, v27, v28
	v_cvt_pk_bf16_f32 v79, v29, v26
	v_cvt_pk_bf16_f32 v80, v23, v24
	v_cvt_pk_bf16_f32 v81, v25, v22
	ds_read_b64 v[232:233], v90 offset:24576
	ds_read_b64 v[236:237], v90 offset:26624
	ds_read_b64 v[234:235], v91 offset:24576
	ds_read_b64 v[238:239], v91 offset:26624
	v_exp_f32_e32 v21, v105
	v_exp_f32_e32 v20, v102
	v_exp_f32_e32 v30, v103
	v_exp_f32_e32 v31, v104
	v_exp_f32_e32 v19, v101
	v_exp_f32_e32 v32, v99
	v_exp_f32_e32 v33, v100
	s_nop 0
	v_exp_f32_e32 v34, v34
	v_exp_f32_e32 v35, v35
	v_exp_f32_e32 v36, v36
	v_exp_f32_e32 v37, v37
	v_exp_f32_e32 v88, v88
	v_exp_f32_e32 v89, v89
	v_cvt_pk_bf16_f32 v18, v18, v32
	v_cvt_pk_bf16_f32 v19, v33, v19
	v_cvt_pk_bf16_f32 v20, v20, v30
	v_cvt_pk_bf16_f32 v21, v31, v21
	s_waitcnt lgkmcnt(0)
	v_cvt_pk_bf16_f32 v83, v36, v37
	v_exp_f32_e32 v93, v82
	v_cvt_pk_bf16_f32 v82, v34, v35
	v_cvt_pk_bf16_f32 v85, v88, v89
	v_mfma_f32_16x16x32_bf16 v[34:37], v[232:235], v[18:21], v[70:73]
	v_cvt_pk_bf16_f32 v87, v92, v93
	v_exp_f32_e32 v97, v97
	v_mfma_f32_16x16x32_bf16 v[30:33], v[232:235], v[82:85], v[50:53]
	v_cvt_pk_bf16_f32 v88, v95, v96
	s_mov_b32 s93, s92
	v_cvt_pk_bf16_f32 v89, v98, v97
	v_mfma_f32_16x16x32_bf16 v[22:25], v[236:239], v[18:21], v[74:77]
	s_mov_b32 s94, s92
	s_mov_b32 s95, s92
	v_mov_b32_e32 v136, v94
	v_mfma_f32_16x16x32_bf16 v[26:29], v[236:239], v[82:85], v[54:57]
	ds_read_b64 v[240:241], v90 offset:28672
	ds_read_b64 v[244:245], v90 offset:30720
	s_nop 1
	ds_read_b64 v[242:243], v91 offset:28672
	ds_read_b64 v[246:247], v91 offset:30720
	v_add_u32_e32 v90, 0x100, v140
	v_add_u32_e32 v91, 0x100, v141
	ds_read_b64 v[234:235], v91 offset:24576
	ds_read_b64 v[238:239], v91 offset:26624
	s_waitcnt lgkmcnt(0)
	v_mfma_f32_16x16x32_bf16 v[62:65], v[240:243], v[18:21], v[62:65]
	v_mfma_f32_16x16x32_bf16 v[42:45], v[240:243], v[82:85], v[42:45]
	v_mfma_f32_16x16x32_bf16 v[70:73], v[244:247], v[82:85], v[46:49]
	s_nop 2
	ds_read_b64 v[232:233], v90 offset:24576
	ds_read_b64 v[236:237], v90 offset:26624
	v_mfma_f32_16x16x32_bf16 v[66:69], v[244:247], v[18:21], v[66:69]
	s_waitcnt lgkmcnt(0)
	v_mfma_f32_16x16x32_bf16 v[50:53], v[232:235], v[78:81], v[34:37]
	v_mfma_f32_16x16x32_bf16 v[34:37], v[232:235], v[86:89], v[30:33]
	v_mfma_f32_16x16x32_bf16 v[54:57], v[236:239], v[78:81], v[22:25]
	v_mfma_f32_16x16x32_bf16 v[30:33], v[236:239], v[86:89], v[26:29]
	s_nop 1
	ds_read_b64 v[240:241], v90 offset:28672
	ds_read_b64 v[244:245], v90 offset:30720
	ds_read_b64 v[242:243], v91 offset:28672
	ds_read_b64 v[246:247], v91 offset:30720
	s_waitcnt lgkmcnt(0)
	v_mfma_f32_16x16x32_bf16 v[46:49], v[240:243], v[78:81], v[62:65]
	s_nop 2
	v_mov_b64_e32 v[62:63], s[92:93]
	v_mov_b64_e32 v[64:65], s[94:95]
	v_mfma_f32_16x16x32_bf16 v[26:29], v[240:243], v[86:89], v[42:45]
	s_nop 0
	v_mfma_f32_16x16x32_bf16 v[18:21], v[62:65], v[18:21], v[58:61]
	v_mfma_f32_16x16x32_bf16 v[58:61], v[62:65], v[82:85], v[38:41]
	v_mfma_f32_16x16x32_bf16 v[42:45], v[244:247], v[78:81], v[66:69]
	v_mfma_f32_16x16x32_bf16 v[22:25], v[244:247], v[86:89], v[70:73]
	v_mfma_f32_16x16x32_bf16 v[38:41], v[62:65], v[78:81], v[18:21]
	v_mfma_f32_16x16x32_bf16 v[18:21], v[62:65], v[86:89], v[58:61]
	s_andn2_b64 vcc, exec, s[40:41]
	s_xor_b32 s43, s43, 2
	s_cbranch_vccnz .LBB0_1685
	s_branch .LBB0_1666

; DEVI int opaque_tid() { int t = __builtin_amdgcn_workitem_id_x(); asm volatile("" : "+v"(t)); return t; }
; DEVI void store_rm_sw(const f32x4 (&acc)[4][4], bf16* dst, long ld, int m0, int n0) {
;   const int tid = opaque_tid(), lane = tid & 63, wid = tid >> 6, wr = wid >> 1, wc = wid & 1, fr = lane & 15, fq = lane >> 4;
;   const int cofs = (fq & 1) * 16 + (fq & 2) * 4;
; #pragma unroll
;   for (int m = 0; m < 4; ++m) {
;     bf16* rp = dst + (long)(m0 + wr * 64 + m * 16 + fr) * ld + n0 + wc * 64 + cofs;
; #pragma unroll
;     for (int n = 0; n < 4; n += 2) {
;       const unsigned x0 = pack2(acc[m][n][0], acc[m][n][1]), x1 = pack2(acc[m][n][2], acc[m][n][3]);
;       const unsigned y0 = pack2(acc[m][n + 1][0], acc[m][n + 1][1]), y1 = pack2(acc[m][n + 1][2], acc[m][n + 1][3]);
;       const u32x2 s0 = __builtin_amdgcn_permlane16_swap(x0, y0, false, false);
;       const u32x2 s1 = __builtin_amdgcn_permlane16_swap(x1, y1, false, false);
;       *(u32x4*)(rp + n * 16) = u32x4{s0[0], s1[0], s0[1], s1[1]};
;     }
;   }
; }
; template <int EPI>
; DEVI void phase_gemm(const Params& p, const bf16* A, int lda, const bf16* Bt, int K, int NT, bf16* dst, int ldd, char* smem, bool nostore = false,
;                      const float* lng = nullptr, const float* lnb = nullptr) {
;     ...
;     } else if (EPI == EPI_RELU2) {
; #pragma unroll
;       for (int m = 0; m < 4; ++m)
; #pragma unroll
;         for (int n = 0; n < 4; ++n)
; #pragma unroll
;           for (int j = 0; j < 4; ++j) { float v = fmaxf(acc[m][n][j], 0.f); acc[m][n][j] = v * v; }
;       if (!nostore || acc[0][0][0] == 123.456f) store_rm_sw(acc, dst, ldd, mt * 128, nt * 128);
.LBB0_1861:
	v_max_f32_e32 v0, 0, v62
	v_mul_f32_e32 v62, v0, v0
	v_max_f32_e32 v0, 0, v63
	v_mul_f32_e32 v63, v0, v0
	v_max_f32_e32 v0, 0, v64
	v_mul_f32_e32 v64, v0, v0
	v_max_f32_e32 v0, 0, v65
	v_mul_f32_e32 v65, v0, v0
	v_max_f32_e32 v0, 0, v58
	v_mul_f32_e32 v58, v0, v0
	v_max_f32_e32 v0, 0, v59
	v_mul_f32_e32 v59, v0, v0
	v_max_f32_e32 v0, 0, v60
	v_mul_f32_e32 v60, v0, v0
	v_max_f32_e32 v0, 0, v61
	v_mul_f32_e32 v61, v0, v0
	v_max_f32_e32 v0, 0, v54
	v_mul_f32_e32 v54, v0, v0
	v_max_f32_e32 v0, 0, v55
	v_mul_f32_e32 v55, v0, v0
	v_max_f32_e32 v0, 0, v56
	v_mul_f32_e32 v56, v0, v0
	v_max_f32_e32 v0, 0, v57
	v_mul_f32_e32 v57, v0, v0
	v_max_f32_e32 v0, 0, v50
	v_mul_f32_e32 v50, v0, v0
	v_max_f32_e32 v0, 0, v51
	v_mul_f32_e32 v51, v0, v0
	v_max_f32_e32 v0, 0, v52
	v_mul_f32_e32 v52, v0, v0
	v_max_f32_e32 v0, 0, v53
	v_mul_f32_e32 v53, v0, v0
	v_max_f32_e32 v0, 0, v46
	v_mul_f32_e32 v46, v0, v0
	v_max_f32_e32 v0, 0, v47
	v_mul_f32_e32 v47, v0, v0
	v_max_f32_e32 v0, 0, v48
	v_mul_f32_e32 v48, v0, v0
	v_max_f32_e32 v0, 0, v49
	v_mul_f32_e32 v49, v0, v0
	v_max_f32_e32 v0, 0, v42
	v_mul_f32_e32 v42, v0, v0
	v_max_f32_e32 v0, 0, v43
	v_mul_f32_e32 v43, v0, v0
	v_max_f32_e32 v0, 0, v44
	v_mul_f32_e32 v44, v0, v0
	v_max_f32_e32 v0, 0, v45
	v_mul_f32_e32 v45, v0, v0
	v_max_f32_e32 v0, 0, v38
	v_mul_f32_e32 v38, v0, v0
	v_max_f32_e32 v0, 0, v39
	v_mul_f32_e32 v39, v0, v0
	v_max_f32_e32 v0, 0, v40
	v_mul_f32_e32 v40, v0, v0
	v_max_f32_e32 v0, 0, v41
	v_mul_f32_e32 v41, v0, v0
	v_max_f32_e32 v0, 0, v34
	v_mul_f32_e32 v34, v0, v0
	v_max_f32_e32 v0, 0, v35
	v_mul_f32_e32 v35, v0, v0
	v_max_f32_e32 v0, 0, v36
	v_mul_f32_e32 v36, v0, v0
	v_max_f32_e32 v0, 0, v37
	v_mul_f32_e32 v37, v0, v0
	v_max_f32_e32 v0, 0, v30
	v_mul_f32_e32 v30, v0, v0
	v_max_f32_e32 v0, 0, v31
	v_mul_f32_e32 v31, v0, v0
	v_max_f32_e32 v0, 0, v32
	v_mul_f32_e32 v32, v0, v0
	v_max_f32_e32 v0, 0, v33
	v_mul_f32_e32 v33, v0, v0
	v_max_f32_e32 v0, 0, v26
	v_mul_f32_e32 v26, v0, v0
	v_max_f32_e32 v0, 0, v27
	v_mul_f32_e32 v27, v0, v0
	v_max_f32_e32 v0, 0, v28
	v_mul_f32_e32 v28, v0, v0
	v_max_f32_e32 v0, 0, v29
	v_mul_f32_e32 v29, v0, v0
	v_max_f32_e32 v0, 0, v22
	v_mul_f32_e32 v22, v0, v0
	v_max_f32_e32 v0, 0, v23
	v_mul_f32_e32 v23, v0, v0
	v_max_f32_e32 v0, 0, v24
	v_mul_f32_e32 v24, v0, v0
	v_max_f32_e32 v0, 0, v25
	v_mul_f32_e32 v25, v0, v0
	v_max_f32_e32 v0, 0, v18
	v_mul_f32_e32 v18, v0, v0
	v_max_f32_e32 v0, 0, v19
	v_mul_f32_e32 v19, v0, v0
	v_max_f32_e32 v0, 0, v20
	v_mul_f32_e32 v20, v0, v0
	v_max_f32_e32 v0, 0, v21
	v_mul_f32_e32 v21, v0, v0
	v_max_f32_e32 v0, 0, v14
	v_mul_f32_e32 v14, v0, v0
	v_max_f32_e32 v0, 0, v15
	v_mul_f32_e32 v15, v0, v0
	v_max_f32_e32 v0, 0, v16
	v_mul_f32_e32 v16, v0, v0
	v_max_f32_e32 v0, 0, v17
	v_mul_f32_e32 v17, v0, v0
	v_max_f32_e32 v0, 0, v10
	v_mul_f32_e32 v66, v0, v0
	v_max_f32_e32 v0, 0, v11
	v_mul_f32_e32 v67, v0, v0
	v_max_f32_e32 v0, 0, v12
	v_mul_f32_e32 v12, v0, v0
	v_max_f32_e32 v0, 0, v13
	v_mul_f32_e32 v13, v0, v0
	v_max_f32_e32 v0, 0, v6
	v_mul_f32_e32 v68, v0, v0
	v_max_f32_e32 v0, 0, v7
	v_mul_f32_e32 v69, v0, v0
	v_max_f32_e32 v0, 0, v8
	v_mul_f32_e32 v70, v0, v0
	v_max_f32_e32 v0, 0, v9
	v_mul_f32_e32 v71, v0, v0
	v_max_f32_e32 v0, 0, v2
	v_mul_f32_e32 v72, v0, v0
	v_max_f32_e32 v0, 0, v3
	v_mul_f32_e32 v73, v0, v0
	v_max_f32_e32 v0, 0, v4
	s_lshl_b32 s10, s40, 4
	v_mul_f32_e32 v74, v0, v0
	v_max_f32_e32 v0, v5, v5
	s_sub_i32 s10, s10, s41
	v_max_f32_e32 v0, 0, v0
	s_and_b32 s40, s10, 0xffffff80
	v_mul_f32_e32 v75, v0, v0
	v_mov_b32_e32 v0, v154
	s_ashr_i32 s41, s40, 31
	v_and_b32_e32 v3, 16, v0
	v_lshrrev_b32_e32 v4, 2, v0
	v_and_or_b32 v4, v4, 8, v3
	v_ashrrev_i32_e32 v3, 1, v0
	s_lshl_b64 s[40:41], s[40:41], 1
	v_and_b32_e32 v2, 64, v0
	v_and_b32_e32 v3, 0xffffffc0, v3
	v_and_or_b32 v0, v0, 15, s13
	s_add_u32 s40, s14, s40
	v_add_u32_e32 v6, v0, v3
	s_addc_u32 s41, s15, s41
	v_lshlrev_b32_e32 v0, 1, v2
	v_lshl_add_u64 v[2:3], s[40:41], 0, v[0:1]
	v_lshlrev_b32_e32 v0, 1, v4
	v_ashrrev_i32_e32 v7, 31, v6
	v_lshl_add_u64 v[8:9], v[2:3], 0, v[0:1]
	v_lshlrev_b64 v[2:3], 13, v[6:7]
	v_lshl_add_u64 v[10:11], v[8:9], 0, v[2:3]
	v_cvt_pk_bf16_f32 v2, v62, v63
	v_cvt_pk_bf16_f32 v3, v64, v65
	v_cvt_pk_bf16_f32 v4, v58, v59
	v_cvt_pk_bf16_f32 v5, v60, v61
	s_nop 0
	v_permlane16_swap_b32_e32 v2, v4
	v_permlane16_swap_b32_e32 v3, v5
	flat_store_dwordx4 v[10:11], v[2:5]
	v_readlane_b32 s10, v249, 47
	s_andn2_b64 vcc, exec, s[38:39]
	v_cvt_pk_bf16_f32 v2, v54, v55
	v_cvt_pk_bf16_f32 v3, v56, v57
	v_cvt_pk_bf16_f32 v4, v50, v51
	v_cvt_pk_bf16_f32 v5, v52, v53
	s_nop 0
	v_permlane16_swap_b32_e32 v2, v4
	v_permlane16_swap_b32_e32 v3, v5
	flat_store_dwordx4 v[10:11], v[2:5] offset:64
	s_add_i32 s6, s6, s10
	s_nop 0
	v_or_b32_e32 v2, 16, v6
	v_ashrrev_i32_e32 v3, 31, v2
	v_lshlrev_b64 v[2:3], 13, v[2:3]
	v_lshl_add_u64 v[10:11], v[8:9], 0, v[2:3]
	v_cvt_pk_bf16_f32 v2, v46, v47
	v_cvt_pk_bf16_f32 v3, v48, v49
	v_cvt_pk_bf16_f32 v4, v42, v43
	v_cvt_pk_bf16_f32 v5, v44, v45
	s_nop 0
	v_permlane16_swap_b32_e32 v2, v4
	v_permlane16_swap_b32_e32 v3, v5
	flat_store_dwordx4 v[10:11], v[2:5]
	s_nop 1
	v_cvt_pk_bf16_f32 v2, v38, v39
	v_cvt_pk_bf16_f32 v3, v40, v41
	v_cvt_pk_bf16_f32 v4, v34, v35
	v_cvt_pk_bf16_f32 v5, v36, v37
	s_nop 0
	v_permlane16_swap_b32_e32 v2, v4
	v_permlane16_swap_b32_e32 v3, v5
	flat_store_dwordx4 v[10:11], v[2:5] offset:64
	s_nop 1
	v_or_b32_e32 v2, 32, v6
	v_ashrrev_i32_e32 v3, 31, v2
	v_lshlrev_b64 v[2:3], 13, v[2:3]
	v_lshl_add_u64 v[10:11], v[8:9], 0, v[2:3]
	v_cvt_pk_bf16_f32 v2, v30, v31
	v_cvt_pk_bf16_f32 v3, v32, v33
	v_cvt_pk_bf16_f32 v4, v26, v27
	v_cvt_pk_bf16_f32 v5, v28, v29
	s_nop 0
	v_permlane16_swap_b32_e32 v2, v4
	v_permlane16_swap_b32_e32 v3, v5
	flat_store_dwordx4 v[10:11], v[2:5]
	s_nop 1
	v_cvt_pk_bf16_f32 v2, v22, v23
	v_cvt_pk_bf16_f32 v3, v24, v25
	v_cvt_pk_bf16_f32 v4, v18, v19
	v_cvt_pk_bf16_f32 v5, v20, v21
	s_nop 0
	v_permlane16_swap_b32_e32 v2, v4
	v_permlane16_swap_b32_e32 v3, v5
	flat_store_dwordx4 v[10:11], v[2:5] offset:64
	s_nop 1
	v_or_b32_e32 v2, 48, v6
	v_ashrrev_i32_e32 v3, 31, v2
	v_lshlrev_b64 v[2:3], 13, v[2:3]
	v_lshl_add_u64 v[6:7], v[8:9], 0, v[2:3]
	v_cvt_pk_bf16_f32 v2, v14, v15
	v_cvt_pk_bf16_f32 v3, v16, v17
	v_cvt_pk_bf16_f32 v4, v66, v67
	v_cvt_pk_bf16_f32 v5, v12, v13
	s_nop 0
	v_permlane16_swap_b32_e32 v2, v4
	v_permlane16_swap_b32_e32 v3, v5
	flat_store_dwordx4 v[6:7], v[2:5]
	s_nop 1
	v_cvt_pk_bf16_f32 v2, v68, v69
	v_cvt_pk_bf16_f32 v3, v70, v71
	v_cvt_pk_bf16_f32 v4, v72, v73
	v_cvt_pk_bf16_f32 v5, v74, v75
	s_nop 0
	v_permlane16_swap_b32_e32 v2, v4
	v_permlane16_swap_b32_e32 v3, v5
	flat_store_dwordx4 v[6:7], v[2:5] offset:64
	s_cbranch_vccz .LBB0_1866
